# GEMM K loops without any s_setprio (144 removed)
# speedup vs baseline: 1.0032x; 1.0012x over previous
; #define PG8_STAGE(bufoff, gbase, voff) do { _Pragma("unroll") for (int _i = 0; _i < 2; ++_i) \
;         __builtin_amdgcn_global_load_lds((const unsigned*)((const char*)(gbase) + (voff)[_i]), (PG8_LAS unsigned*)(lds + (bufoff) + ldsw + _i * 8192), 16, 0, 0); } while (0)
; #define PG8_LDA(dst, b, h) do { _Pragma("unroll") for (int m = 0; m < 4; ++m) _Pragma("unroll") for (int k = 0; k < 2; ++k) dst[m][k] = *(const PG8_LAS bf16x8*)(lds + PG8_SA(b, h) + aoff + m * 2048 + k * 1024); } while (0)
; #define PG8_LDB(dst, b, h) do { _Pragma("unroll") for (int n = 0; n < 2; ++n) _Pragma("unroll") for (int k = 0; k < 2; ++k) dst[n][k] = *(const PG8_LAS bf16x8*)(lds + PG8_SB(b, h) + boff + n * 2048 + k * 1024); } while (0)
; #define PG8_MMA(ai, bj, At, Bt) do { __builtin_amdgcn_s_setprio(1); _Pragma("unroll") for (int m = 0; m < 4; ++m) _Pragma("unroll") for (int n = 0; n < 2; ++n) _Pragma("unroll") for (int k = 0; k < 2; ++k) \
;         acc[ai][bj][m][n] = __builtin_amdgcn_mfma_f32_16x16x32_bf16(Bt[n][k], At[m][k], acc[ai][bj][m][n], 0, 0, 0); __builtin_amdgcn_s_setprio(0); } while (0)
; #define PG8_WAIT_V(n) asm volatile("s_waitcnt vmcnt(" #n ")" ::: "memory")
; #define PG8_WAIT_L(n) asm volatile("s_waitcnt lgkmcnt(" #n ")" ::: "memory")
; template <class Epi, class Sched, bool ALIGN_EPI = false, bool SP2 = false>
; __device__ __forceinline__ void gemm_phase(PG8_LAS unsigned char* lds, const Gemm g, const Sched& S, const Epi& E) {
;     ...
;             const bool last = (t == nt - 2);
;             const char* a1 = cA + (size_t)(t + 1) * kstep;
;             const char* a2 = last ? nA : cA + (size_t)(t + 2) * kstep; const char* b2 = last ? nB : cB + (size_t)(t + 2) * kstep;
;             const char* a3 = a2 + kstep; const char* b3 = b2 + kstep;
;             if (last && has_next) S.a_ready(nxt);
;             if constexpr (SP2) {
;             PG8_LDB(B0, 0, 0); PG8_LDB(B1, 0, 1); PG8_SCHED; PG8_LDA(At, 0, 0); PG8_STAGE(PG8_SA(1, 1), a1 + hstepA, voffA);
;             PG8_WAIT_V(8); PG8_WAIT_L(0); PG8_BAR; PG8_MMA(0, 0, At, B0); PG8_MMA(0, 1, At, B1); PG8_BAR; PG8_SCHED;
;             PG8_LDA(At, 0, 1); PG8_STAGE(PG8_SB(0, 0), b2, voffB); PG8_STAGE(PG8_SB(0, 1), b2 + hstepB, voffB); PG8_STAGE(PG8_SA(0, 0), a2, voffA);
;             PG8_WAIT_V(8); PG8_WAIT_L(0); PG8_BAR; PG8_MMA(1, 0, At, B0); PG8_MMA(1, 1, At, B1); PG8_BAR; PG8_SCHED;
.LBB0_156:
	v_add_u32_e32 v156, s25, v149
	v_add_u32_e32 v172, s40, v149
	ds_read_b128 v[140:143], v156
	ds_read_b128 v[144:147], v156 offset:1024
	ds_read_b128 v[152:155], v156 offset:2048
	ds_read_b128 v[156:159], v156 offset:3072
	ds_read_b128 v[160:163], v172
	ds_read_b128 v[164:167], v172 offset:1024
	ds_read_b128 v[168:171], v172 offset:2048
	ds_read_b128 v[172:175], v172 offset:3072
	s_add_u32 s2, s26, 0xfffc0080
	s_addc_u32 s8, s27, -1
	s_cmp_eq_u32 s78, 12
	s_cselect_b32 s31, s19, s8
	s_cselect_b32 s30, s71, s2
	s_cselect_b32 s29, s17, s75
	s_cselect_b32 s28, s72, s74
	v_lshl_add_u64 v[226:227], s[26:27], 0, v[138:139]
	s_add_i32 m0, s43, 0xc000
	ds_read_b128 v[176:179], v151
	ds_read_b128 v[180:183], v151 offset:1024
	ds_read_b128 v[184:187], v151 offset:2048
	ds_read_b128 v[188:191], v151 offset:3072
	ds_read_b128 v[204:207], v151 offset:4096
	ds_read_b128 v[208:211], v151 offset:5120
	ds_read_b128 v[218:221], v151 offset:6144
	ds_read_b128 v[222:225], v151 offset:7168
	global_load_lds_dwordx4 v[226:227], off
	v_lshl_add_u64 v[226:227], s[26:27], 0, v[136:137]
	s_add_i32 m0, s43, 0xe000
	s_nop 0
	global_load_lds_dwordx4 v[226:227], off
	s_waitcnt vmcnt(8)
	s_waitcnt lgkmcnt(0)
	s_barrier
	s_waitcnt lgkmcnt(0)
	v_mfma_f32_16x16x32_bf16 v[116:119], v[140:143], v[176:179], v[116:119]
	v_mfma_f32_16x16x32_bf16 v[112:115], v[152:155], v[176:179], v[112:115]
	v_mfma_f32_16x16x32_bf16 v[108:111], v[140:143], v[184:187], v[108:111]
	v_mfma_f32_16x16x32_bf16 v[104:107], v[152:155], v[184:187], v[104:107]
	v_mfma_f32_16x16x32_bf16 v[92:95], v[140:143], v[204:207], v[92:95]
	v_mfma_f32_16x16x32_bf16 v[88:91], v[152:155], v[204:207], v[88:91]
	v_mfma_f32_16x16x32_bf16 v[76:79], v[140:143], v[218:221], v[76:79]
	v_mfma_f32_16x16x32_bf16 v[72:75], v[152:155], v[218:221], v[72:75]
	v_mfma_f32_16x16x32_bf16 v[116:119], v[144:147], v[180:183], v[116:119]
	v_mfma_f32_16x16x32_bf16 v[112:115], v[156:159], v[180:183], v[112:115]
	v_mfma_f32_16x16x32_bf16 v[108:111], v[144:147], v[188:191], v[108:111]
	v_mfma_f32_16x16x32_bf16 v[104:107], v[156:159], v[188:191], v[104:107]
	v_mfma_f32_16x16x32_bf16 v[92:95], v[144:147], v[208:211], v[92:95]
	v_mfma_f32_16x16x32_bf16 v[88:91], v[156:159], v[208:211], v[88:91]
	v_mfma_f32_16x16x32_bf16 v[76:79], v[144:147], v[222:225], v[76:79]
	v_mfma_f32_16x16x32_bf16 v[72:75], v[156:159], v[222:225], v[72:75]
	v_mfma_f32_16x16x32_bf16 v[124:127], v[160:163], v[176:179], v[124:127]
	v_mfma_f32_16x16x32_bf16 v[120:123], v[168:171], v[176:179], v[120:123]
	v_mfma_f32_16x16x32_bf16 v[100:103], v[160:163], v[184:187], v[100:103]
	v_mfma_f32_16x16x32_bf16 v[96:99], v[168:171], v[184:187], v[96:99]
	v_mfma_f32_16x16x32_bf16 v[84:87], v[160:163], v[204:207], v[84:87]
	v_mfma_f32_16x16x32_bf16 v[80:83], v[168:171], v[204:207], v[80:83]
	v_mfma_f32_16x16x32_bf16 v[68:71], v[160:163], v[218:221], v[68:71]
	v_mfma_f32_16x16x32_bf16 v[64:67], v[168:171], v[218:221], v[64:67]
	v_mfma_f32_16x16x32_bf16 v[124:127], v[164:167], v[180:183], v[124:127]
	v_mfma_f32_16x16x32_bf16 v[120:123], v[172:175], v[180:183], v[120:123]
	v_mfma_f32_16x16x32_bf16 v[100:103], v[164:167], v[188:191], v[100:103]
	v_mfma_f32_16x16x32_bf16 v[96:99], v[172:175], v[188:191], v[96:99]
	v_mfma_f32_16x16x32_bf16 v[84:87], v[164:167], v[208:211], v[84:87]
	v_mfma_f32_16x16x32_bf16 v[80:83], v[172:175], v[208:211], v[80:83]
	v_mfma_f32_16x16x32_bf16 v[68:71], v[164:167], v[222:225], v[68:71]
	v_mfma_f32_16x16x32_bf16 v[64:67], v[172:175], v[222:225], v[64:67]
	s_barrier
	s_mov_b32 m0, s38
	v_lshl_add_u64 v[226:227], s[28:29], 0, v[192:193]
	s_add_u32 s8, s28, 0x40000
	ds_read_b128 v[176:179], v151 offset:16384
	ds_read_b128 v[180:183], v151 offset:17408
	ds_read_b128 v[184:187], v151 offset:18432
	ds_read_b128 v[188:191], v151 offset:19456
	ds_read_b128 v[204:207], v151 offset:20480
	ds_read_b128 v[208:211], v151 offset:21504
	ds_read_b128 v[218:221], v151 offset:22528
	ds_read_b128 v[222:225], v151 offset:23552
	global_load_lds_dwordx4 v[226:227], off
	v_lshl_add_u64 v[228:229], s[28:29], 0, v[128:129]
	s_mov_b32 m0, s39
	s_addc_u32 s9, s29, 0
	global_load_lds_dwordx4 v[228:229], off
	v_lshl_add_u64 v[230:231], s[8:9], 0, v[192:193]
	s_mov_b32 m0, s41
	v_lshl_add_u64 v[232:233], s[30:31], 0, v[130:131]
	global_load_lds_dwordx4 v[230:231], off
	v_lshl_add_u64 v[230:231], s[8:9], 0, v[128:129]
	s_mov_b32 m0, s42
	s_nop 0
	global_load_lds_dwordx4 v[230:231], off
	v_lshl_add_u64 v[230:231], s[30:31], 0, v[132:133]
	s_mov_b32 m0, s43
	s_nop 0
	global_load_lds_dwordx4 v[230:231], off
	s_mov_b32 m0, s44
	s_nop 0
	global_load_lds_dwordx4 v[232:233], off
	s_waitcnt vmcnt(8)
	s_waitcnt lgkmcnt(0)
	s_barrier
; #define PG8_STAGE(bufoff, gbase, voff) do { _Pragma("unroll") for (int _i = 0; _i < 2; ++_i) \
;         __builtin_amdgcn_global_load_lds((const unsigned*)((const char*)(gbase) + (voff)[_i]), (PG8_LAS unsigned*)(lds + (bufoff) + ldsw + _i * 8192), 16, 0, 0); } while (0)
; #define PG8_LDA(dst, b, h) do { _Pragma("unroll") for (int m = 0; m < 4; ++m) _Pragma("unroll") for (int k = 0; k < 2; ++k) dst[m][k] = *(const PG8_LAS bf16x8*)(lds + PG8_SA(b, h) + aoff + m * 2048 + k * 1024); } while (0)
; #define PG8_LDB(dst, b, h) do { _Pragma("unroll") for (int n = 0; n < 2; ++n) _Pragma("unroll") for (int k = 0; k < 2; ++k) dst[n][k] = *(const PG8_LAS bf16x8*)(lds + PG8_SB(b, h) + boff + n * 2048 + k * 1024); } while (0)
; #define PG8_MMA(ai, bj, At, Bt) do { __builtin_amdgcn_s_setprio(1); _Pragma("unroll") for (int m = 0; m < 4; ++m) _Pragma("unroll") for (int n = 0; n < 2; ++n) _Pragma("unroll") for (int k = 0; k < 2; ++k) \
;         acc[ai][bj][m][n] = __builtin_amdgcn_mfma_f32_16x16x32_bf16(Bt[n][k], At[m][k], acc[ai][bj][m][n], 0, 0, 0); __builtin_amdgcn_s_setprio(0); } while (0)
; #define PG8_WAIT_V(n) asm volatile("s_waitcnt vmcnt(" #n ")" ::: "memory")
; #define PG8_WAIT_L(n) asm volatile("s_waitcnt lgkmcnt(" #n ")" ::: "memory")
; #define PG8_BAR __builtin_amdgcn_s_barrier()
; #define PG8_SCHED __builtin_amdgcn_sched_barrier(0)
; template <class Epi, class Sched, bool ALIGN_EPI = false, bool SP2 = false>
; __device__ __forceinline__ void gemm_phase(PG8_LAS unsigned char* lds, const Gemm g, const Sched& S, const Epi& E) {
;     ...
;             PG8_WAIT_V(8); PG8_WAIT_L(0); PG8_BAR; PG8_MMA(1, 0, At, B0); PG8_MMA(1, 1, At, B1); PG8_BAR; PG8_SCHED;
;             PG8_LDB(B0, 1, 0); PG8_LDB(B1, 1, 1); PG8_SCHED; PG8_LDA(At, 1, 0); PG8_STAGE(PG8_SA(0, 1), a2 + hstepA, voffA);
;             PG8_WAIT_V(8); PG8_WAIT_L(0); PG8_BAR; PG8_MMA(0, 0, At, B0); PG8_MMA(0, 1, At, B1); PG8_BAR; PG8_SCHED;
	s_waitcnt lgkmcnt(0)
	v_mfma_f32_16x16x32_bf16 v[60:63], v[140:143], v[176:179], v[60:63]
	v_mfma_f32_16x16x32_bf16 v[56:59], v[152:155], v[176:179], v[56:59]
	v_mfma_f32_16x16x32_bf16 v[44:47], v[140:143], v[184:187], v[44:47]
	v_mfma_f32_16x16x32_bf16 v[40:43], v[152:155], v[184:187], v[40:43]
	v_mfma_f32_16x16x32_bf16 v[28:31], v[140:143], v[204:207], v[28:31]
	v_mfma_f32_16x16x32_bf16 v[24:27], v[152:155], v[204:207], v[24:27]
	v_mfma_f32_16x16x32_bf16 v[12:15], v[140:143], v[218:221], v[12:15]
	v_mfma_f32_16x16x32_bf16 v[8:11], v[152:155], v[218:221], v[8:11]
	v_mfma_f32_16x16x32_bf16 v[60:63], v[144:147], v[180:183], v[60:63]
	v_mfma_f32_16x16x32_bf16 v[56:59], v[156:159], v[180:183], v[56:59]
	v_mfma_f32_16x16x32_bf16 v[44:47], v[144:147], v[188:191], v[44:47]
	v_mfma_f32_16x16x32_bf16 v[40:43], v[156:159], v[188:191], v[40:43]
	v_mfma_f32_16x16x32_bf16 v[28:31], v[144:147], v[208:211], v[28:31]
	v_mfma_f32_16x16x32_bf16 v[24:27], v[156:159], v[208:211], v[24:27]
	v_mfma_f32_16x16x32_bf16 v[12:15], v[144:147], v[222:225], v[12:15]
	v_mfma_f32_16x16x32_bf16 v[8:11], v[156:159], v[222:225], v[8:11]
	v_mfma_f32_16x16x32_bf16 v[52:55], v[160:163], v[176:179], v[52:55]
	v_mfma_f32_16x16x32_bf16 v[48:51], v[168:171], v[176:179], v[48:51]
	v_mfma_f32_16x16x32_bf16 v[36:39], v[160:163], v[184:187], v[36:39]
	v_mfma_f32_16x16x32_bf16 v[32:35], v[168:171], v[184:187], v[32:35]
	v_mfma_f32_16x16x32_bf16 v[20:23], v[160:163], v[204:207], v[20:23]
	v_mfma_f32_16x16x32_bf16 v[16:19], v[168:171], v[204:207], v[16:19]
	v_mfma_f32_16x16x32_bf16 v[4:7], v[160:163], v[218:221], v[4:7]
	v_mfma_f32_16x16x32_bf16 v[0:3], v[168:171], v[218:221], v[0:3]
	v_mfma_f32_16x16x32_bf16 v[52:55], v[164:167], v[180:183], v[52:55]
	v_mfma_f32_16x16x32_bf16 v[48:51], v[172:175], v[180:183], v[48:51]
	v_mfma_f32_16x16x32_bf16 v[36:39], v[164:167], v[188:191], v[36:39]
	v_mfma_f32_16x16x32_bf16 v[32:35], v[172:175], v[188:191], v[32:35]
	v_mfma_f32_16x16x32_bf16 v[20:23], v[164:167], v[208:211], v[20:23]
	v_mfma_f32_16x16x32_bf16 v[16:19], v[172:175], v[208:211], v[16:19]
	v_mfma_f32_16x16x32_bf16 v[4:7], v[164:167], v[222:225], v[4:7]
	v_mfma_f32_16x16x32_bf16 v[0:3], v[172:175], v[222:225], v[0:3]
	s_barrier
	v_add_u32_e32 v156, s49, v149
	v_add_u32_e32 v172, s64, v149
	ds_read_b128 v[140:143], v156
	ds_read_b128 v[144:147], v156 offset:1024
	ds_read_b128 v[152:155], v156 offset:2048
	ds_read_b128 v[156:159], v156 offset:3072
	ds_read_b128 v[160:163], v172
	ds_read_b128 v[164:167], v172 offset:1024
	ds_read_b128 v[168:171], v172 offset:2048
	ds_read_b128 v[172:175], v172 offset:3072
	s_add_u32 s8, s30, 0x40000
	s_addc_u32 s9, s31, 0
	s_mov_b32 m0, s45
	v_lshl_add_u64 v[234:235], s[8:9], 0, v[132:133]
	ds_read_b128 v[176:179], v151 offset:32768
	ds_read_b128 v[180:183], v151 offset:33792
	ds_read_b128 v[184:187], v151 offset:34816
	ds_read_b128 v[188:191], v151 offset:35840
	ds_read_b128 v[204:207], v151 offset:36864
	ds_read_b128 v[208:211], v151 offset:37888
	ds_read_b128 v[218:221], v151 offset:38912
	ds_read_b128 v[222:225], v151 offset:39936
	global_load_lds_dwordx4 v[234:235], off
	v_lshl_add_u64 v[234:235], s[8:9], 0, v[130:131]
	s_mov_b32 m0, s48
	s_nop 0
	global_load_lds_dwordx4 v[234:235], off
	s_waitcnt vmcnt(8)
	s_waitcnt lgkmcnt(0)
	s_barrier
	s_waitcnt lgkmcnt(0)
	v_mfma_f32_16x16x32_bf16 v[116:119], v[140:143], v[176:179], v[116:119]
	v_mfma_f32_16x16x32_bf16 v[112:115], v[152:155], v[176:179], v[112:115]
	v_mfma_f32_16x16x32_bf16 v[108:111], v[140:143], v[184:187], v[108:111]
	v_mfma_f32_16x16x32_bf16 v[104:107], v[152:155], v[184:187], v[104:107]
	v_mfma_f32_16x16x32_bf16 v[92:95], v[140:143], v[204:207], v[92:95]
	v_mfma_f32_16x16x32_bf16 v[88:91], v[152:155], v[204:207], v[88:91]
	v_mfma_f32_16x16x32_bf16 v[76:79], v[140:143], v[218:221], v[76:79]
	v_mfma_f32_16x16x32_bf16 v[72:75], v[152:155], v[218:221], v[72:75]
	v_mfma_f32_16x16x32_bf16 v[116:119], v[144:147], v[180:183], v[116:119]
	v_mfma_f32_16x16x32_bf16 v[112:115], v[156:159], v[180:183], v[112:115]
	v_mfma_f32_16x16x32_bf16 v[108:111], v[144:147], v[188:191], v[108:111]
	v_mfma_f32_16x16x32_bf16 v[104:107], v[156:159], v[188:191], v[104:107]
	v_mfma_f32_16x16x32_bf16 v[92:95], v[144:147], v[208:211], v[92:95]
	v_mfma_f32_16x16x32_bf16 v[88:91], v[156:159], v[208:211], v[88:91]
	v_mfma_f32_16x16x32_bf16 v[76:79], v[144:147], v[222:225], v[76:79]
	v_mfma_f32_16x16x32_bf16 v[72:75], v[156:159], v[222:225], v[72:75]
	v_mfma_f32_16x16x32_bf16 v[124:127], v[160:163], v[176:179], v[124:127]
	v_mfma_f32_16x16x32_bf16 v[120:123], v[168:171], v[176:179], v[120:123]
	v_mfma_f32_16x16x32_bf16 v[100:103], v[160:163], v[184:187], v[100:103]
	v_mfma_f32_16x16x32_bf16 v[96:99], v[168:171], v[184:187], v[96:99]
	v_mfma_f32_16x16x32_bf16 v[84:87], v[160:163], v[204:207], v[84:87]
	v_mfma_f32_16x16x32_bf16 v[80:83], v[168:171], v[204:207], v[80:83]
	v_mfma_f32_16x16x32_bf16 v[68:71], v[160:163], v[218:221], v[68:71]
	v_mfma_f32_16x16x32_bf16 v[64:67], v[168:171], v[218:221], v[64:67]
	v_mfma_f32_16x16x32_bf16 v[124:127], v[164:167], v[180:183], v[124:127]
	v_mfma_f32_16x16x32_bf16 v[120:123], v[172:175], v[180:183], v[120:123]
	v_mfma_f32_16x16x32_bf16 v[100:103], v[164:167], v[188:191], v[100:103]
	v_mfma_f32_16x16x32_bf16 v[96:99], v[172:175], v[188:191], v[96:99]
	v_mfma_f32_16x16x32_bf16 v[84:87], v[164:167], v[208:211], v[84:87]
	v_mfma_f32_16x16x32_bf16 v[80:83], v[172:175], v[208:211], v[80:83]
	v_mfma_f32_16x16x32_bf16 v[68:71], v[164:167], v[222:225], v[68:71]
	v_mfma_f32_16x16x32_bf16 v[64:67], v[172:175], v[222:225], v[64:67]
	s_barrier
; #define PG8_STAGE(bufoff, gbase, voff) do { _Pragma("unroll") for (int _i = 0; _i < 2; ++_i) \
;         __builtin_amdgcn_global_load_lds((const unsigned*)((const char*)(gbase) + (voff)[_i]), (PG8_LAS unsigned*)(lds + (bufoff) + ldsw + _i * 8192), 16, 0, 0); } while (0)
; #define PG8_LDA(dst, b, h) do { _Pragma("unroll") for (int m = 0; m < 4; ++m) _Pragma("unroll") for (int k = 0; k < 2; ++k) dst[m][k] = *(const PG8_LAS bf16x8*)(lds + PG8_SA(b, h) + aoff + m * 2048 + k * 1024); } while (0)
; #define PG8_MMA(ai, bj, At, Bt) do { __builtin_amdgcn_s_setprio(1); _Pragma("unroll") for (int m = 0; m < 4; ++m) _Pragma("unroll") for (int n = 0; n < 2; ++n) _Pragma("unroll") for (int k = 0; k < 2; ++k) \
;         acc[ai][bj][m][n] = __builtin_amdgcn_mfma_f32_16x16x32_bf16(Bt[n][k], At[m][k], acc[ai][bj][m][n], 0, 0, 0); __builtin_amdgcn_s_setprio(0); } while (0)
; #define PG8_WAIT_V(n) asm volatile("s_waitcnt vmcnt(" #n ")" ::: "memory")
; #define PG8_WAIT_L(n) asm volatile("s_waitcnt lgkmcnt(" #n ")" ::: "memory")
; #define PG8_BAR __builtin_amdgcn_s_barrier()
; #define PG8_SCHED __builtin_amdgcn_sched_barrier(0)
; template <class Epi, class Sched, bool ALIGN_EPI = false, bool SP2 = false>
; __device__ __forceinline__ void gemm_phase(PG8_LAS unsigned char* lds, const Gemm g, const Sched& S, const Epi& E) {
;     ...
;         for (int t = 0; t < nt; t += 2) {
;     ...
;             PG8_LDA(At, 1, 1); PG8_STAGE(PG8_SB(1, 0), b3, voffB); PG8_STAGE(PG8_SB(1, 1), b3 + hstepB, voffB); PG8_STAGE(PG8_SA(1, 0), a3, voffA);
;             PG8_WAIT_V(8); PG8_WAIT_L(0); PG8_BAR; PG8_MMA(1, 0, At, B0); PG8_MMA(1, 1, At, B1); PG8_BAR; PG8_SCHED;
	s_mov_b32 m0, s50
	v_lshl_add_u64 v[226:227], v[226:227], 0, s[76:77]
	s_add_u32 s8, s28, 0x40080
	ds_read_b128 v[176:179], v151 offset:49152
	ds_read_b128 v[180:183], v151 offset:50176
	ds_read_b128 v[184:187], v151 offset:51200
	ds_read_b128 v[188:191], v151 offset:52224
	ds_read_b128 v[204:207], v151 offset:53248
	ds_read_b128 v[208:211], v151 offset:54272
	ds_read_b128 v[218:221], v151 offset:55296
	ds_read_b128 v[222:225], v151 offset:56320
	global_load_lds_dwordx4 v[226:227], off
	v_lshl_add_u64 v[226:227], v[228:229], 0, s[76:77]
	s_mov_b32 m0, s51
	s_addc_u32 s9, s29, 0
	global_load_lds_dwordx4 v[226:227], off
	v_lshl_add_u64 v[226:227], s[8:9], 0, v[192:193]
	s_mov_b32 m0, s65
	s_nop 0
	global_load_lds_dwordx4 v[226:227], off
	v_lshl_add_u64 v[226:227], s[8:9], 0, v[128:129]
	s_mov_b32 m0, s66
	s_nop 0
	global_load_lds_dwordx4 v[226:227], off
	v_lshl_add_u64 v[226:227], v[230:231], 0, s[76:77]
	s_mov_b32 m0, s60
	s_nop 0
	global_load_lds_dwordx4 v[226:227], off
	v_lshl_add_u64 v[226:227], v[232:233], 0, s[76:77]
	s_mov_b32 m0, s61
	s_nop 0
	global_load_lds_dwordx4 v[226:227], off
	s_waitcnt vmcnt(8)
	s_waitcnt lgkmcnt(0)
	s_barrier
	s_waitcnt lgkmcnt(0)
	v_mfma_f32_16x16x32_bf16 v[60:63], v[140:143], v[176:179], v[60:63]
	v_mfma_f32_16x16x32_bf16 v[56:59], v[152:155], v[176:179], v[56:59]
	v_mfma_f32_16x16x32_bf16 v[44:47], v[140:143], v[184:187], v[44:47]
	v_mfma_f32_16x16x32_bf16 v[40:43], v[152:155], v[184:187], v[40:43]
	v_mfma_f32_16x16x32_bf16 v[28:31], v[140:143], v[204:207], v[28:31]
	v_mfma_f32_16x16x32_bf16 v[24:27], v[152:155], v[204:207], v[24:27]
	v_mfma_f32_16x16x32_bf16 v[12:15], v[140:143], v[218:221], v[12:15]
	v_mfma_f32_16x16x32_bf16 v[8:11], v[152:155], v[218:221], v[8:11]
	v_mfma_f32_16x16x32_bf16 v[60:63], v[144:147], v[180:183], v[60:63]
	v_mfma_f32_16x16x32_bf16 v[56:59], v[156:159], v[180:183], v[56:59]
	v_mfma_f32_16x16x32_bf16 v[44:47], v[144:147], v[188:191], v[44:47]
	v_mfma_f32_16x16x32_bf16 v[40:43], v[156:159], v[188:191], v[40:43]
	v_mfma_f32_16x16x32_bf16 v[28:31], v[144:147], v[208:211], v[28:31]
	v_mfma_f32_16x16x32_bf16 v[24:27], v[156:159], v[208:211], v[24:27]
	v_mfma_f32_16x16x32_bf16 v[12:15], v[144:147], v[222:225], v[12:15]
	v_mfma_f32_16x16x32_bf16 v[8:11], v[156:159], v[222:225], v[8:11]
	v_mfma_f32_16x16x32_bf16 v[52:55], v[160:163], v[176:179], v[52:55]
	v_mfma_f32_16x16x32_bf16 v[48:51], v[168:171], v[176:179], v[48:51]
	v_mfma_f32_16x16x32_bf16 v[36:39], v[160:163], v[184:187], v[36:39]
	v_mfma_f32_16x16x32_bf16 v[32:35], v[168:171], v[184:187], v[32:35]
	v_mfma_f32_16x16x32_bf16 v[20:23], v[160:163], v[204:207], v[20:23]
	v_mfma_f32_16x16x32_bf16 v[16:19], v[168:171], v[204:207], v[16:19]
	v_mfma_f32_16x16x32_bf16 v[4:7], v[160:163], v[218:221], v[4:7]
	v_mfma_f32_16x16x32_bf16 v[0:3], v[168:171], v[218:221], v[0:3]
	v_mfma_f32_16x16x32_bf16 v[52:55], v[164:167], v[180:183], v[52:55]
	v_mfma_f32_16x16x32_bf16 v[48:51], v[172:175], v[180:183], v[48:51]
	v_mfma_f32_16x16x32_bf16 v[36:39], v[164:167], v[188:191], v[36:39]
	v_mfma_f32_16x16x32_bf16 v[32:35], v[172:175], v[188:191], v[32:35]
	v_mfma_f32_16x16x32_bf16 v[20:23], v[164:167], v[208:211], v[20:23]
	v_mfma_f32_16x16x32_bf16 v[16:19], v[172:175], v[208:211], v[16:19]
	v_mfma_f32_16x16x32_bf16 v[4:7], v[164:167], v[222:225], v[4:7]
	v_mfma_f32_16x16x32_bf16 v[0:3], v[172:175], v[222:225], v[0:3]
	s_barrier
	s_add_i32 s78, s78, 2
	s_add_u32 s74, s74, 0x100
	s_addc_u32 s75, s75, 0
	s_add_u32 s26, s26, 0x100
	s_addc_u32 s27, s27, 0
	s_cmp_gt_u32 s78, 13
	s_cbranch_scc0 .LBB0_156
	s_and_b64 vcc, exec, s[14:15]
	s_cbranch_vccz .LBB0_159
	s_barrier

; #define PG8_STAGE(bufoff, gbase, voff) do { _Pragma("unroll") for (int _i = 0; _i < 2; ++_i) \
;         __builtin_amdgcn_global_load_lds((const unsigned*)((const char*)(gbase) + (voff)[_i]), (PG8_LAS unsigned*)(lds + (bufoff) + ldsw + _i * 8192), 16, 0, 0); } while (0)
; #define PG8_LDA(dst, b, h) do { _Pragma("unroll") for (int m = 0; m < 4; ++m) _Pragma("unroll") for (int k = 0; k < 2; ++k) dst[m][k] = *(const PG8_LAS bf16x8*)(lds + PG8_SA(b, h) + aoff + m * 2048 + k * 1024); } while (0)
; #define PG8_LDB(dst, b, h) do { _Pragma("unroll") for (int n = 0; n < 2; ++n) _Pragma("unroll") for (int k = 0; k < 2; ++k) dst[n][k] = *(const PG8_LAS bf16x8*)(lds + PG8_SB(b, h) + boff + n * 2048 + k * 1024); } while (0)
; #define PG8_MMA(ai, bj, At, Bt) do { __builtin_amdgcn_s_setprio(1); _Pragma("unroll") for (int m = 0; m < 4; ++m) _Pragma("unroll") for (int n = 0; n < 2; ++n) _Pragma("unroll") for (int k = 0; k < 2; ++k) \
;         acc[ai][bj][m][n] = __builtin_amdgcn_mfma_f32_16x16x32_bf16(Bt[n][k], At[m][k], acc[ai][bj][m][n], 0, 0, 0); __builtin_amdgcn_s_setprio(0); } while (0)
; #define PG8_WAIT_V(n) asm volatile("s_waitcnt vmcnt(" #n ")" ::: "memory")
; #define PG8_WAIT_L(n) asm volatile("s_waitcnt lgkmcnt(" #n ")" ::: "memory")
; template <class Epi, class Sched, bool ALIGN_EPI = false, bool SP2 = false>
; __device__ __forceinline__ void gemm_phase(PG8_LAS unsigned char* lds, const Gemm g, const Sched& S, const Epi& E) {
;     ...
;             const bool last = (t == nt - 2);
;             const char* a1 = cA + (size_t)(t + 1) * kstep;
;             const char* a2 = last ? nA : cA + (size_t)(t + 2) * kstep; const char* b2 = last ? nB : cB + (size_t)(t + 2) * kstep;
;             const char* a3 = a2 + kstep; const char* b3 = b2 + kstep;
;             if (last && has_next) S.a_ready(nxt);
;             if constexpr (SP2) {
;             PG8_LDB(B0, 0, 0); PG8_LDB(B1, 0, 1); PG8_SCHED; PG8_LDA(At, 0, 0); PG8_STAGE(PG8_SA(1, 1), a1 + hstepA, voffA);
;             PG8_WAIT_V(8); PG8_WAIT_L(0); PG8_BAR; PG8_MMA(0, 0, At, B0); PG8_MMA(0, 1, At, B1); PG8_BAR; PG8_SCHED;
;             PG8_LDA(At, 0, 1); PG8_STAGE(PG8_SB(0, 0), b2, voffB); PG8_STAGE(PG8_SB(0, 1), b2 + hstepB, voffB); PG8_STAGE(PG8_SA(0, 0), a2, voffA);
;             PG8_WAIT_V(8); PG8_WAIT_L(0); PG8_BAR; PG8_MMA(1, 0, At, B0); PG8_MMA(1, 1, At, B1); PG8_BAR; PG8_SCHED;
.LBB0_180:
	v_add_u32_e32 v154, s38, v139
	v_add_u32_e32 v170, s41, v139
	ds_read_b128 v[142:145], v154
	ds_read_b128 v[146:149], v154 offset:1024
	ds_read_b128 v[150:153], v154 offset:2048
	ds_read_b128 v[154:157], v154 offset:3072
	ds_read_b128 v[158:161], v170
	ds_read_b128 v[162:165], v170 offset:1024
	ds_read_b128 v[166:169], v170 offset:2048
	ds_read_b128 v[170:173], v170 offset:3072
	s_add_u32 s2, s24, 0xfffc0080
	s_addc_u32 s8, s25, -1
	s_cmp_eq_u32 s75, 12
	s_cselect_b32 s29, s1, s8
	s_cselect_b32 s28, s19, s2
	s_cselect_b32 s27, s17, s74
	s_cselect_b32 s26, s71, s72
	v_lshl_add_u64 v[190:191], s[24:25], 0, v[136:137]
	s_add_i32 m0, s44, 0xc000
	ds_read_b128 v[174:177], v141
	ds_read_b128 v[178:181], v141 offset:1024
	ds_read_b128 v[182:185], v141 offset:2048
	ds_read_b128 v[186:189], v141 offset:3072
	ds_read_b128 v[204:207], v141 offset:4096
	ds_read_b128 v[208:211], v141 offset:5120
	ds_read_b128 v[218:221], v141 offset:6144
	ds_read_b128 v[222:225], v141 offset:7168
	global_load_lds_dwordx4 v[190:191], off
	v_lshl_add_u64 v[190:191], s[24:25], 0, v[134:135]
	s_add_i32 m0, s44, 0xe000
	s_nop 0
	global_load_lds_dwordx4 v[190:191], off
	s_waitcnt vmcnt(8)
	s_waitcnt lgkmcnt(0)
	s_barrier
	s_waitcnt lgkmcnt(0)
	v_mfma_f32_16x16x32_bf16 v[124:127], v[142:145], v[174:177], v[124:127]
	v_mfma_f32_16x16x32_bf16 v[120:123], v[150:153], v[174:177], v[120:123]
	v_mfma_f32_16x16x32_bf16 v[116:119], v[142:145], v[182:185], v[116:119]
	v_mfma_f32_16x16x32_bf16 v[112:115], v[150:153], v[182:185], v[112:115]
	v_mfma_f32_16x16x32_bf16 v[100:103], v[142:145], v[204:207], v[100:103]
	v_mfma_f32_16x16x32_bf16 v[96:99], v[150:153], v[204:207], v[96:99]
	v_mfma_f32_16x16x32_bf16 v[84:87], v[142:145], v[218:221], v[84:87]
	v_mfma_f32_16x16x32_bf16 v[80:83], v[150:153], v[218:221], v[80:83]
	v_mfma_f32_16x16x32_bf16 v[124:127], v[146:149], v[178:181], v[124:127]
	v_mfma_f32_16x16x32_bf16 v[120:123], v[154:157], v[178:181], v[120:123]
	v_mfma_f32_16x16x32_bf16 v[116:119], v[146:149], v[186:189], v[116:119]
	v_mfma_f32_16x16x32_bf16 v[112:115], v[154:157], v[186:189], v[112:115]
	v_mfma_f32_16x16x32_bf16 v[100:103], v[146:149], v[208:211], v[100:103]
	v_mfma_f32_16x16x32_bf16 v[96:99], v[154:157], v[208:211], v[96:99]
	v_mfma_f32_16x16x32_bf16 v[84:87], v[146:149], v[222:225], v[84:87]
	v_mfma_f32_16x16x32_bf16 v[80:83], v[154:157], v[222:225], v[80:83]
	v_mfma_f32_16x16x32_bf16 v[108:111], v[158:161], v[174:177], v[108:111]
	v_mfma_f32_16x16x32_bf16 v[104:107], v[166:169], v[174:177], v[104:107]
	v_mfma_f32_16x16x32_bf16 v[92:95], v[158:161], v[182:185], v[92:95]
	v_mfma_f32_16x16x32_bf16 v[88:91], v[166:169], v[182:185], v[88:91]
	v_mfma_f32_16x16x32_bf16 v[76:79], v[158:161], v[204:207], v[76:79]
	v_mfma_f32_16x16x32_bf16 v[72:75], v[166:169], v[204:207], v[72:75]
	v_mfma_f32_16x16x32_bf16 v[68:71], v[158:161], v[218:221], v[68:71]
	v_mfma_f32_16x16x32_bf16 v[64:67], v[166:169], v[218:221], v[64:67]
	v_mfma_f32_16x16x32_bf16 v[108:111], v[162:165], v[178:181], v[108:111]
	v_mfma_f32_16x16x32_bf16 v[104:107], v[170:173], v[178:181], v[104:107]
	v_mfma_f32_16x16x32_bf16 v[92:95], v[162:165], v[186:189], v[92:95]
	v_mfma_f32_16x16x32_bf16 v[88:91], v[170:173], v[186:189], v[88:91]
	v_mfma_f32_16x16x32_bf16 v[76:79], v[162:165], v[208:211], v[76:79]
	v_mfma_f32_16x16x32_bf16 v[72:75], v[170:173], v[208:211], v[72:75]
	v_mfma_f32_16x16x32_bf16 v[68:71], v[162:165], v[222:225], v[68:71]
	v_mfma_f32_16x16x32_bf16 v[64:67], v[170:173], v[222:225], v[64:67]
	s_barrier
	s_mov_b32 m0, s39
	v_lshl_add_u64 v[190:191], s[26:27], 0, v[192:193]
	s_add_u32 s8, s26, 0x40000
	ds_read_b128 v[174:177], v141 offset:16384
	ds_read_b128 v[178:181], v141 offset:17408
	ds_read_b128 v[182:185], v141 offset:18432
	ds_read_b128 v[186:189], v141 offset:19456
	ds_read_b128 v[204:207], v141 offset:20480
	ds_read_b128 v[208:211], v141 offset:21504
	ds_read_b128 v[218:221], v141 offset:22528
	ds_read_b128 v[222:225], v141 offset:23552
	global_load_lds_dwordx4 v[190:191], off
	v_lshl_add_u64 v[226:227], s[26:27], 0, v[132:133]
	s_mov_b32 m0, s40
	s_addc_u32 s9, s27, 0
	global_load_lds_dwordx4 v[226:227], off
	v_lshl_add_u64 v[228:229], s[8:9], 0, v[192:193]
	s_mov_b32 m0, s42
	v_lshl_add_u64 v[230:231], s[28:29], 0, v[130:131]
	global_load_lds_dwordx4 v[228:229], off
	v_lshl_add_u64 v[228:229], s[8:9], 0, v[132:133]
	s_mov_b32 m0, s43
	s_nop 0
	global_load_lds_dwordx4 v[228:229], off
	v_lshl_add_u64 v[228:229], s[28:29], 0, v[128:129]
	s_mov_b32 m0, s44
	s_nop 0
	global_load_lds_dwordx4 v[228:229], off
	s_mov_b32 m0, s45
	s_nop 0
	global_load_lds_dwordx4 v[230:231], off
	s_waitcnt vmcnt(8)
	s_waitcnt lgkmcnt(0)
	s_barrier
; #define PG8_STAGE(bufoff, gbase, voff) do { _Pragma("unroll") for (int _i = 0; _i < 2; ++_i) \
;         __builtin_amdgcn_global_load_lds((const unsigned*)((const char*)(gbase) + (voff)[_i]), (PG8_LAS unsigned*)(lds + (bufoff) + ldsw + _i * 8192), 16, 0, 0); } while (0)
; #define PG8_LDA(dst, b, h) do { _Pragma("unroll") for (int m = 0; m < 4; ++m) _Pragma("unroll") for (int k = 0; k < 2; ++k) dst[m][k] = *(const PG8_LAS bf16x8*)(lds + PG8_SA(b, h) + aoff + m * 2048 + k * 1024); } while (0)
; #define PG8_LDB(dst, b, h) do { _Pragma("unroll") for (int n = 0; n < 2; ++n) _Pragma("unroll") for (int k = 0; k < 2; ++k) dst[n][k] = *(const PG8_LAS bf16x8*)(lds + PG8_SB(b, h) + boff + n * 2048 + k * 1024); } while (0)
; #define PG8_MMA(ai, bj, At, Bt) do { __builtin_amdgcn_s_setprio(1); _Pragma("unroll") for (int m = 0; m < 4; ++m) _Pragma("unroll") for (int n = 0; n < 2; ++n) _Pragma("unroll") for (int k = 0; k < 2; ++k) \
;         acc[ai][bj][m][n] = __builtin_amdgcn_mfma_f32_16x16x32_bf16(Bt[n][k], At[m][k], acc[ai][bj][m][n], 0, 0, 0); __builtin_amdgcn_s_setprio(0); } while (0)
; #define PG8_WAIT_V(n) asm volatile("s_waitcnt vmcnt(" #n ")" ::: "memory")
; #define PG8_WAIT_L(n) asm volatile("s_waitcnt lgkmcnt(" #n ")" ::: "memory")
; #define PG8_BAR __builtin_amdgcn_s_barrier()
; #define PG8_SCHED __builtin_amdgcn_sched_barrier(0)
; template <class Epi, class Sched, bool ALIGN_EPI = false, bool SP2 = false>
; __device__ __forceinline__ void gemm_phase(PG8_LAS unsigned char* lds, const Gemm g, const Sched& S, const Epi& E) {
;     ...
;             PG8_WAIT_V(8); PG8_WAIT_L(0); PG8_BAR; PG8_MMA(1, 0, At, B0); PG8_MMA(1, 1, At, B1); PG8_BAR; PG8_SCHED;
;             PG8_LDB(B0, 1, 0); PG8_LDB(B1, 1, 1); PG8_SCHED; PG8_LDA(At, 1, 0); PG8_STAGE(PG8_SA(0, 1), a2 + hstepA, voffA);
;             PG8_WAIT_V(8); PG8_WAIT_L(0); PG8_BAR; PG8_MMA(0, 0, At, B0); PG8_MMA(0, 1, At, B1); PG8_BAR; PG8_SCHED;
	s_waitcnt lgkmcnt(0)
	v_mfma_f32_16x16x32_bf16 v[60:63], v[142:145], v[174:177], v[60:63]
	v_mfma_f32_16x16x32_bf16 v[56:59], v[150:153], v[174:177], v[56:59]
	v_mfma_f32_16x16x32_bf16 v[52:55], v[142:145], v[182:185], v[52:55]
	v_mfma_f32_16x16x32_bf16 v[48:51], v[150:153], v[182:185], v[48:51]
	v_mfma_f32_16x16x32_bf16 v[36:39], v[142:145], v[204:207], v[36:39]
	v_mfma_f32_16x16x32_bf16 v[32:35], v[150:153], v[204:207], v[32:35]
	v_mfma_f32_16x16x32_bf16 v[20:23], v[142:145], v[218:221], v[20:23]
	v_mfma_f32_16x16x32_bf16 v[16:19], v[150:153], v[218:221], v[16:19]
	v_mfma_f32_16x16x32_bf16 v[60:63], v[146:149], v[178:181], v[60:63]
	v_mfma_f32_16x16x32_bf16 v[56:59], v[154:157], v[178:181], v[56:59]
	v_mfma_f32_16x16x32_bf16 v[52:55], v[146:149], v[186:189], v[52:55]
	v_mfma_f32_16x16x32_bf16 v[48:51], v[154:157], v[186:189], v[48:51]
	v_mfma_f32_16x16x32_bf16 v[36:39], v[146:149], v[208:211], v[36:39]
	v_mfma_f32_16x16x32_bf16 v[32:35], v[154:157], v[208:211], v[32:35]
	v_mfma_f32_16x16x32_bf16 v[20:23], v[146:149], v[222:225], v[20:23]
	v_mfma_f32_16x16x32_bf16 v[16:19], v[154:157], v[222:225], v[16:19]
	v_mfma_f32_16x16x32_bf16 v[44:47], v[158:161], v[174:177], v[44:47]
	v_mfma_f32_16x16x32_bf16 v[40:43], v[166:169], v[174:177], v[40:43]
	v_mfma_f32_16x16x32_bf16 v[28:31], v[158:161], v[182:185], v[28:31]
	v_mfma_f32_16x16x32_bf16 v[24:27], v[166:169], v[182:185], v[24:27]
	v_mfma_f32_16x16x32_bf16 v[12:15], v[158:161], v[204:207], v[12:15]
	v_mfma_f32_16x16x32_bf16 v[8:11], v[166:169], v[204:207], v[8:11]
	v_mfma_f32_16x16x32_bf16 v[4:7], v[158:161], v[218:221], v[4:7]
	v_mfma_f32_16x16x32_bf16 v[0:3], v[166:169], v[218:221], v[0:3]
	v_mfma_f32_16x16x32_bf16 v[44:47], v[162:165], v[178:181], v[44:47]
	v_mfma_f32_16x16x32_bf16 v[40:43], v[170:173], v[178:181], v[40:43]
	v_mfma_f32_16x16x32_bf16 v[28:31], v[162:165], v[186:189], v[28:31]
	v_mfma_f32_16x16x32_bf16 v[24:27], v[170:173], v[186:189], v[24:27]
	v_mfma_f32_16x16x32_bf16 v[12:15], v[162:165], v[208:211], v[12:15]
	v_mfma_f32_16x16x32_bf16 v[8:11], v[170:173], v[208:211], v[8:11]
	v_mfma_f32_16x16x32_bf16 v[4:7], v[162:165], v[222:225], v[4:7]
	v_mfma_f32_16x16x32_bf16 v[0:3], v[170:173], v[222:225], v[0:3]
	s_barrier
	v_add_u32_e32 v154, s50, v139
	v_add_u32_e32 v170, s65, v139
	ds_read_b128 v[142:145], v154
	ds_read_b128 v[146:149], v154 offset:1024
	ds_read_b128 v[150:153], v154 offset:2048
	ds_read_b128 v[154:157], v154 offset:3072
	ds_read_b128 v[158:161], v170
	ds_read_b128 v[162:165], v170 offset:1024
	ds_read_b128 v[166:169], v170 offset:2048
	ds_read_b128 v[170:173], v170 offset:3072
	s_add_u32 s8, s28, 0x40000
	s_addc_u32 s9, s29, 0
	s_mov_b32 m0, s48
	v_lshl_add_u64 v[232:233], s[8:9], 0, v[128:129]
	ds_read_b128 v[174:177], v141 offset:32768
	ds_read_b128 v[178:181], v141 offset:33792
	ds_read_b128 v[182:185], v141 offset:34816
	ds_read_b128 v[186:189], v141 offset:35840
	ds_read_b128 v[204:207], v141 offset:36864
	ds_read_b128 v[208:211], v141 offset:37888
	ds_read_b128 v[218:221], v141 offset:38912
	ds_read_b128 v[222:225], v141 offset:39936
	global_load_lds_dwordx4 v[232:233], off
	v_lshl_add_u64 v[232:233], s[8:9], 0, v[130:131]
	s_mov_b32 m0, s49
	s_nop 0
	global_load_lds_dwordx4 v[232:233], off
	s_waitcnt vmcnt(8)
	s_waitcnt lgkmcnt(0)
	s_barrier
	s_waitcnt lgkmcnt(0)
	v_mfma_f32_16x16x32_bf16 v[124:127], v[142:145], v[174:177], v[124:127]
	v_mfma_f32_16x16x32_bf16 v[120:123], v[150:153], v[174:177], v[120:123]
	v_mfma_f32_16x16x32_bf16 v[116:119], v[142:145], v[182:185], v[116:119]
	v_mfma_f32_16x16x32_bf16 v[112:115], v[150:153], v[182:185], v[112:115]
	v_mfma_f32_16x16x32_bf16 v[100:103], v[142:145], v[204:207], v[100:103]
	v_mfma_f32_16x16x32_bf16 v[96:99], v[150:153], v[204:207], v[96:99]
	v_mfma_f32_16x16x32_bf16 v[84:87], v[142:145], v[218:221], v[84:87]
	v_mfma_f32_16x16x32_bf16 v[80:83], v[150:153], v[218:221], v[80:83]
	v_mfma_f32_16x16x32_bf16 v[124:127], v[146:149], v[178:181], v[124:127]
	v_mfma_f32_16x16x32_bf16 v[120:123], v[154:157], v[178:181], v[120:123]
	v_mfma_f32_16x16x32_bf16 v[116:119], v[146:149], v[186:189], v[116:119]
	v_mfma_f32_16x16x32_bf16 v[112:115], v[154:157], v[186:189], v[112:115]
	v_mfma_f32_16x16x32_bf16 v[100:103], v[146:149], v[208:211], v[100:103]
	v_mfma_f32_16x16x32_bf16 v[96:99], v[154:157], v[208:211], v[96:99]
	v_mfma_f32_16x16x32_bf16 v[84:87], v[146:149], v[222:225], v[84:87]
	v_mfma_f32_16x16x32_bf16 v[80:83], v[154:157], v[222:225], v[80:83]
	v_mfma_f32_16x16x32_bf16 v[108:111], v[158:161], v[174:177], v[108:111]
	v_mfma_f32_16x16x32_bf16 v[104:107], v[166:169], v[174:177], v[104:107]
	v_mfma_f32_16x16x32_bf16 v[92:95], v[158:161], v[182:185], v[92:95]
	v_mfma_f32_16x16x32_bf16 v[88:91], v[166:169], v[182:185], v[88:91]
	v_mfma_f32_16x16x32_bf16 v[76:79], v[158:161], v[204:207], v[76:79]
	v_mfma_f32_16x16x32_bf16 v[72:75], v[166:169], v[204:207], v[72:75]
	v_mfma_f32_16x16x32_bf16 v[68:71], v[158:161], v[218:221], v[68:71]
	v_mfma_f32_16x16x32_bf16 v[64:67], v[166:169], v[218:221], v[64:67]
	v_mfma_f32_16x16x32_bf16 v[108:111], v[162:165], v[178:181], v[108:111]
	v_mfma_f32_16x16x32_bf16 v[104:107], v[170:173], v[178:181], v[104:107]
	v_mfma_f32_16x16x32_bf16 v[92:95], v[162:165], v[186:189], v[92:95]
	v_mfma_f32_16x16x32_bf16 v[88:91], v[170:173], v[186:189], v[88:91]
	v_mfma_f32_16x16x32_bf16 v[76:79], v[162:165], v[208:211], v[76:79]
	v_mfma_f32_16x16x32_bf16 v[72:75], v[170:173], v[208:211], v[72:75]
	v_mfma_f32_16x16x32_bf16 v[68:71], v[162:165], v[222:225], v[68:71]
	v_mfma_f32_16x16x32_bf16 v[64:67], v[170:173], v[222:225], v[64:67]
	s_barrier
; #define PG8_STAGE(bufoff, gbase, voff) do { _Pragma("unroll") for (int _i = 0; _i < 2; ++_i) \
;         __builtin_amdgcn_global_load_lds((const unsigned*)((const char*)(gbase) + (voff)[_i]), (PG8_LAS unsigned*)(lds + (bufoff) + ldsw + _i * 8192), 16, 0, 0); } while (0)
; #define PG8_LDA(dst, b, h) do { _Pragma("unroll") for (int m = 0; m < 4; ++m) _Pragma("unroll") for (int k = 0; k < 2; ++k) dst[m][k] = *(const PG8_LAS bf16x8*)(lds + PG8_SA(b, h) + aoff + m * 2048 + k * 1024); } while (0)
; #define PG8_MMA(ai, bj, At, Bt) do { __builtin_amdgcn_s_setprio(1); _Pragma("unroll") for (int m = 0; m < 4; ++m) _Pragma("unroll") for (int n = 0; n < 2; ++n) _Pragma("unroll") for (int k = 0; k < 2; ++k) \
;         acc[ai][bj][m][n] = __builtin_amdgcn_mfma_f32_16x16x32_bf16(Bt[n][k], At[m][k], acc[ai][bj][m][n], 0, 0, 0); __builtin_amdgcn_s_setprio(0); } while (0)
; #define PG8_WAIT_V(n) asm volatile("s_waitcnt vmcnt(" #n ")" ::: "memory")
; #define PG8_WAIT_L(n) asm volatile("s_waitcnt lgkmcnt(" #n ")" ::: "memory")
; #define PG8_BAR __builtin_amdgcn_s_barrier()
; #define PG8_SCHED __builtin_amdgcn_sched_barrier(0)
; template <class Epi, class Sched, bool ALIGN_EPI = false, bool SP2 = false>
; __device__ __forceinline__ void gemm_phase(PG8_LAS unsigned char* lds, const Gemm g, const Sched& S, const Epi& E) {
;     ...
;         for (int t = 0; t < nt; t += 2) {
;     ...
;             PG8_LDA(At, 1, 1); PG8_STAGE(PG8_SB(1, 0), b3, voffB); PG8_STAGE(PG8_SB(1, 1), b3 + hstepB, voffB); PG8_STAGE(PG8_SA(1, 0), a3, voffA);
;             PG8_WAIT_V(8); PG8_WAIT_L(0); PG8_BAR; PG8_MMA(1, 0, At, B0); PG8_MMA(1, 1, At, B1); PG8_BAR; PG8_SCHED;
	s_mov_b32 m0, s51
	v_lshl_add_u64 v[190:191], v[190:191], 0, s[76:77]
	s_add_u32 s8, s26, 0x40080
	ds_read_b128 v[174:177], v141 offset:49152
	ds_read_b128 v[178:181], v141 offset:50176
	ds_read_b128 v[182:185], v141 offset:51200
	ds_read_b128 v[186:189], v141 offset:52224
	ds_read_b128 v[204:207], v141 offset:53248
	ds_read_b128 v[208:211], v141 offset:54272
	ds_read_b128 v[218:221], v141 offset:55296
	ds_read_b128 v[222:225], v141 offset:56320
	global_load_lds_dwordx4 v[190:191], off
	v_lshl_add_u64 v[190:191], v[226:227], 0, s[76:77]
	s_mov_b32 m0, s60
	s_addc_u32 s9, s27, 0
	global_load_lds_dwordx4 v[190:191], off
	v_lshl_add_u64 v[190:191], s[8:9], 0, v[192:193]
	s_mov_b32 m0, s66
	s_nop 0
	global_load_lds_dwordx4 v[190:191], off
	v_lshl_add_u64 v[190:191], s[8:9], 0, v[132:133]
	s_mov_b32 m0, s67
	s_nop 0
	global_load_lds_dwordx4 v[190:191], off
	v_lshl_add_u64 v[190:191], v[228:229], 0, s[76:77]
	s_mov_b32 m0, s61
	s_nop 0
	global_load_lds_dwordx4 v[190:191], off
	v_lshl_add_u64 v[190:191], v[230:231], 0, s[76:77]
	s_mov_b32 m0, s64
	s_nop 0
	global_load_lds_dwordx4 v[190:191], off
	s_waitcnt vmcnt(8)
	s_waitcnt lgkmcnt(0)
	s_barrier
	s_waitcnt lgkmcnt(0)
	v_mfma_f32_16x16x32_bf16 v[60:63], v[142:145], v[174:177], v[60:63]
	v_mfma_f32_16x16x32_bf16 v[56:59], v[150:153], v[174:177], v[56:59]
	v_mfma_f32_16x16x32_bf16 v[52:55], v[142:145], v[182:185], v[52:55]
	v_mfma_f32_16x16x32_bf16 v[48:51], v[150:153], v[182:185], v[48:51]
	v_mfma_f32_16x16x32_bf16 v[36:39], v[142:145], v[204:207], v[36:39]
	v_mfma_f32_16x16x32_bf16 v[32:35], v[150:153], v[204:207], v[32:35]
	v_mfma_f32_16x16x32_bf16 v[20:23], v[142:145], v[218:221], v[20:23]
	v_mfma_f32_16x16x32_bf16 v[16:19], v[150:153], v[218:221], v[16:19]
	v_mfma_f32_16x16x32_bf16 v[60:63], v[146:149], v[178:181], v[60:63]
	v_mfma_f32_16x16x32_bf16 v[56:59], v[154:157], v[178:181], v[56:59]
	v_mfma_f32_16x16x32_bf16 v[52:55], v[146:149], v[186:189], v[52:55]
	v_mfma_f32_16x16x32_bf16 v[48:51], v[154:157], v[186:189], v[48:51]
	v_mfma_f32_16x16x32_bf16 v[36:39], v[146:149], v[208:211], v[36:39]
	v_mfma_f32_16x16x32_bf16 v[32:35], v[154:157], v[208:211], v[32:35]
	v_mfma_f32_16x16x32_bf16 v[20:23], v[146:149], v[222:225], v[20:23]
	v_mfma_f32_16x16x32_bf16 v[16:19], v[154:157], v[222:225], v[16:19]
	v_mfma_f32_16x16x32_bf16 v[44:47], v[158:161], v[174:177], v[44:47]
	v_mfma_f32_16x16x32_bf16 v[40:43], v[166:169], v[174:177], v[40:43]
	v_mfma_f32_16x16x32_bf16 v[28:31], v[158:161], v[182:185], v[28:31]
	v_mfma_f32_16x16x32_bf16 v[24:27], v[166:169], v[182:185], v[24:27]
	v_mfma_f32_16x16x32_bf16 v[12:15], v[158:161], v[204:207], v[12:15]
	v_mfma_f32_16x16x32_bf16 v[8:11], v[166:169], v[204:207], v[8:11]
	v_mfma_f32_16x16x32_bf16 v[4:7], v[158:161], v[218:221], v[4:7]
	v_mfma_f32_16x16x32_bf16 v[0:3], v[166:169], v[218:221], v[0:3]
	v_mfma_f32_16x16x32_bf16 v[44:47], v[162:165], v[178:181], v[44:47]
	v_mfma_f32_16x16x32_bf16 v[40:43], v[170:173], v[178:181], v[40:43]
	v_mfma_f32_16x16x32_bf16 v[28:31], v[162:165], v[186:189], v[28:31]
	v_mfma_f32_16x16x32_bf16 v[24:27], v[170:173], v[186:189], v[24:27]
	v_mfma_f32_16x16x32_bf16 v[12:15], v[162:165], v[208:211], v[12:15]
	v_mfma_f32_16x16x32_bf16 v[8:11], v[170:173], v[208:211], v[8:11]
	v_mfma_f32_16x16x32_bf16 v[4:7], v[162:165], v[222:225], v[4:7]
	v_mfma_f32_16x16x32_bf16 v[0:3], v[170:173], v[222:225], v[0:3]
	s_barrier
	s_add_i32 s75, s75, 2
	s_add_u32 s72, s72, 0x100
	s_addc_u32 s74, s74, 0
	s_add_u32 s24, s24, 0x100
	s_addc_u32 s25, s25, 0
	s_cmp_gt_u32 s75, 13
	s_cbranch_scc0 .LBB0_180
	s_and_b64 vcc, exec, s[10:11]
	s_cbranch_vccz .LBB0_183
	s_barrier

; #define PG8_STAGE(bufoff, gbase, voff) do { _Pragma("unroll") for (int _i = 0; _i < 2; ++_i) \
;         __builtin_amdgcn_global_load_lds((const unsigned*)((const char*)(gbase) + (voff)[_i]), (PG8_LAS unsigned*)(lds + (bufoff) + ldsw + _i * 8192), 16, 0, 0); } while (0)
; #define PG8_LDA(dst, b, h) do { _Pragma("unroll") for (int m = 0; m < 4; ++m) _Pragma("unroll") for (int k = 0; k < 2; ++k) dst[m][k] = *(const PG8_LAS bf16x8*)(lds + PG8_SA(b, h) + aoff + m * 2048 + k * 1024); } while (0)
; #define PG8_LDB(dst, b, h) do { _Pragma("unroll") for (int n = 0; n < 2; ++n) _Pragma("unroll") for (int k = 0; k < 2; ++k) dst[n][k] = *(const PG8_LAS bf16x8*)(lds + PG8_SB(b, h) + boff + n * 2048 + k * 1024); } while (0)
; #define PG8_MMA(ai, bj, At, Bt) do { __builtin_amdgcn_s_setprio(1); _Pragma("unroll") for (int m = 0; m < 4; ++m) _Pragma("unroll") for (int n = 0; n < 2; ++n) _Pragma("unroll") for (int k = 0; k < 2; ++k) \
;         acc[ai][bj][m][n] = __builtin_amdgcn_mfma_f32_16x16x32_bf16(Bt[n][k], At[m][k], acc[ai][bj][m][n], 0, 0, 0); __builtin_amdgcn_s_setprio(0); } while (0)
; #define PG8_WAIT_V(n) asm volatile("s_waitcnt vmcnt(" #n ")" ::: "memory")
; #define PG8_WAIT_L(n) asm volatile("s_waitcnt lgkmcnt(" #n ")" ::: "memory")
; template <class Epi, class Sched, bool ALIGN_EPI = false, bool SP2 = false>
; __device__ __forceinline__ void gemm_phase(PG8_LAS unsigned char* lds, const Gemm g, const Sched& S, const Epi& E) {
;     ...
;             const bool last = (t == nt - 2);
;             const char* a1 = cA + (size_t)(t + 1) * kstep;
;             const char* a2 = last ? nA : cA + (size_t)(t + 2) * kstep; const char* b2 = last ? nB : cB + (size_t)(t + 2) * kstep;
;             const char* a3 = a2 + kstep; const char* b3 = b2 + kstep;
;             if (last && has_next) S.a_ready(nxt);
;             if constexpr (SP2) {
;             PG8_LDB(B0, 0, 0); PG8_LDB(B1, 0, 1); PG8_SCHED; PG8_LDA(At, 0, 0); PG8_STAGE(PG8_SA(1, 1), a1 + hstepA, voffA);
;             PG8_WAIT_V(8); PG8_WAIT_L(0); PG8_BAR; PG8_MMA(0, 0, At, B0); PG8_MMA(0, 1, At, B1); PG8_BAR; PG8_SCHED;
;             PG8_LDA(At, 0, 1); PG8_STAGE(PG8_SB(0, 0), b2, voffB); PG8_STAGE(PG8_SB(0, 1), b2 + hstepB, voffB); PG8_STAGE(PG8_SA(0, 0), a2, voffA);
;             PG8_WAIT_V(8); PG8_WAIT_L(0); PG8_BAR; PG8_MMA(1, 0, At, B0); PG8_MMA(1, 1, At, B1); PG8_BAR; PG8_SCHED;
.LBB0_278:
	v_add_u32_e32 v142, s35, v145
	ds_read_b128 v[138:141], v142
	ds_read_b128 v[148:151], v142 offset:1024
	ds_read_b128 v[152:155], v142 offset:2048
	ds_read_b128 v[156:159], v142 offset:3072
	v_add_u32_e32 v142, s38, v145
	ds_read_b128 v[160:163], v142
	ds_read_b128 v[164:167], v142 offset:1024
	ds_read_b128 v[168:171], v142 offset:2048
	ds_read_b128 v[172:175], v142 offset:3072
	s_add_u32 s22, s20, 0x100
	s_addc_u32 s23, s21, 0
	s_cmp_eq_u32 s78, 40
	s_cselect_b32 s27, s9, s23
	s_cselect_b32 s26, s8, s22
	s_cselect_b32 s25, s19, s75
	s_cselect_b32 s24, s18, s74
	v_lshl_add_u64 v[142:143], s[20:21], 0, v[136:137]
	s_add_i32 m0, s41, 0xc000
	ds_read_b128 v[176:179], v147
	ds_read_b128 v[180:183], v147 offset:1024
	ds_read_b128 v[184:187], v147 offset:2048
	ds_read_b128 v[188:191], v147 offset:3072
	ds_read_b128 v[204:207], v147 offset:4096
	ds_read_b128 v[208:211], v147 offset:5120
	ds_read_b128 v[218:221], v147 offset:6144
	ds_read_b128 v[222:225], v147 offset:7168
	global_load_lds_dwordx4 v[142:143], off
	v_lshl_add_u64 v[142:143], s[20:21], 0, v[134:135]
	s_add_i32 m0, s41, 0xe000
	s_nop 0
	global_load_lds_dwordx4 v[142:143], off
	s_waitcnt vmcnt(8)
	s_waitcnt lgkmcnt(0)
	s_barrier
	s_waitcnt lgkmcnt(0)
	v_mfma_f32_16x16x32_bf16 v[124:127], v[138:141], v[176:179], v[124:127]
	v_mfma_f32_16x16x32_bf16 v[120:123], v[152:155], v[176:179], v[120:123]
	v_mfma_f32_16x16x32_bf16 v[108:111], v[138:141], v[184:187], v[108:111]
	v_mfma_f32_16x16x32_bf16 v[104:107], v[152:155], v[184:187], v[104:107]
	v_mfma_f32_16x16x32_bf16 v[92:95], v[138:141], v[204:207], v[92:95]
	v_mfma_f32_16x16x32_bf16 v[88:91], v[152:155], v[204:207], v[88:91]
	v_mfma_f32_16x16x32_bf16 v[76:79], v[138:141], v[218:221], v[76:79]
	v_mfma_f32_16x16x32_bf16 v[72:75], v[152:155], v[218:221], v[72:75]
	v_mfma_f32_16x16x32_bf16 v[124:127], v[148:151], v[180:183], v[124:127]
	v_mfma_f32_16x16x32_bf16 v[120:123], v[156:159], v[180:183], v[120:123]
	v_mfma_f32_16x16x32_bf16 v[108:111], v[148:151], v[188:191], v[108:111]
	v_mfma_f32_16x16x32_bf16 v[104:107], v[156:159], v[188:191], v[104:107]
	v_mfma_f32_16x16x32_bf16 v[92:95], v[148:151], v[208:211], v[92:95]
	v_mfma_f32_16x16x32_bf16 v[88:91], v[156:159], v[208:211], v[88:91]
	v_mfma_f32_16x16x32_bf16 v[76:79], v[148:151], v[222:225], v[76:79]
	v_mfma_f32_16x16x32_bf16 v[72:75], v[156:159], v[222:225], v[72:75]
	v_mfma_f32_16x16x32_bf16 v[116:119], v[160:163], v[176:179], v[116:119]
	v_mfma_f32_16x16x32_bf16 v[112:115], v[168:171], v[176:179], v[112:115]
	v_mfma_f32_16x16x32_bf16 v[100:103], v[160:163], v[184:187], v[100:103]
	v_mfma_f32_16x16x32_bf16 v[96:99], v[168:171], v[184:187], v[96:99]
	v_mfma_f32_16x16x32_bf16 v[84:87], v[160:163], v[204:207], v[84:87]
	v_mfma_f32_16x16x32_bf16 v[80:83], v[168:171], v[204:207], v[80:83]
	v_mfma_f32_16x16x32_bf16 v[68:71], v[160:163], v[218:221], v[68:71]
	v_mfma_f32_16x16x32_bf16 v[64:67], v[168:171], v[218:221], v[64:67]
	v_mfma_f32_16x16x32_bf16 v[116:119], v[164:167], v[180:183], v[116:119]
	v_mfma_f32_16x16x32_bf16 v[112:115], v[172:175], v[180:183], v[112:115]
	v_mfma_f32_16x16x32_bf16 v[100:103], v[164:167], v[188:191], v[100:103]
	v_mfma_f32_16x16x32_bf16 v[96:99], v[172:175], v[188:191], v[96:99]
	v_mfma_f32_16x16x32_bf16 v[84:87], v[164:167], v[208:211], v[84:87]
	v_mfma_f32_16x16x32_bf16 v[80:83], v[172:175], v[208:211], v[80:83]
	v_mfma_f32_16x16x32_bf16 v[68:71], v[164:167], v[222:225], v[68:71]
	v_mfma_f32_16x16x32_bf16 v[64:67], v[172:175], v[222:225], v[64:67]
	s_barrier
	s_mov_b32 m0, s36
	v_lshl_add_u64 v[142:143], s[24:25], 0, v[192:193]
	s_add_u32 s20, s24, 0xb0000
	ds_read_b128 v[176:179], v147 offset:16384
	ds_read_b128 v[180:183], v147 offset:17408
	ds_read_b128 v[184:187], v147 offset:18432
	ds_read_b128 v[188:191], v147 offset:19456
	ds_read_b128 v[204:207], v147 offset:20480
	ds_read_b128 v[208:211], v147 offset:21504
	ds_read_b128 v[218:221], v147 offset:22528
	ds_read_b128 v[222:225], v147 offset:23552
	global_load_lds_dwordx4 v[142:143], off
	v_lshl_add_u64 v[226:227], s[24:25], 0, v[132:133]
	s_mov_b32 m0, s37
	s_addc_u32 s21, s25, 0
	global_load_lds_dwordx4 v[226:227], off
	v_lshl_add_u64 v[228:229], s[20:21], 0, v[192:193]
	s_mov_b32 m0, s39
	v_lshl_add_u64 v[230:231], s[26:27], 0, v[130:131]
	global_load_lds_dwordx4 v[228:229], off
	v_lshl_add_u64 v[228:229], s[20:21], 0, v[132:133]
	s_mov_b32 m0, s40
	s_nop 0
	global_load_lds_dwordx4 v[228:229], off
	v_lshl_add_u64 v[228:229], s[26:27], 0, v[128:129]
	s_mov_b32 m0, s41
	s_nop 0
	global_load_lds_dwordx4 v[228:229], off
	s_mov_b32 m0, s42
	s_nop 0
	global_load_lds_dwordx4 v[230:231], off
	s_waitcnt vmcnt(8)
	s_waitcnt lgkmcnt(0)
	s_barrier
; #define PG8_STAGE(bufoff, gbase, voff) do { _Pragma("unroll") for (int _i = 0; _i < 2; ++_i) \
;         __builtin_amdgcn_global_load_lds((const unsigned*)((const char*)(gbase) + (voff)[_i]), (PG8_LAS unsigned*)(lds + (bufoff) + ldsw + _i * 8192), 16, 0, 0); } while (0)
; #define PG8_LDA(dst, b, h) do { _Pragma("unroll") for (int m = 0; m < 4; ++m) _Pragma("unroll") for (int k = 0; k < 2; ++k) dst[m][k] = *(const PG8_LAS bf16x8*)(lds + PG8_SA(b, h) + aoff + m * 2048 + k * 1024); } while (0)
; #define PG8_LDB(dst, b, h) do { _Pragma("unroll") for (int n = 0; n < 2; ++n) _Pragma("unroll") for (int k = 0; k < 2; ++k) dst[n][k] = *(const PG8_LAS bf16x8*)(lds + PG8_SB(b, h) + boff + n * 2048 + k * 1024); } while (0)
; #define PG8_MMA(ai, bj, At, Bt) do { __builtin_amdgcn_s_setprio(1); _Pragma("unroll") for (int m = 0; m < 4; ++m) _Pragma("unroll") for (int n = 0; n < 2; ++n) _Pragma("unroll") for (int k = 0; k < 2; ++k) \
;         acc[ai][bj][m][n] = __builtin_amdgcn_mfma_f32_16x16x32_bf16(Bt[n][k], At[m][k], acc[ai][bj][m][n], 0, 0, 0); __builtin_amdgcn_s_setprio(0); } while (0)
; #define PG8_WAIT_V(n) asm volatile("s_waitcnt vmcnt(" #n ")" ::: "memory")
; #define PG8_WAIT_L(n) asm volatile("s_waitcnt lgkmcnt(" #n ")" ::: "memory")
; #define PG8_BAR __builtin_amdgcn_s_barrier()
; #define PG8_SCHED __builtin_amdgcn_sched_barrier(0)
; template <class Epi, class Sched, bool ALIGN_EPI = false, bool SP2 = false>
; __device__ __forceinline__ void gemm_phase(PG8_LAS unsigned char* lds, const Gemm g, const Sched& S, const Epi& E) {
;     ...
;             PG8_WAIT_V(8); PG8_WAIT_L(0); PG8_BAR; PG8_MMA(1, 0, At, B0); PG8_MMA(1, 1, At, B1); PG8_BAR; PG8_SCHED;
;             PG8_LDB(B0, 1, 0); PG8_LDB(B1, 1, 1); PG8_SCHED; PG8_LDA(At, 1, 0); PG8_STAGE(PG8_SA(0, 1), a2 + hstepA, voffA);
;             PG8_WAIT_V(8); PG8_WAIT_L(0); PG8_BAR; PG8_MMA(0, 0, At, B0); PG8_MMA(0, 1, At, B1); PG8_BAR; PG8_SCHED;
	s_waitcnt lgkmcnt(0)
	v_mfma_f32_16x16x32_bf16 v[60:63], v[138:141], v[176:179], v[60:63]
	v_mfma_f32_16x16x32_bf16 v[56:59], v[152:155], v[176:179], v[56:59]
	v_mfma_f32_16x16x32_bf16 v[44:47], v[138:141], v[184:187], v[44:47]
	v_mfma_f32_16x16x32_bf16 v[40:43], v[152:155], v[184:187], v[40:43]
	v_mfma_f32_16x16x32_bf16 v[28:31], v[138:141], v[204:207], v[28:31]
	v_mfma_f32_16x16x32_bf16 v[24:27], v[152:155], v[204:207], v[24:27]
	v_mfma_f32_16x16x32_bf16 v[12:15], v[138:141], v[218:221], v[12:15]
	v_mfma_f32_16x16x32_bf16 v[8:11], v[152:155], v[218:221], v[8:11]
	v_mfma_f32_16x16x32_bf16 v[60:63], v[148:151], v[180:183], v[60:63]
	v_mfma_f32_16x16x32_bf16 v[56:59], v[156:159], v[180:183], v[56:59]
	v_mfma_f32_16x16x32_bf16 v[44:47], v[148:151], v[188:191], v[44:47]
	v_mfma_f32_16x16x32_bf16 v[40:43], v[156:159], v[188:191], v[40:43]
	v_mfma_f32_16x16x32_bf16 v[28:31], v[148:151], v[208:211], v[28:31]
	v_mfma_f32_16x16x32_bf16 v[24:27], v[156:159], v[208:211], v[24:27]
	v_mfma_f32_16x16x32_bf16 v[12:15], v[148:151], v[222:225], v[12:15]
	v_mfma_f32_16x16x32_bf16 v[8:11], v[156:159], v[222:225], v[8:11]
	v_mfma_f32_16x16x32_bf16 v[52:55], v[160:163], v[176:179], v[52:55]
	v_mfma_f32_16x16x32_bf16 v[48:51], v[168:171], v[176:179], v[48:51]
	v_mfma_f32_16x16x32_bf16 v[36:39], v[160:163], v[184:187], v[36:39]
	v_mfma_f32_16x16x32_bf16 v[32:35], v[168:171], v[184:187], v[32:35]
	v_mfma_f32_16x16x32_bf16 v[20:23], v[160:163], v[204:207], v[20:23]
	v_mfma_f32_16x16x32_bf16 v[16:19], v[168:171], v[204:207], v[16:19]
	v_mfma_f32_16x16x32_bf16 v[4:7], v[160:163], v[218:221], v[4:7]
	v_mfma_f32_16x16x32_bf16 v[0:3], v[168:171], v[218:221], v[0:3]
	v_mfma_f32_16x16x32_bf16 v[52:55], v[164:167], v[180:183], v[52:55]
	v_mfma_f32_16x16x32_bf16 v[48:51], v[172:175], v[180:183], v[48:51]
	v_mfma_f32_16x16x32_bf16 v[36:39], v[164:167], v[188:191], v[36:39]
	v_mfma_f32_16x16x32_bf16 v[32:35], v[172:175], v[188:191], v[32:35]
	v_mfma_f32_16x16x32_bf16 v[20:23], v[164:167], v[208:211], v[20:23]
	v_mfma_f32_16x16x32_bf16 v[16:19], v[172:175], v[208:211], v[16:19]
	v_mfma_f32_16x16x32_bf16 v[4:7], v[164:167], v[222:225], v[4:7]
	v_mfma_f32_16x16x32_bf16 v[0:3], v[172:175], v[222:225], v[0:3]
	s_barrier
	v_add_u32_e32 v156, s48, v145
	v_add_u32_e32 v172, s61, v145
	ds_read_b128 v[138:141], v156
	ds_read_b128 v[148:151], v156 offset:1024
	ds_read_b128 v[152:155], v156 offset:2048
	ds_read_b128 v[156:159], v156 offset:3072
	ds_read_b128 v[160:163], v172
	ds_read_b128 v[164:167], v172 offset:1024
	ds_read_b128 v[168:171], v172 offset:2048
	ds_read_b128 v[172:175], v172 offset:3072
	s_add_u32 s20, s26, 0xb0000
	s_addc_u32 s21, s27, 0
	s_mov_b32 m0, s43
	v_lshl_add_u64 v[232:233], s[20:21], 0, v[128:129]
	ds_read_b128 v[176:179], v147 offset:32768
	ds_read_b128 v[180:183], v147 offset:33792
	ds_read_b128 v[184:187], v147 offset:34816
	ds_read_b128 v[188:191], v147 offset:35840
	ds_read_b128 v[204:207], v147 offset:36864
	ds_read_b128 v[208:211], v147 offset:37888
	ds_read_b128 v[218:221], v147 offset:38912
	ds_read_b128 v[222:225], v147 offset:39936
	global_load_lds_dwordx4 v[232:233], off
	v_lshl_add_u64 v[232:233], s[20:21], 0, v[130:131]
	s_mov_b32 m0, s44
	s_nop 0
	global_load_lds_dwordx4 v[232:233], off
	s_waitcnt vmcnt(8)
	s_waitcnt lgkmcnt(0)
	s_barrier
	s_waitcnt lgkmcnt(0)
	v_mfma_f32_16x16x32_bf16 v[124:127], v[138:141], v[176:179], v[124:127]
	v_mfma_f32_16x16x32_bf16 v[120:123], v[152:155], v[176:179], v[120:123]
	v_mfma_f32_16x16x32_bf16 v[108:111], v[138:141], v[184:187], v[108:111]
	v_mfma_f32_16x16x32_bf16 v[104:107], v[152:155], v[184:187], v[104:107]
	v_mfma_f32_16x16x32_bf16 v[92:95], v[138:141], v[204:207], v[92:95]
	v_mfma_f32_16x16x32_bf16 v[88:91], v[152:155], v[204:207], v[88:91]
	v_mfma_f32_16x16x32_bf16 v[76:79], v[138:141], v[218:221], v[76:79]
	v_mfma_f32_16x16x32_bf16 v[72:75], v[152:155], v[218:221], v[72:75]
	v_mfma_f32_16x16x32_bf16 v[124:127], v[148:151], v[180:183], v[124:127]
	v_mfma_f32_16x16x32_bf16 v[120:123], v[156:159], v[180:183], v[120:123]
	v_mfma_f32_16x16x32_bf16 v[108:111], v[148:151], v[188:191], v[108:111]
	v_mfma_f32_16x16x32_bf16 v[104:107], v[156:159], v[188:191], v[104:107]
	v_mfma_f32_16x16x32_bf16 v[92:95], v[148:151], v[208:211], v[92:95]
	v_mfma_f32_16x16x32_bf16 v[88:91], v[156:159], v[208:211], v[88:91]
	v_mfma_f32_16x16x32_bf16 v[76:79], v[148:151], v[222:225], v[76:79]
	v_mfma_f32_16x16x32_bf16 v[72:75], v[156:159], v[222:225], v[72:75]
	v_mfma_f32_16x16x32_bf16 v[116:119], v[160:163], v[176:179], v[116:119]
	v_mfma_f32_16x16x32_bf16 v[112:115], v[168:171], v[176:179], v[112:115]
	v_mfma_f32_16x16x32_bf16 v[100:103], v[160:163], v[184:187], v[100:103]
	v_mfma_f32_16x16x32_bf16 v[96:99], v[168:171], v[184:187], v[96:99]
	v_mfma_f32_16x16x32_bf16 v[84:87], v[160:163], v[204:207], v[84:87]
	v_mfma_f32_16x16x32_bf16 v[80:83], v[168:171], v[204:207], v[80:83]
	v_mfma_f32_16x16x32_bf16 v[68:71], v[160:163], v[218:221], v[68:71]
	v_mfma_f32_16x16x32_bf16 v[64:67], v[168:171], v[218:221], v[64:67]
	v_mfma_f32_16x16x32_bf16 v[116:119], v[164:167], v[180:183], v[116:119]
	v_mfma_f32_16x16x32_bf16 v[112:115], v[172:175], v[180:183], v[112:115]
	v_mfma_f32_16x16x32_bf16 v[100:103], v[164:167], v[188:191], v[100:103]
	v_mfma_f32_16x16x32_bf16 v[96:99], v[172:175], v[188:191], v[96:99]
	v_mfma_f32_16x16x32_bf16 v[84:87], v[164:167], v[208:211], v[84:87]
	v_mfma_f32_16x16x32_bf16 v[80:83], v[172:175], v[208:211], v[80:83]
	v_mfma_f32_16x16x32_bf16 v[68:71], v[164:167], v[222:225], v[68:71]
	v_mfma_f32_16x16x32_bf16 v[64:67], v[172:175], v[222:225], v[64:67]
	s_barrier
; #define PG8_STAGE(bufoff, gbase, voff) do { _Pragma("unroll") for (int _i = 0; _i < 2; ++_i) \
;         __builtin_amdgcn_global_load_lds((const unsigned*)((const char*)(gbase) + (voff)[_i]), (PG8_LAS unsigned*)(lds + (bufoff) + ldsw + _i * 8192), 16, 0, 0); } while (0)
; #define PG8_LDA(dst, b, h) do { _Pragma("unroll") for (int m = 0; m < 4; ++m) _Pragma("unroll") for (int k = 0; k < 2; ++k) dst[m][k] = *(const PG8_LAS bf16x8*)(lds + PG8_SA(b, h) + aoff + m * 2048 + k * 1024); } while (0)
; #define PG8_MMA(ai, bj, At, Bt) do { __builtin_amdgcn_s_setprio(1); _Pragma("unroll") for (int m = 0; m < 4; ++m) _Pragma("unroll") for (int n = 0; n < 2; ++n) _Pragma("unroll") for (int k = 0; k < 2; ++k) \
;         acc[ai][bj][m][n] = __builtin_amdgcn_mfma_f32_16x16x32_bf16(Bt[n][k], At[m][k], acc[ai][bj][m][n], 0, 0, 0); __builtin_amdgcn_s_setprio(0); } while (0)
; #define PG8_WAIT_V(n) asm volatile("s_waitcnt vmcnt(" #n ")" ::: "memory")
; #define PG8_WAIT_L(n) asm volatile("s_waitcnt lgkmcnt(" #n ")" ::: "memory")
; #define PG8_BAR __builtin_amdgcn_s_barrier()
; #define PG8_SCHED __builtin_amdgcn_sched_barrier(0)
; template <class Epi, class Sched, bool ALIGN_EPI = false, bool SP2 = false>
; __device__ __forceinline__ void gemm_phase(PG8_LAS unsigned char* lds, const Gemm g, const Sched& S, const Epi& E) {
;     ...
;             PG8_LDA(At, 1, 1); PG8_STAGE(PG8_SB(1, 0), b3, voffB); PG8_STAGE(PG8_SB(1, 1), b3 + hstepB, voffB); PG8_STAGE(PG8_SA(1, 0), a3, voffA);
;             PG8_WAIT_V(8); PG8_WAIT_L(0); PG8_BAR; PG8_MMA(1, 0, At, B0); PG8_MMA(1, 1, At, B1); PG8_BAR; PG8_SCHED;
;     __device__ __forceinline__ void operator()(const f32x4 (&acc)[2][2][4][2], const pg8::Unit& u, int wr, int wc, int fr, int fq) const {
;         const int row0 = u.pm * 256 + wr * 64 + fr, col0 = u.pn * 256 + wc * 32 + 8 * fq;
; #pragma unroll
;         for (int ai = 0; ai < 2; ++ai)
; #pragma unroll
;             for (int m = 0; m < 4; ++m) {
;                 const int row = row0 + ai * 128 + m * 16; float ss = 0.f;
; #pragma unroll
;                 for (int bj = 0; bj < 2; ++bj) {
;                     const size_t off = (size_t)row * DM + col0 + bj * 128;
;                     const v4u b = *(const v4u*)(xb + off);
	s_mov_b32 m0, s49
	v_lshl_add_u64 v[142:143], v[142:143], 0, s[76:77]
	s_add_u32 s20, s24, 0xb0080
	ds_read_b128 v[176:179], v147 offset:49152
	ds_read_b128 v[180:183], v147 offset:50176
	ds_read_b128 v[184:187], v147 offset:51200
	ds_read_b128 v[188:191], v147 offset:52224
	ds_read_b128 v[204:207], v147 offset:53248
	ds_read_b128 v[208:211], v147 offset:54272
	ds_read_b128 v[218:221], v147 offset:55296
	ds_read_b128 v[222:225], v147 offset:56320
	global_load_lds_dwordx4 v[142:143], off
	v_lshl_add_u64 v[142:143], v[226:227], 0, s[76:77]
	s_mov_b32 m0, s50
	s_addc_u32 s21, s25, 0
	global_load_lds_dwordx4 v[142:143], off
	v_lshl_add_u64 v[142:143], s[20:21], 0, v[192:193]
	s_mov_b32 m0, s64
	s_nop 0
	global_load_lds_dwordx4 v[142:143], off
	v_lshl_add_u64 v[142:143], s[20:21], 0, v[132:133]
	s_mov_b32 m0, s65
	s_nop 0
	global_load_lds_dwordx4 v[142:143], off
	v_lshl_add_u64 v[142:143], v[228:229], 0, s[76:77]
	s_mov_b32 m0, s51
	s_nop 0
	global_load_lds_dwordx4 v[142:143], off
	v_lshl_add_u64 v[142:143], v[230:231], 0, s[76:77]
	s_mov_b32 m0, s60
	s_nop 0
	global_load_lds_dwordx4 v[142:143], off
	s_waitcnt vmcnt(8)
	s_waitcnt lgkmcnt(0)
	s_barrier
	s_waitcnt lgkmcnt(0)
	v_mfma_f32_16x16x32_bf16 v[60:63], v[138:141], v[176:179], v[60:63]
	v_mfma_f32_16x16x32_bf16 v[56:59], v[152:155], v[176:179], v[56:59]
	v_mfma_f32_16x16x32_bf16 v[44:47], v[138:141], v[184:187], v[44:47]
	v_mfma_f32_16x16x32_bf16 v[40:43], v[152:155], v[184:187], v[40:43]
	v_mfma_f32_16x16x32_bf16 v[28:31], v[138:141], v[204:207], v[28:31]
	v_mfma_f32_16x16x32_bf16 v[24:27], v[152:155], v[204:207], v[24:27]
	v_mfma_f32_16x16x32_bf16 v[12:15], v[138:141], v[218:221], v[12:15]
	v_mfma_f32_16x16x32_bf16 v[8:11], v[152:155], v[218:221], v[8:11]
	v_mfma_f32_16x16x32_bf16 v[60:63], v[148:151], v[180:183], v[60:63]
	v_mfma_f32_16x16x32_bf16 v[56:59], v[156:159], v[180:183], v[56:59]
	v_mfma_f32_16x16x32_bf16 v[44:47], v[148:151], v[188:191], v[44:47]
	v_mfma_f32_16x16x32_bf16 v[40:43], v[156:159], v[188:191], v[40:43]
	v_mfma_f32_16x16x32_bf16 v[28:31], v[148:151], v[208:211], v[28:31]
	v_mfma_f32_16x16x32_bf16 v[24:27], v[156:159], v[208:211], v[24:27]
	v_mfma_f32_16x16x32_bf16 v[12:15], v[148:151], v[222:225], v[12:15]
	v_mfma_f32_16x16x32_bf16 v[8:11], v[156:159], v[222:225], v[8:11]
	v_mfma_f32_16x16x32_bf16 v[52:55], v[160:163], v[176:179], v[52:55]
	v_mfma_f32_16x16x32_bf16 v[48:51], v[168:171], v[176:179], v[48:51]
	v_mfma_f32_16x16x32_bf16 v[36:39], v[160:163], v[184:187], v[36:39]
	v_mfma_f32_16x16x32_bf16 v[32:35], v[168:171], v[184:187], v[32:35]
	v_mfma_f32_16x16x32_bf16 v[20:23], v[160:163], v[204:207], v[20:23]
	v_mfma_f32_16x16x32_bf16 v[16:19], v[168:171], v[204:207], v[16:19]
	v_mfma_f32_16x16x32_bf16 v[4:7], v[160:163], v[218:221], v[4:7]
	v_mfma_f32_16x16x32_bf16 v[0:3], v[168:171], v[218:221], v[0:3]
	v_mfma_f32_16x16x32_bf16 v[52:55], v[164:167], v[180:183], v[52:55]
	v_mfma_f32_16x16x32_bf16 v[48:51], v[172:175], v[180:183], v[48:51]
	v_mfma_f32_16x16x32_bf16 v[36:39], v[164:167], v[188:191], v[36:39]
	v_mfma_f32_16x16x32_bf16 v[32:35], v[172:175], v[188:191], v[32:35]
	v_mfma_f32_16x16x32_bf16 v[20:23], v[164:167], v[208:211], v[20:23]
	v_mfma_f32_16x16x32_bf16 v[16:19], v[172:175], v[208:211], v[16:19]
	v_mfma_f32_16x16x32_bf16 v[4:7], v[164:167], v[222:225], v[4:7]
	v_mfma_f32_16x16x32_bf16 v[0:3], v[172:175], v[222:225], v[0:3]
	s_barrier
	s_add_i32 s78, s78, 2
	s_add_u32 s74, s74, 0x100
	s_addc_u32 s75, s75, 0
	s_cmp_gt_u32 s78, 41
	s_mov_b64 s[20:21], s[22:23]
	s_cbranch_scc0 .LBB0_278
	v_lshl_add_u32 v159, s68, 8, v144
	v_lshl_or_b32 v158, s34, 8, v146
	v_lshlrev_b32_e32 v159, 11, v159
	v_lshl_add_u32 v159, v158, 1, v159
	v_add_u32_e32 v218, 0x8000, v159
	v_add_u32_e32 v219, 0x10000, v159
	v_add_u32_e32 v240, 0x18000, v159
	v_add_u32_e32 v241, 0x40000, v159
	v_add_u32_e32 v245, 0x48000, v159
	v_add_u32_e32 v246, 0x50000, v159
	v_add_u32_e32 v247, 0x58000, v159
	global_load_dwordx4 v[160:163], v159, s[12:13]
	global_load_dwordx4 v[164:167], v159, s[12:13] offset:256
	global_load_dwordx4 v[168:171], v218, s[12:13]
	global_load_dwordx4 v[172:175], v218, s[12:13] offset:256
	global_load_dwordx4 v[176:179], v219, s[12:13]
	global_load_dwordx4 v[180:183], v219, s[12:13] offset:256
	global_load_dwordx4 v[184:187], v240, s[12:13]
	global_load_dwordx4 v[188:191], v240, s[12:13] offset:256
	global_load_dwordx4 v[204:207], v241, s[12:13]
	global_load_dwordx4 v[208:211], v241, s[12:13] offset:256
	global_load_dwordx4 v[220:223], v245, s[12:13]
	global_load_dwordx4 v[224:227], v245, s[12:13] offset:256
	global_load_dwordx4 v[228:231], v246, s[12:13]
	global_load_dwordx4 v[232:235], v246, s[12:13] offset:256
	global_load_dwordx4 v[236:239], v247, s[12:13]
	global_load_dwordx4 v[248:251], v247, s[12:13] offset:256
	s_and_b64 vcc, exec, s[16:17]
	s_cbranch_vccz .LBB0_281
	s_barrier

; #define PG8_STAGE(bufoff, gbase, voff) do { _Pragma("unroll") for (int _i = 0; _i < 2; ++_i) \
;         __builtin_amdgcn_global_load_lds((const unsigned*)((const char*)(gbase) + (voff)[_i]), (PG8_LAS unsigned*)(lds + (bufoff) + ldsw + _i * 8192), 16, 0, 0); } while (0)
; #define PG8_LDA(dst, b, h) do { _Pragma("unroll") for (int m = 0; m < 4; ++m) _Pragma("unroll") for (int k = 0; k < 2; ++k) dst[m][k] = *(const PG8_LAS bf16x8*)(lds + PG8_SA(b, h) + aoff + m * 2048 + k * 1024); } while (0)
; #define PG8_LDB(dst, b, h) do { _Pragma("unroll") for (int n = 0; n < 2; ++n) _Pragma("unroll") for (int k = 0; k < 2; ++k) dst[n][k] = *(const PG8_LAS bf16x8*)(lds + PG8_SB(b, h) + boff + n * 2048 + k * 1024); } while (0)
; #define PG8_MMA(ai, bj, At, Bt) do { __builtin_amdgcn_s_setprio(1); _Pragma("unroll") for (int m = 0; m < 4; ++m) _Pragma("unroll") for (int n = 0; n < 2; ++n) _Pragma("unroll") for (int k = 0; k < 2; ++k) \
;         acc[ai][bj][m][n] = __builtin_amdgcn_mfma_f32_16x16x32_bf16(Bt[n][k], At[m][k], acc[ai][bj][m][n], 0, 0, 0); __builtin_amdgcn_s_setprio(0); } while (0)
; #define PG8_WAIT_V(n) asm volatile("s_waitcnt vmcnt(" #n ")" ::: "memory")
; #define PG8_WAIT_L(n) asm volatile("s_waitcnt lgkmcnt(" #n ")" ::: "memory")
; template <class Epi, class Sched, bool ALIGN_EPI = false, bool SP2 = false>
; __device__ __forceinline__ void gemm_phase(PG8_LAS unsigned char* lds, const Gemm g, const Sched& S, const Epi& E) {
;     ...
;             const bool last = (t == nt - 2);
;             const char* a1 = cA + (size_t)(t + 1) * kstep;
;             const char* a2 = last ? nA : cA + (size_t)(t + 2) * kstep; const char* b2 = last ? nB : cB + (size_t)(t + 2) * kstep;
;             const char* a3 = a2 + kstep; const char* b3 = b2 + kstep;
;             if (last && has_next) S.a_ready(nxt);
;             if constexpr (SP2) {
;             PG8_LDB(B0, 0, 0); PG8_LDB(B1, 0, 1); PG8_SCHED; PG8_LDA(At, 0, 0); PG8_STAGE(PG8_SA(1, 1), a1 + hstepA, voffA);
;             PG8_WAIT_V(8); PG8_WAIT_L(0); PG8_BAR; PG8_MMA(0, 0, At, B0); PG8_MMA(0, 1, At, B1); PG8_BAR; PG8_SCHED;
;             PG8_LDA(At, 0, 1); PG8_STAGE(PG8_SB(0, 0), b2, voffB); PG8_STAGE(PG8_SB(0, 1), b2 + hstepB, voffB); PG8_STAGE(PG8_SA(0, 0), a2, voffA);
;             PG8_WAIT_V(8); PG8_WAIT_L(0); PG8_BAR; PG8_MMA(1, 0, At, B0); PG8_MMA(1, 1, At, B1); PG8_BAR; PG8_SCHED;
.LBB0_380:
	v_add_u32_e32 v140, s85, v173
	v_add_u32_e32 v170, s78, v173
	ds_read_b128 v[128:131], v140
	ds_read_b128 v[132:135], v140 offset:1024
	ds_read_b128 v[136:139], v140 offset:2048
	ds_read_b128 v[140:143], v140 offset:3072
	ds_read_b128 v[144:147], v170
	ds_read_b128 v[148:151], v170 offset:1024
	ds_read_b128 v[166:169], v170 offset:2048
	ds_read_b128 v[176:179], v170 offset:3072
	s_add_u32 s2, s12, 0xfffc0080
	s_addc_u32 s14, s13, -1
	s_cmp_eq_u32 s22, 12
	s_cselect_b32 s17, s9, s14
	s_cselect_b32 s16, s11, s2
	s_cselect_b32 s15, s18, s21
	s_cselect_b32 s14, s19, s20
	v_lshl_add_u64 v[170:171], s[12:13], 0, v[164:165]
	s_add_i32 m0, s61, 0xc000
	ds_read_b128 v[180:183], v175
	ds_read_b128 v[184:187], v175 offset:1024
	ds_read_b128 v[188:191], v175 offset:2048
	ds_read_b128 v[204:207], v175 offset:3072
	ds_read_b128 v[208:211], v175 offset:4096
	ds_read_b128 v[218:221], v175 offset:5120
	ds_read_b128 v[222:225], v175 offset:6144
	ds_read_b128 v[226:229], v175 offset:7168
	global_load_lds_dwordx4 v[170:171], off
	v_lshl_add_u64 v[170:171], s[12:13], 0, v[162:163]
	s_add_i32 m0, s61, 0xe000
	s_nop 0
	global_load_lds_dwordx4 v[170:171], off
	s_waitcnt vmcnt(8)
	s_waitcnt lgkmcnt(0)
	s_barrier
	s_waitcnt lgkmcnt(0)
	v_mfma_f32_16x16x32_bf16 v[60:63], v[128:131], v[180:183], v[60:63]
	v_mfma_f32_16x16x32_bf16 v[56:59], v[136:139], v[180:183], v[56:59]
	v_mfma_f32_16x16x32_bf16 v[52:55], v[128:131], v[188:191], v[52:55]
	v_mfma_f32_16x16x32_bf16 v[48:51], v[136:139], v[188:191], v[48:51]
	v_mfma_f32_16x16x32_bf16 v[44:47], v[128:131], v[208:211], v[44:47]
	v_mfma_f32_16x16x32_bf16 v[40:43], v[136:139], v[208:211], v[40:43]
	v_mfma_f32_16x16x32_bf16 v[36:39], v[128:131], v[222:225], v[36:39]
	v_mfma_f32_16x16x32_bf16 v[32:35], v[136:139], v[222:225], v[32:35]
	v_mfma_f32_16x16x32_bf16 v[60:63], v[132:135], v[184:187], v[60:63]
	v_mfma_f32_16x16x32_bf16 v[56:59], v[140:143], v[184:187], v[56:59]
	v_mfma_f32_16x16x32_bf16 v[52:55], v[132:135], v[204:207], v[52:55]
	v_mfma_f32_16x16x32_bf16 v[48:51], v[140:143], v[204:207], v[48:51]
	v_mfma_f32_16x16x32_bf16 v[44:47], v[132:135], v[218:221], v[44:47]
	v_mfma_f32_16x16x32_bf16 v[40:43], v[140:143], v[218:221], v[40:43]
	v_mfma_f32_16x16x32_bf16 v[36:39], v[132:135], v[226:229], v[36:39]
	v_mfma_f32_16x16x32_bf16 v[32:35], v[140:143], v[226:229], v[32:35]
	v_mfma_f32_16x16x32_bf16 v[124:127], v[144:147], v[180:183], v[124:127]
	v_mfma_f32_16x16x32_bf16 v[120:123], v[166:169], v[180:183], v[120:123]
	v_mfma_f32_16x16x32_bf16 v[116:119], v[144:147], v[188:191], v[116:119]
	v_mfma_f32_16x16x32_bf16 v[112:115], v[166:169], v[188:191], v[112:115]
	v_mfma_f32_16x16x32_bf16 v[108:111], v[144:147], v[208:211], v[108:111]
	v_mfma_f32_16x16x32_bf16 v[104:107], v[166:169], v[208:211], v[104:107]
	v_mfma_f32_16x16x32_bf16 v[100:103], v[144:147], v[222:225], v[100:103]
	v_mfma_f32_16x16x32_bf16 v[96:99], v[166:169], v[222:225], v[96:99]
	v_mfma_f32_16x16x32_bf16 v[124:127], v[148:151], v[184:187], v[124:127]
	v_mfma_f32_16x16x32_bf16 v[120:123], v[176:179], v[184:187], v[120:123]
	v_mfma_f32_16x16x32_bf16 v[116:119], v[148:151], v[204:207], v[116:119]
	v_mfma_f32_16x16x32_bf16 v[112:115], v[176:179], v[204:207], v[112:115]
	v_mfma_f32_16x16x32_bf16 v[108:111], v[148:151], v[218:221], v[108:111]
	v_mfma_f32_16x16x32_bf16 v[104:107], v[176:179], v[218:221], v[104:107]
	v_mfma_f32_16x16x32_bf16 v[100:103], v[148:151], v[226:229], v[100:103]
	v_mfma_f32_16x16x32_bf16 v[96:99], v[176:179], v[226:229], v[96:99]
	s_barrier
	s_mov_b32 m0, s70
	v_lshl_add_u64 v[170:171], s[14:15], 0, v[154:155]
	s_add_u32 s24, s14, 0x40000
	ds_read_b128 v[180:183], v175 offset:16384
	ds_read_b128 v[184:187], v175 offset:17408
	ds_read_b128 v[188:191], v175 offset:18432
	ds_read_b128 v[204:207], v175 offset:19456
	ds_read_b128 v[208:211], v175 offset:20480
	ds_read_b128 v[218:221], v175 offset:21504
	ds_read_b128 v[222:225], v175 offset:22528
	ds_read_b128 v[226:229], v175 offset:23552
	global_load_lds_dwordx4 v[170:171], off
	v_lshl_add_u64 v[230:231], s[14:15], 0, v[158:159]
	s_mov_b32 m0, s71
	s_addc_u32 s25, s15, 0
	global_load_lds_dwordx4 v[230:231], off
	v_lshl_add_u64 v[232:233], s[24:25], 0, v[154:155]
	s_mov_b32 m0, s79
	v_lshl_add_u64 v[234:235], s[16:17], 0, v[156:157]
	global_load_lds_dwordx4 v[232:233], off
	v_lshl_add_u64 v[232:233], s[24:25], 0, v[158:159]
	s_mov_b32 m0, s60
	s_nop 0
	global_load_lds_dwordx4 v[232:233], off
	v_lshl_add_u64 v[232:233], s[16:17], 0, v[152:153]
	s_mov_b32 m0, s61
	s_nop 0
	global_load_lds_dwordx4 v[232:233], off
	s_mov_b32 m0, s75
	s_nop 0
	global_load_lds_dwordx4 v[234:235], off
	s_waitcnt vmcnt(8)
	s_waitcnt lgkmcnt(0)
	s_barrier
; #define PG8_STAGE(bufoff, gbase, voff) do { _Pragma("unroll") for (int _i = 0; _i < 2; ++_i) \
;         __builtin_amdgcn_global_load_lds((const unsigned*)((const char*)(gbase) + (voff)[_i]), (PG8_LAS unsigned*)(lds + (bufoff) + ldsw + _i * 8192), 16, 0, 0); } while (0)
; #define PG8_LDA(dst, b, h) do { _Pragma("unroll") for (int m = 0; m < 4; ++m) _Pragma("unroll") for (int k = 0; k < 2; ++k) dst[m][k] = *(const PG8_LAS bf16x8*)(lds + PG8_SA(b, h) + aoff + m * 2048 + k * 1024); } while (0)
; #define PG8_LDB(dst, b, h) do { _Pragma("unroll") for (int n = 0; n < 2; ++n) _Pragma("unroll") for (int k = 0; k < 2; ++k) dst[n][k] = *(const PG8_LAS bf16x8*)(lds + PG8_SB(b, h) + boff + n * 2048 + k * 1024); } while (0)
; #define PG8_MMA(ai, bj, At, Bt) do { __builtin_amdgcn_s_setprio(1); _Pragma("unroll") for (int m = 0; m < 4; ++m) _Pragma("unroll") for (int n = 0; n < 2; ++n) _Pragma("unroll") for (int k = 0; k < 2; ++k) \
;         acc[ai][bj][m][n] = __builtin_amdgcn_mfma_f32_16x16x32_bf16(Bt[n][k], At[m][k], acc[ai][bj][m][n], 0, 0, 0); __builtin_amdgcn_s_setprio(0); } while (0)
; #define PG8_WAIT_V(n) asm volatile("s_waitcnt vmcnt(" #n ")" ::: "memory")
; #define PG8_WAIT_L(n) asm volatile("s_waitcnt lgkmcnt(" #n ")" ::: "memory")
; #define PG8_BAR __builtin_amdgcn_s_barrier()
; #define PG8_SCHED __builtin_amdgcn_sched_barrier(0)
; template <class Epi, class Sched, bool ALIGN_EPI = false, bool SP2 = false>
; __device__ __forceinline__ void gemm_phase(PG8_LAS unsigned char* lds, const Gemm g, const Sched& S, const Epi& E) {
;     ...
;             PG8_WAIT_V(8); PG8_WAIT_L(0); PG8_BAR; PG8_MMA(1, 0, At, B0); PG8_MMA(1, 1, At, B1); PG8_BAR; PG8_SCHED;
;             PG8_LDB(B0, 1, 0); PG8_LDB(B1, 1, 1); PG8_SCHED; PG8_LDA(At, 1, 0); PG8_STAGE(PG8_SA(0, 1), a2 + hstepA, voffA);
;             PG8_WAIT_V(8); PG8_WAIT_L(0); PG8_BAR; PG8_MMA(0, 0, At, B0); PG8_MMA(0, 1, At, B1); PG8_BAR; PG8_SCHED;
	s_waitcnt lgkmcnt(0)
	v_mfma_f32_16x16x32_bf16 v[28:31], v[128:131], v[180:183], v[28:31]
	v_mfma_f32_16x16x32_bf16 v[24:27], v[136:139], v[180:183], v[24:27]
	v_mfma_f32_16x16x32_bf16 v[20:23], v[128:131], v[188:191], v[20:23]
	v_mfma_f32_16x16x32_bf16 v[16:19], v[136:139], v[188:191], v[16:19]
	v_mfma_f32_16x16x32_bf16 v[12:15], v[128:131], v[208:211], v[12:15]
	v_mfma_f32_16x16x32_bf16 v[8:11], v[136:139], v[208:211], v[8:11]
	v_mfma_f32_16x16x32_bf16 v[4:7], v[128:131], v[222:225], v[4:7]
	v_mfma_f32_16x16x32_bf16 v[0:3], v[136:139], v[222:225], v[0:3]
	v_mfma_f32_16x16x32_bf16 v[28:31], v[132:135], v[184:187], v[28:31]
	v_mfma_f32_16x16x32_bf16 v[24:27], v[140:143], v[184:187], v[24:27]
	v_mfma_f32_16x16x32_bf16 v[20:23], v[132:135], v[204:207], v[20:23]
	v_mfma_f32_16x16x32_bf16 v[16:19], v[140:143], v[204:207], v[16:19]
	v_mfma_f32_16x16x32_bf16 v[12:15], v[132:135], v[218:221], v[12:15]
	v_mfma_f32_16x16x32_bf16 v[8:11], v[140:143], v[218:221], v[8:11]
	v_mfma_f32_16x16x32_bf16 v[4:7], v[132:135], v[226:229], v[4:7]
	v_mfma_f32_16x16x32_bf16 v[0:3], v[140:143], v[226:229], v[0:3]
	v_mfma_f32_16x16x32_bf16 v[92:95], v[144:147], v[180:183], v[92:95]
	v_mfma_f32_16x16x32_bf16 v[88:91], v[166:169], v[180:183], v[88:91]
	v_mfma_f32_16x16x32_bf16 v[84:87], v[144:147], v[188:191], v[84:87]
	v_mfma_f32_16x16x32_bf16 v[80:83], v[166:169], v[188:191], v[80:83]
	v_mfma_f32_16x16x32_bf16 v[76:79], v[144:147], v[208:211], v[76:79]
	v_mfma_f32_16x16x32_bf16 v[72:75], v[166:169], v[208:211], v[72:75]
	v_mfma_f32_16x16x32_bf16 v[68:71], v[144:147], v[222:225], v[68:71]
	v_mfma_f32_16x16x32_bf16 v[64:67], v[166:169], v[222:225], v[64:67]
	v_mfma_f32_16x16x32_bf16 v[92:95], v[148:151], v[184:187], v[92:95]
	v_mfma_f32_16x16x32_bf16 v[88:91], v[176:179], v[184:187], v[88:91]
	v_mfma_f32_16x16x32_bf16 v[84:87], v[148:151], v[204:207], v[84:87]
	v_mfma_f32_16x16x32_bf16 v[80:83], v[176:179], v[204:207], v[80:83]
	v_mfma_f32_16x16x32_bf16 v[76:79], v[148:151], v[218:221], v[76:79]
	v_mfma_f32_16x16x32_bf16 v[72:75], v[176:179], v[218:221], v[72:75]
	v_mfma_f32_16x16x32_bf16 v[68:71], v[148:151], v[226:229], v[68:71]
	v_mfma_f32_16x16x32_bf16 v[64:67], v[176:179], v[226:229], v[64:67]
	s_barrier
	v_add_u32_e32 v140, s68, v173
	v_add_u32_e32 v176, s1, v173
	ds_read_b128 v[128:131], v140
	ds_read_b128 v[132:135], v140 offset:1024
	ds_read_b128 v[136:139], v140 offset:2048
	ds_read_b128 v[140:143], v140 offset:3072
	ds_read_b128 v[144:147], v176
	ds_read_b128 v[148:151], v176 offset:1024
	ds_read_b128 v[166:169], v176 offset:2048
	ds_read_b128 v[176:179], v176 offset:3072
	s_add_u32 s16, s16, 0x40000
	s_addc_u32 s17, s17, 0
	s_mov_b32 m0, s4
	v_lshl_add_u64 v[236:237], s[16:17], 0, v[152:153]
	ds_read_b128 v[180:183], v175 offset:32768
	ds_read_b128 v[184:187], v175 offset:33792
	ds_read_b128 v[188:191], v175 offset:34816
	ds_read_b128 v[204:207], v175 offset:35840
	ds_read_b128 v[208:211], v175 offset:36864
	ds_read_b128 v[218:221], v175 offset:37888
	ds_read_b128 v[222:225], v175 offset:38912
	ds_read_b128 v[226:229], v175 offset:39936
	global_load_lds_dwordx4 v[236:237], off
	v_lshl_add_u64 v[236:237], s[16:17], 0, v[156:157]
	s_mov_b32 m0, s5
	s_nop 0
	global_load_lds_dwordx4 v[236:237], off
	s_waitcnt vmcnt(8)
	s_waitcnt lgkmcnt(0)
	s_barrier
	s_waitcnt lgkmcnt(0)
	v_mfma_f32_16x16x32_bf16 v[60:63], v[128:131], v[180:183], v[60:63]
	v_mfma_f32_16x16x32_bf16 v[56:59], v[136:139], v[180:183], v[56:59]
	v_mfma_f32_16x16x32_bf16 v[52:55], v[128:131], v[188:191], v[52:55]
	v_mfma_f32_16x16x32_bf16 v[48:51], v[136:139], v[188:191], v[48:51]
	v_mfma_f32_16x16x32_bf16 v[44:47], v[128:131], v[208:211], v[44:47]
	v_mfma_f32_16x16x32_bf16 v[40:43], v[136:139], v[208:211], v[40:43]
	v_mfma_f32_16x16x32_bf16 v[36:39], v[128:131], v[222:225], v[36:39]
	v_mfma_f32_16x16x32_bf16 v[32:35], v[136:139], v[222:225], v[32:35]
	v_mfma_f32_16x16x32_bf16 v[60:63], v[132:135], v[184:187], v[60:63]
	v_mfma_f32_16x16x32_bf16 v[56:59], v[140:143], v[184:187], v[56:59]
	v_mfma_f32_16x16x32_bf16 v[52:55], v[132:135], v[204:207], v[52:55]
	v_mfma_f32_16x16x32_bf16 v[48:51], v[140:143], v[204:207], v[48:51]
	v_mfma_f32_16x16x32_bf16 v[44:47], v[132:135], v[218:221], v[44:47]
	v_mfma_f32_16x16x32_bf16 v[40:43], v[140:143], v[218:221], v[40:43]
	v_mfma_f32_16x16x32_bf16 v[36:39], v[132:135], v[226:229], v[36:39]
	v_mfma_f32_16x16x32_bf16 v[32:35], v[140:143], v[226:229], v[32:35]
	v_mfma_f32_16x16x32_bf16 v[124:127], v[144:147], v[180:183], v[124:127]
	v_mfma_f32_16x16x32_bf16 v[120:123], v[166:169], v[180:183], v[120:123]
	v_mfma_f32_16x16x32_bf16 v[116:119], v[144:147], v[188:191], v[116:119]
	v_mfma_f32_16x16x32_bf16 v[112:115], v[166:169], v[188:191], v[112:115]
	v_mfma_f32_16x16x32_bf16 v[108:111], v[144:147], v[208:211], v[108:111]
	v_mfma_f32_16x16x32_bf16 v[104:107], v[166:169], v[208:211], v[104:107]
	v_mfma_f32_16x16x32_bf16 v[100:103], v[144:147], v[222:225], v[100:103]
	v_mfma_f32_16x16x32_bf16 v[96:99], v[166:169], v[222:225], v[96:99]
	v_mfma_f32_16x16x32_bf16 v[124:127], v[148:151], v[184:187], v[124:127]
	v_mfma_f32_16x16x32_bf16 v[120:123], v[176:179], v[184:187], v[120:123]
	v_mfma_f32_16x16x32_bf16 v[116:119], v[148:151], v[204:207], v[116:119]
	v_mfma_f32_16x16x32_bf16 v[112:115], v[176:179], v[204:207], v[112:115]
	v_mfma_f32_16x16x32_bf16 v[108:111], v[148:151], v[218:221], v[108:111]
	v_mfma_f32_16x16x32_bf16 v[104:107], v[176:179], v[218:221], v[104:107]
	v_mfma_f32_16x16x32_bf16 v[100:103], v[148:151], v[226:229], v[100:103]
	v_mfma_f32_16x16x32_bf16 v[96:99], v[176:179], v[226:229], v[96:99]
	s_barrier
; #define PG8_STAGE(bufoff, gbase, voff) do { _Pragma("unroll") for (int _i = 0; _i < 2; ++_i) \
;         __builtin_amdgcn_global_load_lds((const unsigned*)((const char*)(gbase) + (voff)[_i]), (PG8_LAS unsigned*)(lds + (bufoff) + ldsw + _i * 8192), 16, 0, 0); } while (0)
; #define PG8_LDA(dst, b, h) do { _Pragma("unroll") for (int m = 0; m < 4; ++m) _Pragma("unroll") for (int k = 0; k < 2; ++k) dst[m][k] = *(const PG8_LAS bf16x8*)(lds + PG8_SA(b, h) + aoff + m * 2048 + k * 1024); } while (0)
; #define PG8_MMA(ai, bj, At, Bt) do { __builtin_amdgcn_s_setprio(1); _Pragma("unroll") for (int m = 0; m < 4; ++m) _Pragma("unroll") for (int n = 0; n < 2; ++n) _Pragma("unroll") for (int k = 0; k < 2; ++k) \
;         acc[ai][bj][m][n] = __builtin_amdgcn_mfma_f32_16x16x32_bf16(Bt[n][k], At[m][k], acc[ai][bj][m][n], 0, 0, 0); __builtin_amdgcn_s_setprio(0); } while (0)
; #define PG8_WAIT_V(n) asm volatile("s_waitcnt vmcnt(" #n ")" ::: "memory")
; #define PG8_WAIT_L(n) asm volatile("s_waitcnt lgkmcnt(" #n ")" ::: "memory")
; #define PG8_BAR __builtin_amdgcn_s_barrier()
; #define PG8_SCHED __builtin_amdgcn_sched_barrier(0)
; template <class Epi, class Sched, bool ALIGN_EPI = false, bool SP2 = false>
; __device__ __forceinline__ void gemm_phase(PG8_LAS unsigned char* lds, const Gemm g, const Sched& S, const Epi& E) {
;     ...
;             PG8_LDA(At, 1, 1); PG8_STAGE(PG8_SB(1, 0), b3, voffB); PG8_STAGE(PG8_SB(1, 1), b3 + hstepB, voffB); PG8_STAGE(PG8_SA(1, 0), a3, voffA);
;             PG8_WAIT_V(8); PG8_WAIT_L(0); PG8_BAR; PG8_MMA(1, 0, At, B0); PG8_MMA(1, 1, At, B1); PG8_BAR; PG8_SCHED;
; __device__ __forceinline__ float row_rstd(const float* ssq, int row, int fq) {
;     const f32x4 v = *(const f32x4*)(ssq + (size_t)row * 16 + fq * 4);
;     float s = (v[0] + v[1]) + (v[2] + v[3]);
;     s += __shfl_xor(s, 16); s += __shfl_xor(s, 32);
;     return __builtin_amdgcn_rsqf(s * (1.f / DM) + EPS);
; }
	s_mov_b32 m0, s84
	v_lshl_add_u64 v[170:171], v[170:171], 0, s[76:77]
	s_add_u32 s14, s14, 0x40080
	ds_read_b128 v[180:183], v175 offset:49152
	ds_read_b128 v[184:187], v175 offset:50176
	ds_read_b128 v[188:191], v175 offset:51200
	ds_read_b128 v[204:207], v175 offset:52224
	ds_read_b128 v[208:211], v175 offset:53248
	ds_read_b128 v[218:221], v175 offset:54272
	ds_read_b128 v[222:225], v175 offset:55296
	ds_read_b128 v[226:229], v175 offset:56320
	global_load_lds_dwordx4 v[170:171], off
	v_lshl_add_u64 v[170:171], v[230:231], 0, s[76:77]
	s_mov_b32 m0, s64
	s_addc_u32 s15, s15, 0
	global_load_lds_dwordx4 v[170:171], off
	v_lshl_add_u64 v[170:171], s[14:15], 0, v[154:155]
	s_mov_b32 m0, s48
	s_nop 0
	global_load_lds_dwordx4 v[170:171], off
	v_lshl_add_u64 v[170:171], s[14:15], 0, v[158:159]
	s_mov_b32 m0, s49
	s_nop 0
	global_load_lds_dwordx4 v[170:171], off
	v_lshl_add_u64 v[170:171], v[232:233], 0, s[76:77]
	s_mov_b32 m0, s65
	s_nop 0
	global_load_lds_dwordx4 v[170:171], off
	v_lshl_add_u64 v[170:171], v[234:235], 0, s[76:77]
	s_mov_b32 m0, s0
	s_nop 0
	global_load_lds_dwordx4 v[170:171], off
	s_waitcnt vmcnt(8)
	s_waitcnt lgkmcnt(0)
	s_barrier
	s_waitcnt lgkmcnt(0)
	v_mfma_f32_16x16x32_bf16 v[28:31], v[128:131], v[180:183], v[28:31]
	v_mfma_f32_16x16x32_bf16 v[24:27], v[136:139], v[180:183], v[24:27]
	v_mfma_f32_16x16x32_bf16 v[20:23], v[128:131], v[188:191], v[20:23]
	v_mfma_f32_16x16x32_bf16 v[16:19], v[136:139], v[188:191], v[16:19]
	v_mfma_f32_16x16x32_bf16 v[12:15], v[128:131], v[208:211], v[12:15]
	v_mfma_f32_16x16x32_bf16 v[8:11], v[136:139], v[208:211], v[8:11]
	v_mfma_f32_16x16x32_bf16 v[4:7], v[128:131], v[222:225], v[4:7]
	v_mfma_f32_16x16x32_bf16 v[0:3], v[136:139], v[222:225], v[0:3]
	v_mfma_f32_16x16x32_bf16 v[28:31], v[132:135], v[184:187], v[28:31]
	v_mfma_f32_16x16x32_bf16 v[24:27], v[140:143], v[184:187], v[24:27]
	v_mfma_f32_16x16x32_bf16 v[20:23], v[132:135], v[204:207], v[20:23]
	v_mfma_f32_16x16x32_bf16 v[16:19], v[140:143], v[204:207], v[16:19]
	v_mfma_f32_16x16x32_bf16 v[12:15], v[132:135], v[218:221], v[12:15]
	v_mfma_f32_16x16x32_bf16 v[8:11], v[140:143], v[218:221], v[8:11]
	v_mfma_f32_16x16x32_bf16 v[4:7], v[132:135], v[226:229], v[4:7]
	v_mfma_f32_16x16x32_bf16 v[0:3], v[140:143], v[226:229], v[0:3]
	v_mfma_f32_16x16x32_bf16 v[92:95], v[144:147], v[180:183], v[92:95]
	v_mfma_f32_16x16x32_bf16 v[88:91], v[166:169], v[180:183], v[88:91]
	v_mfma_f32_16x16x32_bf16 v[84:87], v[144:147], v[188:191], v[84:87]
	v_mfma_f32_16x16x32_bf16 v[80:83], v[166:169], v[188:191], v[80:83]
	v_mfma_f32_16x16x32_bf16 v[76:79], v[144:147], v[208:211], v[76:79]
	v_mfma_f32_16x16x32_bf16 v[72:75], v[166:169], v[208:211], v[72:75]
	v_mfma_f32_16x16x32_bf16 v[68:71], v[144:147], v[222:225], v[68:71]
	v_mfma_f32_16x16x32_bf16 v[64:67], v[166:169], v[222:225], v[64:67]
	v_mfma_f32_16x16x32_bf16 v[92:95], v[148:151], v[184:187], v[92:95]
	v_mfma_f32_16x16x32_bf16 v[88:91], v[176:179], v[184:187], v[88:91]
	v_mfma_f32_16x16x32_bf16 v[84:87], v[148:151], v[204:207], v[84:87]
	v_mfma_f32_16x16x32_bf16 v[80:83], v[176:179], v[204:207], v[80:83]
	v_mfma_f32_16x16x32_bf16 v[76:79], v[148:151], v[218:221], v[76:79]
	v_mfma_f32_16x16x32_bf16 v[72:75], v[176:179], v[218:221], v[72:75]
	v_mfma_f32_16x16x32_bf16 v[68:71], v[148:151], v[226:229], v[68:71]
	v_mfma_f32_16x16x32_bf16 v[64:67], v[176:179], v[226:229], v[64:67]
	s_barrier
	s_add_i32 s22, s22, 2
	s_add_u32 s20, s20, 0x100
	s_addc_u32 s21, s21, 0
	s_add_u32 s12, s12, 0x100
	s_addc_u32 s13, s13, 0
	s_cmp_gt_u32 s22, 13
	s_cbranch_scc0 .LBB0_380
	s_cmp_eq_u32 s10, 14
	s_cbranch_scc1 .Lewh_skip
	v_lshl_add_u32 v214, s8, 8, v172
	v_mov_b32_e32 v128, v214
	v_ashrrev_i32_e32 v129, 31, v128
	v_lshlrev_b64 v[128:129], 6, v[128:129]
	v_lshl_add_u64 v[128:129], v[160:161], 0, v[128:129]
	global_load_dwordx4 v[128:131], v[128:129], off
	v_add_u32_e32 v132, 16, v214
	v_ashrrev_i32_e32 v133, 31, v132
	v_lshlrev_b64 v[132:133], 6, v[132:133]
	v_lshl_add_u64 v[132:133], v[160:161], 0, v[132:133]
	global_load_dwordx4 v[132:135], v[132:133], off
	v_add_u32_e32 v136, 32, v214
	v_ashrrev_i32_e32 v137, 31, v136
	v_lshlrev_b64 v[136:137], 6, v[136:137]
	v_lshl_add_u64 v[136:137], v[160:161], 0, v[136:137]
	global_load_dwordx4 v[136:139], v[136:137], off
	v_add_u32_e32 v140, 48, v214
	v_ashrrev_i32_e32 v141, 31, v140
	v_lshlrev_b64 v[140:141], 6, v[140:141]
	v_lshl_add_u64 v[140:141], v[160:161], 0, v[140:141]
	global_load_dwordx4 v[140:143], v[140:141], off
	v_add_u32_e32 v144, 0x80, v214
	v_ashrrev_i32_e32 v145, 31, v144
	v_lshlrev_b64 v[144:145], 6, v[144:145]
	v_lshl_add_u64 v[144:145], v[160:161], 0, v[144:145]
	global_load_dwordx4 v[144:147], v[144:145], off
	v_add_u32_e32 v148, 0x90, v214
	v_ashrrev_i32_e32 v149, 31, v148
	v_lshlrev_b64 v[148:149], 6, v[148:149]
	v_lshl_add_u64 v[148:149], v[160:161], 0, v[148:149]
	global_load_dwordx4 v[148:151], v[148:149], off
	v_add_u32_e32 v236, 0xa0, v214
	v_ashrrev_i32_e32 v237, 31, v236
	v_lshlrev_b64 v[236:237], 6, v[236:237]
	v_lshl_add_u64 v[236:237], v[160:161], 0, v[236:237]
	global_load_dwordx4 v[236:239], v[236:237], off
	v_add_u32_e32 v246, 0xb0, v214
	v_ashrrev_i32_e32 v247, 31, v246
	v_lshlrev_b64 v[246:247], 6, v[246:247]
	v_lshl_add_u64 v[246:247], v[160:161], 0, v[246:247]
	global_load_dwordx4 v[246:249], v[246:247], off

; #define PG8_STAGE(bufoff, gbase, voff) do { _Pragma("unroll") for (int _i = 0; _i < 2; ++_i) \
;         __builtin_amdgcn_global_load_lds((const unsigned*)((const char*)(gbase) + (voff)[_i]), (PG8_LAS unsigned*)(lds + (bufoff) + ldsw + _i * 8192), 16, 0, 0); } while (0)
; #define PG8_LDA(dst, b, h) do { _Pragma("unroll") for (int m = 0; m < 4; ++m) _Pragma("unroll") for (int k = 0; k < 2; ++k) dst[m][k] = *(const PG8_LAS bf16x8*)(lds + PG8_SA(b, h) + aoff + m * 2048 + k * 1024); } while (0)
; #define PG8_LDB(dst, b, h) do { _Pragma("unroll") for (int n = 0; n < 2; ++n) _Pragma("unroll") for (int k = 0; k < 2; ++k) dst[n][k] = *(const PG8_LAS bf16x8*)(lds + PG8_SB(b, h) + boff + n * 2048 + k * 1024); } while (0)
; #define PG8_MMA(ai, bj, At, Bt) do { __builtin_amdgcn_s_setprio(1); _Pragma("unroll") for (int m = 0; m < 4; ++m) _Pragma("unroll") for (int n = 0; n < 2; ++n) _Pragma("unroll") for (int k = 0; k < 2; ++k) \
;         acc[ai][bj][m][n] = __builtin_amdgcn_mfma_f32_16x16x32_bf16(Bt[n][k], At[m][k], acc[ai][bj][m][n], 0, 0, 0); __builtin_amdgcn_s_setprio(0); } while (0)
; #define PG8_WAIT_V(n) asm volatile("s_waitcnt vmcnt(" #n ")" ::: "memory")
; #define PG8_WAIT_L(n) asm volatile("s_waitcnt lgkmcnt(" #n ")" ::: "memory")
; #define PG8_BAR __builtin_amdgcn_s_barrier()
; #define PG8_SCHED __builtin_amdgcn_sched_barrier(0)
; template <class Epi, class Sched, bool ALIGN_EPI = false, bool SP2 = false>
; __device__ __forceinline__ void gemm_phase(PG8_LAS unsigned char* lds, const Gemm g, const Sched& S, const Epi& E) {
;     ...
;             PG8_LDB(B0, 0, 0); PG8_LDB(B1, 0, 1); PG8_SCHED; PG8_LDA(At, 0, 0); PG8_STAGE(PG8_SA(1, 1), a1 + hstepA, voffA);
;             PG8_WAIT_V(8); PG8_WAIT_L(0); PG8_BAR; PG8_MMA(0, 0, At, B0); PG8_MMA(0, 1, At, B1); PG8_BAR; PG8_SCHED;
;             PG8_LDA(At, 0, 1); PG8_STAGE(PG8_SB(0, 0), b2, voffB); PG8_STAGE(PG8_SB(0, 1), b2 + hstepB, voffB); PG8_STAGE(PG8_SA(0, 0), a2, voffA);
.LBB0_885:
	v_add_u32_e32 v142, s9, v145
	ds_read_b128 v[138:141], v142
	ds_read_b128 v[148:151], v142 offset:1024
	ds_read_b128 v[152:155], v142 offset:2048
	ds_read_b128 v[156:159], v142 offset:3072
	v_add_u32_e32 v142, s42, v145
	ds_read_b128 v[160:163], v142
	ds_read_b128 v[164:167], v142 offset:1024
	ds_read_b128 v[168:171], v142 offset:2048
	ds_read_b128 v[172:175], v142 offset:3072
	s_add_u32 s2, s28, 0xfffc0080
	s_addc_u32 s30, s29, -1
	s_cmp_eq_u32 s82, 12
	s_cselect_b32 s35, s21, s30
	s_cselect_b32 s34, s27, s2
	s_cselect_b32 s31, s19, s79
	s_cselect_b32 s30, s68, s78
	v_lshl_add_u64 v[142:143], s[28:29], 0, v[136:137]
	s_add_i32 m0, s45, 0xc000
	ds_read_b128 v[176:179], v147
	ds_read_b128 v[180:183], v147 offset:1024
	ds_read_b128 v[184:187], v147 offset:2048
	ds_read_b128 v[188:191], v147 offset:3072
	ds_read_b128 v[204:207], v147 offset:4096
	ds_read_b128 v[208:211], v147 offset:5120
	ds_read_b128 v[218:221], v147 offset:6144
	ds_read_b128 v[222:225], v147 offset:7168
	global_load_lds_dwordx4 v[142:143], off
	v_lshl_add_u64 v[142:143], s[28:29], 0, v[134:135]
	s_add_i32 m0, s45, 0xe000
	s_nop 0
	global_load_lds_dwordx4 v[142:143], off
	s_waitcnt vmcnt(8)
	s_waitcnt lgkmcnt(0)
	s_barrier
	s_waitcnt lgkmcnt(0)
	v_mfma_f32_16x16x32_bf16 v[124:127], v[138:141], v[176:179], v[124:127]
	v_mfma_f32_16x16x32_bf16 v[120:123], v[152:155], v[176:179], v[120:123]
	v_mfma_f32_16x16x32_bf16 v[108:111], v[138:141], v[184:187], v[108:111]
	v_mfma_f32_16x16x32_bf16 v[104:107], v[152:155], v[184:187], v[104:107]
	v_mfma_f32_16x16x32_bf16 v[92:95], v[138:141], v[204:207], v[92:95]
	v_mfma_f32_16x16x32_bf16 v[88:91], v[152:155], v[204:207], v[88:91]
	v_mfma_f32_16x16x32_bf16 v[76:79], v[138:141], v[218:221], v[76:79]
	v_mfma_f32_16x16x32_bf16 v[72:75], v[152:155], v[218:221], v[72:75]
	v_mfma_f32_16x16x32_bf16 v[124:127], v[148:151], v[180:183], v[124:127]
	v_mfma_f32_16x16x32_bf16 v[120:123], v[156:159], v[180:183], v[120:123]
	v_mfma_f32_16x16x32_bf16 v[108:111], v[148:151], v[188:191], v[108:111]
	v_mfma_f32_16x16x32_bf16 v[104:107], v[156:159], v[188:191], v[104:107]
	v_mfma_f32_16x16x32_bf16 v[92:95], v[148:151], v[208:211], v[92:95]
	v_mfma_f32_16x16x32_bf16 v[88:91], v[156:159], v[208:211], v[88:91]
	v_mfma_f32_16x16x32_bf16 v[76:79], v[148:151], v[222:225], v[76:79]
	v_mfma_f32_16x16x32_bf16 v[72:75], v[156:159], v[222:225], v[72:75]
	v_mfma_f32_16x16x32_bf16 v[116:119], v[160:163], v[176:179], v[116:119]
	v_mfma_f32_16x16x32_bf16 v[112:115], v[168:171], v[176:179], v[112:115]
	v_mfma_f32_16x16x32_bf16 v[100:103], v[160:163], v[184:187], v[100:103]
	v_mfma_f32_16x16x32_bf16 v[96:99], v[168:171], v[184:187], v[96:99]
	v_mfma_f32_16x16x32_bf16 v[84:87], v[160:163], v[204:207], v[84:87]
	v_mfma_f32_16x16x32_bf16 v[80:83], v[168:171], v[204:207], v[80:83]
	v_mfma_f32_16x16x32_bf16 v[68:71], v[160:163], v[218:221], v[68:71]
	v_mfma_f32_16x16x32_bf16 v[64:67], v[168:171], v[218:221], v[64:67]
	v_mfma_f32_16x16x32_bf16 v[116:119], v[164:167], v[180:183], v[116:119]
	v_mfma_f32_16x16x32_bf16 v[112:115], v[172:175], v[180:183], v[112:115]
	v_mfma_f32_16x16x32_bf16 v[100:103], v[164:167], v[188:191], v[100:103]
	v_mfma_f32_16x16x32_bf16 v[96:99], v[172:175], v[188:191], v[96:99]
	v_mfma_f32_16x16x32_bf16 v[84:87], v[164:167], v[208:211], v[84:87]
	v_mfma_f32_16x16x32_bf16 v[80:83], v[172:175], v[208:211], v[80:83]
	v_mfma_f32_16x16x32_bf16 v[68:71], v[164:167], v[222:225], v[68:71]
	v_mfma_f32_16x16x32_bf16 v[64:67], v[172:175], v[222:225], v[64:67]
	s_barrier
	s_mov_b32 m0, s40
	v_lshl_add_u64 v[142:143], s[30:31], 0, v[192:193]
	s_add_u32 s84, s30, 0x40000
	ds_read_b128 v[176:179], v147 offset:16384
	ds_read_b128 v[180:183], v147 offset:17408
	ds_read_b128 v[184:187], v147 offset:18432
	ds_read_b128 v[188:191], v147 offset:19456
	ds_read_b128 v[204:207], v147 offset:20480
	ds_read_b128 v[208:211], v147 offset:21504
	ds_read_b128 v[218:221], v147 offset:22528
	ds_read_b128 v[222:225], v147 offset:23552
	global_load_lds_dwordx4 v[142:143], off
	v_lshl_add_u64 v[226:227], s[30:31], 0, v[132:133]
	s_mov_b32 m0, s41
	s_addc_u32 s85, s31, 0
	global_load_lds_dwordx4 v[226:227], off
	v_lshl_add_u64 v[228:229], s[84:85], 0, v[192:193]
	s_mov_b32 m0, s43
	v_lshl_add_u64 v[230:231], s[34:35], 0, v[130:131]
	global_load_lds_dwordx4 v[228:229], off
	v_lshl_add_u64 v[228:229], s[84:85], 0, v[132:133]
	s_mov_b32 m0, s44
	s_nop 0
	global_load_lds_dwordx4 v[228:229], off
	v_lshl_add_u64 v[228:229], s[34:35], 0, v[128:129]
	s_mov_b32 m0, s45
	s_nop 0
	global_load_lds_dwordx4 v[228:229], off
	s_mov_b32 m0, s48
	s_nop 0
	global_load_lds_dwordx4 v[230:231], off
	s_waitcnt vmcnt(8)
	s_waitcnt lgkmcnt(0)
	s_barrier
; #define PG8_STAGE(bufoff, gbase, voff) do { _Pragma("unroll") for (int _i = 0; _i < 2; ++_i) \
;         __builtin_amdgcn_global_load_lds((const unsigned*)((const char*)(gbase) + (voff)[_i]), (PG8_LAS unsigned*)(lds + (bufoff) + ldsw + _i * 8192), 16, 0, 0); } while (0)
; #define PG8_LDA(dst, b, h) do { _Pragma("unroll") for (int m = 0; m < 4; ++m) _Pragma("unroll") for (int k = 0; k < 2; ++k) dst[m][k] = *(const PG8_LAS bf16x8*)(lds + PG8_SA(b, h) + aoff + m * 2048 + k * 1024); } while (0)
; #define PG8_LDB(dst, b, h) do { _Pragma("unroll") for (int n = 0; n < 2; ++n) _Pragma("unroll") for (int k = 0; k < 2; ++k) dst[n][k] = *(const PG8_LAS bf16x8*)(lds + PG8_SB(b, h) + boff + n * 2048 + k * 1024); } while (0)
; #define PG8_MMA(ai, bj, At, Bt) do { __builtin_amdgcn_s_setprio(1); _Pragma("unroll") for (int m = 0; m < 4; ++m) _Pragma("unroll") for (int n = 0; n < 2; ++n) _Pragma("unroll") for (int k = 0; k < 2; ++k) \
;         acc[ai][bj][m][n] = __builtin_amdgcn_mfma_f32_16x16x32_bf16(Bt[n][k], At[m][k], acc[ai][bj][m][n], 0, 0, 0); __builtin_amdgcn_s_setprio(0); } while (0)
; #define PG8_WAIT_V(n) asm volatile("s_waitcnt vmcnt(" #n ")" ::: "memory")
; #define PG8_WAIT_L(n) asm volatile("s_waitcnt lgkmcnt(" #n ")" ::: "memory")
; #define PG8_BAR __builtin_amdgcn_s_barrier()
; #define PG8_SCHED __builtin_amdgcn_sched_barrier(0)
; template <class Epi, class Sched, bool ALIGN_EPI = false, bool SP2 = false>
; __device__ __forceinline__ void gemm_phase(PG8_LAS unsigned char* lds, const Gemm g, const Sched& S, const Epi& E) {
;     ...
;             PG8_WAIT_V(8); PG8_WAIT_L(0); PG8_BAR; PG8_MMA(1, 0, At, B0); PG8_MMA(1, 1, At, B1); PG8_BAR; PG8_SCHED;
;             PG8_LDB(B0, 1, 0); PG8_LDB(B1, 1, 1); PG8_SCHED; PG8_LDA(At, 1, 0); PG8_STAGE(PG8_SA(0, 1), a2 + hstepA, voffA);
;             PG8_WAIT_V(8); PG8_WAIT_L(0); PG8_BAR; PG8_MMA(0, 0, At, B0); PG8_MMA(0, 1, At, B1); PG8_BAR; PG8_SCHED;
	s_waitcnt lgkmcnt(0)
	v_mfma_f32_16x16x32_bf16 v[60:63], v[138:141], v[176:179], v[60:63]
	v_mfma_f32_16x16x32_bf16 v[56:59], v[152:155], v[176:179], v[56:59]
	v_mfma_f32_16x16x32_bf16 v[44:47], v[138:141], v[184:187], v[44:47]
	v_mfma_f32_16x16x32_bf16 v[40:43], v[152:155], v[184:187], v[40:43]
	v_mfma_f32_16x16x32_bf16 v[28:31], v[138:141], v[204:207], v[28:31]
	v_mfma_f32_16x16x32_bf16 v[24:27], v[152:155], v[204:207], v[24:27]
	v_mfma_f32_16x16x32_bf16 v[12:15], v[138:141], v[218:221], v[12:15]
	v_mfma_f32_16x16x32_bf16 v[8:11], v[152:155], v[218:221], v[8:11]
	v_mfma_f32_16x16x32_bf16 v[60:63], v[148:151], v[180:183], v[60:63]
	v_mfma_f32_16x16x32_bf16 v[56:59], v[156:159], v[180:183], v[56:59]
	v_mfma_f32_16x16x32_bf16 v[44:47], v[148:151], v[188:191], v[44:47]
	v_mfma_f32_16x16x32_bf16 v[40:43], v[156:159], v[188:191], v[40:43]
	v_mfma_f32_16x16x32_bf16 v[28:31], v[148:151], v[208:211], v[28:31]
	v_mfma_f32_16x16x32_bf16 v[24:27], v[156:159], v[208:211], v[24:27]
	v_mfma_f32_16x16x32_bf16 v[12:15], v[148:151], v[222:225], v[12:15]
	v_mfma_f32_16x16x32_bf16 v[8:11], v[156:159], v[222:225], v[8:11]
	v_mfma_f32_16x16x32_bf16 v[52:55], v[160:163], v[176:179], v[52:55]
	v_mfma_f32_16x16x32_bf16 v[48:51], v[168:171], v[176:179], v[48:51]
	v_mfma_f32_16x16x32_bf16 v[36:39], v[160:163], v[184:187], v[36:39]
	v_mfma_f32_16x16x32_bf16 v[32:35], v[168:171], v[184:187], v[32:35]
	v_mfma_f32_16x16x32_bf16 v[20:23], v[160:163], v[204:207], v[20:23]
	v_mfma_f32_16x16x32_bf16 v[16:19], v[168:171], v[204:207], v[16:19]
	v_mfma_f32_16x16x32_bf16 v[4:7], v[160:163], v[218:221], v[4:7]
	v_mfma_f32_16x16x32_bf16 v[0:3], v[168:171], v[218:221], v[0:3]
	v_mfma_f32_16x16x32_bf16 v[52:55], v[164:167], v[180:183], v[52:55]
	v_mfma_f32_16x16x32_bf16 v[48:51], v[172:175], v[180:183], v[48:51]
	v_mfma_f32_16x16x32_bf16 v[36:39], v[164:167], v[188:191], v[36:39]
	v_mfma_f32_16x16x32_bf16 v[32:35], v[172:175], v[188:191], v[32:35]
	v_mfma_f32_16x16x32_bf16 v[20:23], v[164:167], v[208:211], v[20:23]
	v_mfma_f32_16x16x32_bf16 v[16:19], v[172:175], v[208:211], v[16:19]
	v_mfma_f32_16x16x32_bf16 v[4:7], v[164:167], v[222:225], v[4:7]
	v_mfma_f32_16x16x32_bf16 v[0:3], v[172:175], v[222:225], v[0:3]
	s_barrier
	v_add_u32_e32 v156, s60, v145
	v_add_u32_e32 v172, s67, v145
	ds_read_b128 v[138:141], v156
	ds_read_b128 v[148:151], v156 offset:1024
	ds_read_b128 v[152:155], v156 offset:2048
	ds_read_b128 v[156:159], v156 offset:3072
	ds_read_b128 v[160:163], v172
	ds_read_b128 v[164:167], v172 offset:1024
	ds_read_b128 v[168:171], v172 offset:2048
	ds_read_b128 v[172:175], v172 offset:3072
	s_add_u32 s34, s34, 0x40000
	s_addc_u32 s35, s35, 0
	s_mov_b32 m0, s49
	v_lshl_add_u64 v[232:233], s[34:35], 0, v[128:129]
	ds_read_b128 v[176:179], v147 offset:32768
	ds_read_b128 v[180:183], v147 offset:33792
	ds_read_b128 v[184:187], v147 offset:34816
	ds_read_b128 v[188:191], v147 offset:35840
	ds_read_b128 v[204:207], v147 offset:36864
	ds_read_b128 v[208:211], v147 offset:37888
	ds_read_b128 v[218:221], v147 offset:38912
	ds_read_b128 v[222:225], v147 offset:39936
	global_load_lds_dwordx4 v[232:233], off
	v_lshl_add_u64 v[232:233], s[34:35], 0, v[130:131]
	s_mov_b32 m0, s50
	s_nop 0
	global_load_lds_dwordx4 v[232:233], off
	s_waitcnt vmcnt(8)
	s_waitcnt lgkmcnt(0)
	s_barrier
	s_waitcnt lgkmcnt(0)
	v_mfma_f32_16x16x32_bf16 v[124:127], v[138:141], v[176:179], v[124:127]
	v_mfma_f32_16x16x32_bf16 v[120:123], v[152:155], v[176:179], v[120:123]
	v_mfma_f32_16x16x32_bf16 v[108:111], v[138:141], v[184:187], v[108:111]
	v_mfma_f32_16x16x32_bf16 v[104:107], v[152:155], v[184:187], v[104:107]
	v_mfma_f32_16x16x32_bf16 v[92:95], v[138:141], v[204:207], v[92:95]
	v_mfma_f32_16x16x32_bf16 v[88:91], v[152:155], v[204:207], v[88:91]
	v_mfma_f32_16x16x32_bf16 v[76:79], v[138:141], v[218:221], v[76:79]
	v_mfma_f32_16x16x32_bf16 v[72:75], v[152:155], v[218:221], v[72:75]
	v_mfma_f32_16x16x32_bf16 v[124:127], v[148:151], v[180:183], v[124:127]
	v_mfma_f32_16x16x32_bf16 v[120:123], v[156:159], v[180:183], v[120:123]
	v_mfma_f32_16x16x32_bf16 v[108:111], v[148:151], v[188:191], v[108:111]
	v_mfma_f32_16x16x32_bf16 v[104:107], v[156:159], v[188:191], v[104:107]
	v_mfma_f32_16x16x32_bf16 v[92:95], v[148:151], v[208:211], v[92:95]
	v_mfma_f32_16x16x32_bf16 v[88:91], v[156:159], v[208:211], v[88:91]
	v_mfma_f32_16x16x32_bf16 v[76:79], v[148:151], v[222:225], v[76:79]
	v_mfma_f32_16x16x32_bf16 v[72:75], v[156:159], v[222:225], v[72:75]
	v_mfma_f32_16x16x32_bf16 v[116:119], v[160:163], v[176:179], v[116:119]
	v_mfma_f32_16x16x32_bf16 v[112:115], v[168:171], v[176:179], v[112:115]
	v_mfma_f32_16x16x32_bf16 v[100:103], v[160:163], v[184:187], v[100:103]
	v_mfma_f32_16x16x32_bf16 v[96:99], v[168:171], v[184:187], v[96:99]
	v_mfma_f32_16x16x32_bf16 v[84:87], v[160:163], v[204:207], v[84:87]
	v_mfma_f32_16x16x32_bf16 v[80:83], v[168:171], v[204:207], v[80:83]
	v_mfma_f32_16x16x32_bf16 v[68:71], v[160:163], v[218:221], v[68:71]
	v_mfma_f32_16x16x32_bf16 v[64:67], v[168:171], v[218:221], v[64:67]
	v_mfma_f32_16x16x32_bf16 v[116:119], v[164:167], v[180:183], v[116:119]
	v_mfma_f32_16x16x32_bf16 v[112:115], v[172:175], v[180:183], v[112:115]
	v_mfma_f32_16x16x32_bf16 v[100:103], v[164:167], v[188:191], v[100:103]
	v_mfma_f32_16x16x32_bf16 v[96:99], v[172:175], v[188:191], v[96:99]
	v_mfma_f32_16x16x32_bf16 v[84:87], v[164:167], v[208:211], v[84:87]
	v_mfma_f32_16x16x32_bf16 v[80:83], v[172:175], v[208:211], v[80:83]
	v_mfma_f32_16x16x32_bf16 v[68:71], v[164:167], v[222:225], v[68:71]
	v_mfma_f32_16x16x32_bf16 v[64:67], v[172:175], v[222:225], v[64:67]
	s_barrier
; #define PG8_STAGE(bufoff, gbase, voff) do { _Pragma("unroll") for (int _i = 0; _i < 2; ++_i) \
;         __builtin_amdgcn_global_load_lds((const unsigned*)((const char*)(gbase) + (voff)[_i]), (PG8_LAS unsigned*)(lds + (bufoff) + ldsw + _i * 8192), 16, 0, 0); } while (0)
; #define PG8_LDA(dst, b, h) do { _Pragma("unroll") for (int m = 0; m < 4; ++m) _Pragma("unroll") for (int k = 0; k < 2; ++k) dst[m][k] = *(const PG8_LAS bf16x8*)(lds + PG8_SA(b, h) + aoff + m * 2048 + k * 1024); } while (0)
; #define PG8_MMA(ai, bj, At, Bt) do { __builtin_amdgcn_s_setprio(1); _Pragma("unroll") for (int m = 0; m < 4; ++m) _Pragma("unroll") for (int n = 0; n < 2; ++n) _Pragma("unroll") for (int k = 0; k < 2; ++k) \
;         acc[ai][bj][m][n] = __builtin_amdgcn_mfma_f32_16x16x32_bf16(Bt[n][k], At[m][k], acc[ai][bj][m][n], 0, 0, 0); __builtin_amdgcn_s_setprio(0); } while (0)
; #define PG8_WAIT_V(n) asm volatile("s_waitcnt vmcnt(" #n ")" ::: "memory")
; #define PG8_WAIT_L(n) asm volatile("s_waitcnt lgkmcnt(" #n ")" ::: "memory")
; #define PG8_BAR __builtin_amdgcn_s_barrier()
; #define PG8_SCHED __builtin_amdgcn_sched_barrier(0)
; template <class Epi, class Sched, bool ALIGN_EPI = false, bool SP2 = false>
; __device__ __forceinline__ void gemm_phase(PG8_LAS unsigned char* lds, const Gemm g, const Sched& S, const Epi& E) {
;     ...
;             PG8_LDA(At, 1, 1); PG8_STAGE(PG8_SB(1, 0), b3, voffB); PG8_STAGE(PG8_SB(1, 1), b3 + hstepB, voffB); PG8_STAGE(PG8_SA(1, 0), a3, voffA);
;             PG8_WAIT_V(8); PG8_WAIT_L(0); PG8_BAR; PG8_MMA(1, 0, At, B0); PG8_MMA(1, 1, At, B1); PG8_BAR; PG8_SCHED;
;     __device__ __forceinline__ void operator()(const f32x4 (&acc)[2][2][4][2], const pg8::Unit& u, int wr, int wc, int fr, int fq) const {
;     ...
;                     const size_t off = (size_t)row * DM + col0 + bj * 128;
;                     const v4u b = *(const v4u*)(xb + off);
	s_mov_b32 m0, s61
	v_lshl_add_u64 v[142:143], v[142:143], 0, s[76:77]
	s_add_u32 s30, s30, 0x40080
	ds_read_b128 v[176:179], v147 offset:49152
	ds_read_b128 v[180:183], v147 offset:50176
	ds_read_b128 v[184:187], v147 offset:51200
	ds_read_b128 v[188:191], v147 offset:52224
	ds_read_b128 v[204:207], v147 offset:53248
	ds_read_b128 v[208:211], v147 offset:54272
	ds_read_b128 v[218:221], v147 offset:55296
	ds_read_b128 v[222:225], v147 offset:56320
	global_load_lds_dwordx4 v[142:143], off
	v_lshl_add_u64 v[142:143], v[226:227], 0, s[76:77]
	s_mov_b32 m0, s64
	s_addc_u32 s31, s31, 0
	global_load_lds_dwordx4 v[142:143], off
	v_lshl_add_u64 v[142:143], s[30:31], 0, v[192:193]
	s_mov_b32 m0, s70
	s_nop 0
	global_load_lds_dwordx4 v[142:143], off
	v_lshl_add_u64 v[142:143], s[30:31], 0, v[132:133]
	s_mov_b32 m0, s71
	s_nop 0
	global_load_lds_dwordx4 v[142:143], off
	v_lshl_add_u64 v[142:143], v[228:229], 0, s[76:77]
	s_mov_b32 m0, s65
	s_nop 0
	global_load_lds_dwordx4 v[142:143], off
	v_lshl_add_u64 v[142:143], v[230:231], 0, s[76:77]
	s_mov_b32 m0, s66
	s_nop 0
	global_load_lds_dwordx4 v[142:143], off
	s_waitcnt vmcnt(8)
	s_waitcnt lgkmcnt(0)
	s_barrier
	s_waitcnt lgkmcnt(0)
	v_mfma_f32_16x16x32_bf16 v[60:63], v[138:141], v[176:179], v[60:63]
	v_mfma_f32_16x16x32_bf16 v[56:59], v[152:155], v[176:179], v[56:59]
	v_mfma_f32_16x16x32_bf16 v[44:47], v[138:141], v[184:187], v[44:47]
	v_mfma_f32_16x16x32_bf16 v[40:43], v[152:155], v[184:187], v[40:43]
	v_mfma_f32_16x16x32_bf16 v[28:31], v[138:141], v[204:207], v[28:31]
	v_mfma_f32_16x16x32_bf16 v[24:27], v[152:155], v[204:207], v[24:27]
	v_mfma_f32_16x16x32_bf16 v[12:15], v[138:141], v[218:221], v[12:15]
	v_mfma_f32_16x16x32_bf16 v[8:11], v[152:155], v[218:221], v[8:11]
	v_mfma_f32_16x16x32_bf16 v[60:63], v[148:151], v[180:183], v[60:63]
	v_mfma_f32_16x16x32_bf16 v[56:59], v[156:159], v[180:183], v[56:59]
	v_mfma_f32_16x16x32_bf16 v[44:47], v[148:151], v[188:191], v[44:47]
	v_mfma_f32_16x16x32_bf16 v[40:43], v[156:159], v[188:191], v[40:43]
	v_mfma_f32_16x16x32_bf16 v[28:31], v[148:151], v[208:211], v[28:31]
	v_mfma_f32_16x16x32_bf16 v[24:27], v[156:159], v[208:211], v[24:27]
	v_mfma_f32_16x16x32_bf16 v[12:15], v[148:151], v[222:225], v[12:15]
	v_mfma_f32_16x16x32_bf16 v[8:11], v[156:159], v[222:225], v[8:11]
	v_mfma_f32_16x16x32_bf16 v[52:55], v[160:163], v[176:179], v[52:55]
	v_mfma_f32_16x16x32_bf16 v[48:51], v[168:171], v[176:179], v[48:51]
	v_mfma_f32_16x16x32_bf16 v[36:39], v[160:163], v[184:187], v[36:39]
	v_mfma_f32_16x16x32_bf16 v[32:35], v[168:171], v[184:187], v[32:35]
	v_mfma_f32_16x16x32_bf16 v[20:23], v[160:163], v[204:207], v[20:23]
	v_mfma_f32_16x16x32_bf16 v[16:19], v[168:171], v[204:207], v[16:19]
	v_mfma_f32_16x16x32_bf16 v[4:7], v[160:163], v[218:221], v[4:7]
	v_mfma_f32_16x16x32_bf16 v[0:3], v[168:171], v[218:221], v[0:3]
	v_mfma_f32_16x16x32_bf16 v[52:55], v[164:167], v[180:183], v[52:55]
	v_mfma_f32_16x16x32_bf16 v[48:51], v[172:175], v[180:183], v[48:51]
	v_mfma_f32_16x16x32_bf16 v[36:39], v[164:167], v[188:191], v[36:39]
	v_mfma_f32_16x16x32_bf16 v[32:35], v[172:175], v[188:191], v[32:35]
	v_mfma_f32_16x16x32_bf16 v[20:23], v[164:167], v[208:211], v[20:23]
	v_mfma_f32_16x16x32_bf16 v[16:19], v[172:175], v[208:211], v[16:19]
	v_mfma_f32_16x16x32_bf16 v[4:7], v[164:167], v[222:225], v[4:7]
	v_mfma_f32_16x16x32_bf16 v[0:3], v[172:175], v[222:225], v[0:3]
	s_barrier
	s_add_i32 s82, s82, 2
	s_add_u32 s78, s78, 0x100
	s_addc_u32 s79, s79, 0
	s_add_u32 s28, s28, 0x100
	s_addc_u32 s29, s29, 0
	s_cmp_gt_u32 s82, 13
	s_cbranch_scc0 .LBB0_885
	v_lshl_add_u32 v159, s26, 8, v144
	v_lshl_or_b32 v158, s8, 8, v146
	v_lshlrev_b32_e32 v159, 11, v159
	v_lshl_add_u32 v159, v158, 1, v159
	v_add_u32_e32 v218, 0x8000, v159
	v_add_u32_e32 v219, 0x10000, v159
	v_add_u32_e32 v240, 0x18000, v159
	v_add_u32_e32 v241, 0x40000, v159
	v_add_u32_e32 v245, 0x48000, v159
	v_add_u32_e32 v246, 0x50000, v159
	v_add_u32_e32 v247, 0x58000, v159
	global_load_dwordx4 v[160:163], v159, s[12:13]
	global_load_dwordx4 v[164:167], v159, s[12:13] offset:256
	global_load_dwordx4 v[168:171], v218, s[12:13]
	global_load_dwordx4 v[172:175], v218, s[12:13] offset:256
	global_load_dwordx4 v[176:179], v219, s[12:13]
	global_load_dwordx4 v[180:183], v219, s[12:13] offset:256
	global_load_dwordx4 v[184:187], v240, s[12:13]
	global_load_dwordx4 v[188:191], v240, s[12:13] offset:256
	global_load_dwordx4 v[204:207], v241, s[12:13]
	global_load_dwordx4 v[208:211], v241, s[12:13] offset:256
	global_load_dwordx4 v[220:223], v245, s[12:13]
	global_load_dwordx4 v[224:227], v245, s[12:13] offset:256
	global_load_dwordx4 v[228:231], v246, s[12:13]
	global_load_dwordx4 v[232:235], v246, s[12:13] offset:256
	global_load_dwordx4 v[236:239], v247, s[12:13]
	global_load_dwordx4 v[248:251], v247, s[12:13] offset:256
	s_and_b64 vcc, exec, s[16:17]
	s_cbranch_vccz .LBB0_888
	s_barrier

; #define PG8_STAGE(bufoff, gbase, voff) do { _Pragma("unroll") for (int _i = 0; _i < 2; ++_i) \
;         __builtin_amdgcn_global_load_lds((const unsigned*)((const char*)(gbase) + (voff)[_i]), (PG8_LAS unsigned*)(lds + (bufoff) + ldsw + _i * 8192), 16, 0, 0); } while (0)
; #define PG8_LDA(dst, b, h) do { _Pragma("unroll") for (int m = 0; m < 4; ++m) _Pragma("unroll") for (int k = 0; k < 2; ++k) dst[m][k] = *(const PG8_LAS bf16x8*)(lds + PG8_SA(b, h) + aoff + m * 2048 + k * 1024); } while (0)
; #define PG8_LDB(dst, b, h) do { _Pragma("unroll") for (int n = 0; n < 2; ++n) _Pragma("unroll") for (int k = 0; k < 2; ++k) dst[n][k] = *(const PG8_LAS bf16x8*)(lds + PG8_SB(b, h) + boff + n * 2048 + k * 1024); } while (0)
; #define PG8_MMA(ai, bj, At, Bt) do { __builtin_amdgcn_s_setprio(1); _Pragma("unroll") for (int m = 0; m < 4; ++m) _Pragma("unroll") for (int n = 0; n < 2; ++n) _Pragma("unroll") for (int k = 0; k < 2; ++k) \
;         acc[ai][bj][m][n] = __builtin_amdgcn_mfma_f32_16x16x32_bf16(Bt[n][k], At[m][k], acc[ai][bj][m][n], 0, 0, 0); __builtin_amdgcn_s_setprio(0); } while (0)
; #define PG8_WAIT_V(n) asm volatile("s_waitcnt vmcnt(" #n ")" ::: "memory")
; #define PG8_WAIT_L(n) asm volatile("s_waitcnt lgkmcnt(" #n ")" ::: "memory")
; #define PG8_BAR __builtin_amdgcn_s_barrier()
; #define PG8_SCHED __builtin_amdgcn_sched_barrier(0)
; template <class Epi, class Sched, bool ALIGN_EPI = false, bool SP2 = false>
; __device__ __forceinline__ void gemm_phase(PG8_LAS unsigned char* lds, const Gemm g, const Sched& S, const Epi& E) {
;     ...
;             PG8_LDB(B0, 0, 0); PG8_LDB(B1, 0, 1); PG8_SCHED; PG8_LDA(At, 0, 0); PG8_STAGE(PG8_SA(1, 1), a1 + hstepA, voffA);
;             PG8_WAIT_V(8); PG8_WAIT_L(0); PG8_BAR; PG8_MMA(0, 0, At, B0); PG8_MMA(0, 1, At, B1); PG8_BAR; PG8_SCHED;
;             PG8_LDA(At, 0, 1); PG8_STAGE(PG8_SB(0, 0), b2, voffB); PG8_STAGE(PG8_SB(0, 1), b2 + hstepB, voffB); PG8_STAGE(PG8_SA(0, 0), a2, voffA);
.LBB0_995:
	v_add_u32_e32 v154, s38, v175
	v_add_u32_e32 v170, s41, v175
	ds_read_b128 v[142:145], v154
	ds_read_b128 v[146:149], v154 offset:1024
	ds_read_b128 v[150:153], v154 offset:2048
	ds_read_b128 v[154:157], v154 offset:3072
	ds_read_b128 v[158:161], v170
	ds_read_b128 v[162:165], v170 offset:1024
	ds_read_b128 v[166:169], v170 offset:2048
	ds_read_b128 v[170:173], v170 offset:3072
	s_add_u32 s2, s26, 0xfffc0080
	s_addc_u32 s28, s27, -1
	s_cmp_eq_u32 s82, 12
	s_cselect_b32 s31, s17, s28
	s_cselect_b32 s30, s23, s2
	s_cselect_b32 s29, s15, s79
	s_cselect_b32 s28, s25, s78
	v_lshl_add_u64 v[246:247], s[26:27], 0, v[140:141]
	s_add_i32 m0, s44, 0xc000
	ds_read_b128 v[208:211], v207
	ds_read_b128 v[218:221], v207 offset:1024
	ds_read_b128 v[222:225], v207 offset:2048
	ds_read_b128 v[226:229], v207 offset:3072
	ds_read_b128 v[230:233], v207 offset:4096
	ds_read_b128 v[234:237], v207 offset:5120
	ds_read_b128 v[238:241], v207 offset:6144
	ds_read_b128 v[242:245], v207 offset:7168
	global_load_lds_dwordx4 v[246:247], off
	v_lshl_add_u64 v[246:247], s[26:27], 0, v[138:139]
	s_add_i32 m0, s44, 0xe000
	s_nop 0
	global_load_lds_dwordx4 v[246:247], off
	s_waitcnt vmcnt(8)
	s_waitcnt lgkmcnt(0)
	s_barrier
	s_waitcnt lgkmcnt(0)
	v_mfma_f32_16x16x32_bf16 v[124:127], v[142:145], v[208:211], v[124:127]
	v_mfma_f32_16x16x32_bf16 v[120:123], v[150:153], v[208:211], v[120:123]
	v_mfma_f32_16x16x32_bf16 v[108:111], v[142:145], v[222:225], v[108:111]
	v_mfma_f32_16x16x32_bf16 v[104:107], v[150:153], v[222:225], v[104:107]
	v_mfma_f32_16x16x32_bf16 v[92:95], v[142:145], v[230:233], v[92:95]
	v_mfma_f32_16x16x32_bf16 v[88:91], v[150:153], v[230:233], v[88:91]
	v_mfma_f32_16x16x32_bf16 v[76:79], v[142:145], v[238:241], v[76:79]
	v_mfma_f32_16x16x32_bf16 v[72:75], v[150:153], v[238:241], v[72:75]
	v_mfma_f32_16x16x32_bf16 v[124:127], v[146:149], v[218:221], v[124:127]
	v_mfma_f32_16x16x32_bf16 v[120:123], v[154:157], v[218:221], v[120:123]
	v_mfma_f32_16x16x32_bf16 v[108:111], v[146:149], v[226:229], v[108:111]
	v_mfma_f32_16x16x32_bf16 v[104:107], v[154:157], v[226:229], v[104:107]
	v_mfma_f32_16x16x32_bf16 v[92:95], v[146:149], v[234:237], v[92:95]
	v_mfma_f32_16x16x32_bf16 v[88:91], v[154:157], v[234:237], v[88:91]
	v_mfma_f32_16x16x32_bf16 v[76:79], v[146:149], v[242:245], v[76:79]
	v_mfma_f32_16x16x32_bf16 v[72:75], v[154:157], v[242:245], v[72:75]
	v_mfma_f32_16x16x32_bf16 v[116:119], v[158:161], v[208:211], v[116:119]
	v_mfma_f32_16x16x32_bf16 v[112:115], v[166:169], v[208:211], v[112:115]
	v_mfma_f32_16x16x32_bf16 v[100:103], v[158:161], v[222:225], v[100:103]
	v_mfma_f32_16x16x32_bf16 v[96:99], v[166:169], v[222:225], v[96:99]
	v_mfma_f32_16x16x32_bf16 v[84:87], v[158:161], v[230:233], v[84:87]
	v_mfma_f32_16x16x32_bf16 v[80:83], v[166:169], v[230:233], v[80:83]
	v_mfma_f32_16x16x32_bf16 v[68:71], v[158:161], v[238:241], v[68:71]
	v_mfma_f32_16x16x32_bf16 v[64:67], v[166:169], v[238:241], v[64:67]
	v_mfma_f32_16x16x32_bf16 v[116:119], v[162:165], v[218:221], v[116:119]
	v_mfma_f32_16x16x32_bf16 v[112:115], v[170:173], v[218:221], v[112:115]
	v_mfma_f32_16x16x32_bf16 v[100:103], v[162:165], v[226:229], v[100:103]
	v_mfma_f32_16x16x32_bf16 v[96:99], v[170:173], v[226:229], v[96:99]
	v_mfma_f32_16x16x32_bf16 v[84:87], v[162:165], v[234:237], v[84:87]
	v_mfma_f32_16x16x32_bf16 v[80:83], v[170:173], v[234:237], v[80:83]
	v_mfma_f32_16x16x32_bf16 v[68:71], v[162:165], v[242:245], v[68:71]
	v_mfma_f32_16x16x32_bf16 v[64:67], v[170:173], v[242:245], v[64:67]
	s_barrier
	s_mov_b32 m0, s39
	v_lshl_add_u64 v[246:247], s[28:29], 0, v[130:131]
	s_add_u32 s84, s28, 0x40000
	ds_read_b128 v[208:211], v207 offset:16384
	ds_read_b128 v[218:221], v207 offset:17408
	ds_read_b128 v[222:225], v207 offset:18432
	ds_read_b128 v[226:229], v207 offset:19456
	ds_read_b128 v[230:233], v207 offset:20480
	ds_read_b128 v[234:237], v207 offset:21504
	ds_read_b128 v[238:241], v207 offset:22528
	ds_read_b128 v[242:245], v207 offset:23552
	global_load_lds_dwordx4 v[246:247], off
	v_lshl_add_u64 v[248:249], s[28:29], 0, v[134:135]
	s_mov_b32 m0, s40
	s_addc_u32 s85, s29, 0
	global_load_lds_dwordx4 v[248:249], off
	v_lshl_add_u64 v[250:251], s[84:85], 0, v[130:131]
	s_mov_b32 m0, s42
	v_lshl_add_u64 v[252:253], s[30:31], 0, v[132:133]
	global_load_lds_dwordx4 v[250:251], off
	v_lshl_add_u64 v[250:251], s[84:85], 0, v[134:135]
	s_mov_b32 m0, s43
	s_nop 0
	global_load_lds_dwordx4 v[250:251], off
	v_lshl_add_u64 v[250:251], s[30:31], 0, v[128:129]
	s_mov_b32 m0, s44
	s_nop 0
	global_load_lds_dwordx4 v[250:251], off
	s_mov_b32 m0, s45
	s_nop 0
	global_load_lds_dwordx4 v[252:253], off
	s_waitcnt vmcnt(8)
	s_waitcnt lgkmcnt(0)
	s_barrier
; #define PG8_STAGE(bufoff, gbase, voff) do { _Pragma("unroll") for (int _i = 0; _i < 2; ++_i) \
;         __builtin_amdgcn_global_load_lds((const unsigned*)((const char*)(gbase) + (voff)[_i]), (PG8_LAS unsigned*)(lds + (bufoff) + ldsw + _i * 8192), 16, 0, 0); } while (0)
; #define PG8_LDA(dst, b, h) do { _Pragma("unroll") for (int m = 0; m < 4; ++m) _Pragma("unroll") for (int k = 0; k < 2; ++k) dst[m][k] = *(const PG8_LAS bf16x8*)(lds + PG8_SA(b, h) + aoff + m * 2048 + k * 1024); } while (0)
; #define PG8_LDB(dst, b, h) do { _Pragma("unroll") for (int n = 0; n < 2; ++n) _Pragma("unroll") for (int k = 0; k < 2; ++k) dst[n][k] = *(const PG8_LAS bf16x8*)(lds + PG8_SB(b, h) + boff + n * 2048 + k * 1024); } while (0)
; #define PG8_MMA(ai, bj, At, Bt) do { __builtin_amdgcn_s_setprio(1); _Pragma("unroll") for (int m = 0; m < 4; ++m) _Pragma("unroll") for (int n = 0; n < 2; ++n) _Pragma("unroll") for (int k = 0; k < 2; ++k) \
;         acc[ai][bj][m][n] = __builtin_amdgcn_mfma_f32_16x16x32_bf16(Bt[n][k], At[m][k], acc[ai][bj][m][n], 0, 0, 0); __builtin_amdgcn_s_setprio(0); } while (0)
; #define PG8_WAIT_V(n) asm volatile("s_waitcnt vmcnt(" #n ")" ::: "memory")
; #define PG8_WAIT_L(n) asm volatile("s_waitcnt lgkmcnt(" #n ")" ::: "memory")
; #define PG8_BAR __builtin_amdgcn_s_barrier()
; #define PG8_SCHED __builtin_amdgcn_sched_barrier(0)
; template <class Epi, class Sched, bool ALIGN_EPI = false, bool SP2 = false>
; __device__ __forceinline__ void gemm_phase(PG8_LAS unsigned char* lds, const Gemm g, const Sched& S, const Epi& E) {
;     ...
;             PG8_WAIT_V(8); PG8_WAIT_L(0); PG8_BAR; PG8_MMA(1, 0, At, B0); PG8_MMA(1, 1, At, B1); PG8_BAR; PG8_SCHED;
;             PG8_LDB(B0, 1, 0); PG8_LDB(B1, 1, 1); PG8_SCHED; PG8_LDA(At, 1, 0); PG8_STAGE(PG8_SA(0, 1), a2 + hstepA, voffA);
;             PG8_WAIT_V(8); PG8_WAIT_L(0); PG8_BAR; PG8_MMA(0, 0, At, B0); PG8_MMA(0, 1, At, B1); PG8_BAR; PG8_SCHED;
	s_waitcnt lgkmcnt(0)
	v_mfma_f32_16x16x32_bf16 v[60:63], v[142:145], v[208:211], v[60:63]
	v_mfma_f32_16x16x32_bf16 v[56:59], v[150:153], v[208:211], v[56:59]
	v_mfma_f32_16x16x32_bf16 v[44:47], v[142:145], v[222:225], v[44:47]
	v_mfma_f32_16x16x32_bf16 v[40:43], v[150:153], v[222:225], v[40:43]
	v_mfma_f32_16x16x32_bf16 v[28:31], v[142:145], v[230:233], v[28:31]
	v_mfma_f32_16x16x32_bf16 v[24:27], v[150:153], v[230:233], v[24:27]
	v_mfma_f32_16x16x32_bf16 v[12:15], v[142:145], v[238:241], v[12:15]
	v_mfma_f32_16x16x32_bf16 v[8:11], v[150:153], v[238:241], v[8:11]
	v_mfma_f32_16x16x32_bf16 v[60:63], v[146:149], v[218:221], v[60:63]
	v_mfma_f32_16x16x32_bf16 v[56:59], v[154:157], v[218:221], v[56:59]
	v_mfma_f32_16x16x32_bf16 v[44:47], v[146:149], v[226:229], v[44:47]
	v_mfma_f32_16x16x32_bf16 v[40:43], v[154:157], v[226:229], v[40:43]
	v_mfma_f32_16x16x32_bf16 v[28:31], v[146:149], v[234:237], v[28:31]
	v_mfma_f32_16x16x32_bf16 v[24:27], v[154:157], v[234:237], v[24:27]
	v_mfma_f32_16x16x32_bf16 v[12:15], v[146:149], v[242:245], v[12:15]
	v_mfma_f32_16x16x32_bf16 v[8:11], v[154:157], v[242:245], v[8:11]
	v_mfma_f32_16x16x32_bf16 v[52:55], v[158:161], v[208:211], v[52:55]
	v_mfma_f32_16x16x32_bf16 v[48:51], v[166:169], v[208:211], v[48:51]
	v_mfma_f32_16x16x32_bf16 v[36:39], v[158:161], v[222:225], v[36:39]
	v_mfma_f32_16x16x32_bf16 v[32:35], v[166:169], v[222:225], v[32:35]
	v_mfma_f32_16x16x32_bf16 v[20:23], v[158:161], v[230:233], v[20:23]
	v_mfma_f32_16x16x32_bf16 v[16:19], v[166:169], v[230:233], v[16:19]
	v_mfma_f32_16x16x32_bf16 v[4:7], v[158:161], v[238:241], v[4:7]
	v_mfma_f32_16x16x32_bf16 v[0:3], v[166:169], v[238:241], v[0:3]
	v_mfma_f32_16x16x32_bf16 v[52:55], v[162:165], v[218:221], v[52:55]
	v_mfma_f32_16x16x32_bf16 v[48:51], v[170:173], v[218:221], v[48:51]
	v_mfma_f32_16x16x32_bf16 v[36:39], v[162:165], v[226:229], v[36:39]
	v_mfma_f32_16x16x32_bf16 v[32:35], v[170:173], v[226:229], v[32:35]
	v_mfma_f32_16x16x32_bf16 v[20:23], v[162:165], v[234:237], v[20:23]
	v_mfma_f32_16x16x32_bf16 v[16:19], v[170:173], v[234:237], v[16:19]
	v_mfma_f32_16x16x32_bf16 v[4:7], v[162:165], v[242:245], v[4:7]
	v_mfma_f32_16x16x32_bf16 v[0:3], v[170:173], v[242:245], v[0:3]
	s_barrier
	v_add_u32_e32 v154, s50, v175
	v_add_u32_e32 v170, s65, v175
	ds_read_b128 v[142:145], v154
	ds_read_b128 v[146:149], v154 offset:1024
	ds_read_b128 v[150:153], v154 offset:2048
	ds_read_b128 v[154:157], v154 offset:3072
	ds_read_b128 v[158:161], v170
	ds_read_b128 v[162:165], v170 offset:1024
	ds_read_b128 v[166:169], v170 offset:2048
	ds_read_b128 v[170:173], v170 offset:3072
	s_add_u32 s30, s30, 0x40000
	s_addc_u32 s31, s31, 0
	s_mov_b32 m0, s48
	v_lshl_add_u64 v[194:195], s[30:31], 0, v[128:129]
	ds_read_b128 v[208:211], v207 offset:32768
	ds_read_b128 v[218:221], v207 offset:33792
	ds_read_b128 v[222:225], v207 offset:34816
	ds_read_b128 v[226:229], v207 offset:35840
	ds_read_b128 v[230:233], v207 offset:36864
	ds_read_b128 v[234:237], v207 offset:37888
	ds_read_b128 v[238:241], v207 offset:38912
	ds_read_b128 v[242:245], v207 offset:39936
	global_load_lds_dwordx4 v[194:195], off
	v_lshl_add_u64 v[194:195], s[30:31], 0, v[132:133]
	s_mov_b32 m0, s49
	s_nop 0
	global_load_lds_dwordx4 v[194:195], off
	s_waitcnt vmcnt(8)
	s_waitcnt lgkmcnt(0)
	s_barrier
	s_waitcnt lgkmcnt(0)
	v_mfma_f32_16x16x32_bf16 v[124:127], v[142:145], v[208:211], v[124:127]
	v_mfma_f32_16x16x32_bf16 v[120:123], v[150:153], v[208:211], v[120:123]
	v_mfma_f32_16x16x32_bf16 v[108:111], v[142:145], v[222:225], v[108:111]
	v_mfma_f32_16x16x32_bf16 v[104:107], v[150:153], v[222:225], v[104:107]
	v_mfma_f32_16x16x32_bf16 v[92:95], v[142:145], v[230:233], v[92:95]
	v_mfma_f32_16x16x32_bf16 v[88:91], v[150:153], v[230:233], v[88:91]
	v_mfma_f32_16x16x32_bf16 v[76:79], v[142:145], v[238:241], v[76:79]
	v_mfma_f32_16x16x32_bf16 v[72:75], v[150:153], v[238:241], v[72:75]
	v_mfma_f32_16x16x32_bf16 v[124:127], v[146:149], v[218:221], v[124:127]
	v_mfma_f32_16x16x32_bf16 v[120:123], v[154:157], v[218:221], v[120:123]
	v_mfma_f32_16x16x32_bf16 v[108:111], v[146:149], v[226:229], v[108:111]
	v_mfma_f32_16x16x32_bf16 v[104:107], v[154:157], v[226:229], v[104:107]
	v_mfma_f32_16x16x32_bf16 v[92:95], v[146:149], v[234:237], v[92:95]
	v_mfma_f32_16x16x32_bf16 v[88:91], v[154:157], v[234:237], v[88:91]
	v_mfma_f32_16x16x32_bf16 v[76:79], v[146:149], v[242:245], v[76:79]
	v_mfma_f32_16x16x32_bf16 v[72:75], v[154:157], v[242:245], v[72:75]
	v_mfma_f32_16x16x32_bf16 v[116:119], v[158:161], v[208:211], v[116:119]
	v_mfma_f32_16x16x32_bf16 v[112:115], v[166:169], v[208:211], v[112:115]
	v_mfma_f32_16x16x32_bf16 v[100:103], v[158:161], v[222:225], v[100:103]
	v_mfma_f32_16x16x32_bf16 v[96:99], v[166:169], v[222:225], v[96:99]
	v_mfma_f32_16x16x32_bf16 v[84:87], v[158:161], v[230:233], v[84:87]
	v_mfma_f32_16x16x32_bf16 v[80:83], v[166:169], v[230:233], v[80:83]
	v_mfma_f32_16x16x32_bf16 v[68:71], v[158:161], v[238:241], v[68:71]
	v_mfma_f32_16x16x32_bf16 v[64:67], v[166:169], v[238:241], v[64:67]
	v_mfma_f32_16x16x32_bf16 v[116:119], v[162:165], v[218:221], v[116:119]
	v_mfma_f32_16x16x32_bf16 v[112:115], v[170:173], v[218:221], v[112:115]
	v_mfma_f32_16x16x32_bf16 v[100:103], v[162:165], v[226:229], v[100:103]
	v_mfma_f32_16x16x32_bf16 v[96:99], v[170:173], v[226:229], v[96:99]
	v_mfma_f32_16x16x32_bf16 v[84:87], v[162:165], v[234:237], v[84:87]
	v_mfma_f32_16x16x32_bf16 v[80:83], v[170:173], v[234:237], v[80:83]
	v_mfma_f32_16x16x32_bf16 v[68:71], v[162:165], v[242:245], v[68:71]
	v_mfma_f32_16x16x32_bf16 v[64:67], v[170:173], v[242:245], v[64:67]
	s_barrier
; #define PG8_STAGE(bufoff, gbase, voff) do { _Pragma("unroll") for (int _i = 0; _i < 2; ++_i) \
;         __builtin_amdgcn_global_load_lds((const unsigned*)((const char*)(gbase) + (voff)[_i]), (PG8_LAS unsigned*)(lds + (bufoff) + ldsw + _i * 8192), 16, 0, 0); } while (0)
; #define PG8_LDA(dst, b, h) do { _Pragma("unroll") for (int m = 0; m < 4; ++m) _Pragma("unroll") for (int k = 0; k < 2; ++k) dst[m][k] = *(const PG8_LAS bf16x8*)(lds + PG8_SA(b, h) + aoff + m * 2048 + k * 1024); } while (0)
; #define PG8_MMA(ai, bj, At, Bt) do { __builtin_amdgcn_s_setprio(1); _Pragma("unroll") for (int m = 0; m < 4; ++m) _Pragma("unroll") for (int n = 0; n < 2; ++n) _Pragma("unroll") for (int k = 0; k < 2; ++k) \
;         acc[ai][bj][m][n] = __builtin_amdgcn_mfma_f32_16x16x32_bf16(Bt[n][k], At[m][k], acc[ai][bj][m][n], 0, 0, 0); __builtin_amdgcn_s_setprio(0); } while (0)
; #define PG8_WAIT_V(n) asm volatile("s_waitcnt vmcnt(" #n ")" ::: "memory")
; #define PG8_WAIT_L(n) asm volatile("s_waitcnt lgkmcnt(" #n ")" ::: "memory")
; #define PG8_BAR __builtin_amdgcn_s_barrier()
; #define PG8_SCHED __builtin_amdgcn_sched_barrier(0)
; template <class Epi, class Sched, bool ALIGN_EPI = false, bool SP2 = false>
; __device__ __forceinline__ void gemm_phase(PG8_LAS unsigned char* lds, const Gemm g, const Sched& S, const Epi& E) {
;     ...
;             PG8_LDA(At, 1, 1); PG8_STAGE(PG8_SB(1, 0), b3, voffB); PG8_STAGE(PG8_SB(1, 1), b3 + hstepB, voffB); PG8_STAGE(PG8_SA(1, 0), a3, voffA);
;             PG8_WAIT_V(8); PG8_WAIT_L(0); PG8_BAR; PG8_MMA(1, 0, At, B0); PG8_MMA(1, 1, At, B1); PG8_BAR; PG8_SCHED;
; __device__ __forceinline__ void row_rstd4(const float* ssq, int row0, int fq, float (&rs)[4]) {
;     f32x4 v[4];
; #pragma unroll
;     for (int m = 0; m < 4; ++m) v[m] = *(const f32x4*)(ssq + (size_t)(row0 + m * 16) * 16 + fq * 4);
; #pragma unroll
;     for (int m = 0; m < 4; ++m) { float t = (v[m][0] + v[m][1]) + (v[m][2] + v[m][3]); t += __shfl_xor(t, 16); t += __shfl_xor(t, 32); rs[m] = __builtin_amdgcn_rsqf(t * (1.f / DM) + EPS); }
	s_mov_b32 m0, s51
	v_lshl_add_u64 v[194:195], v[246:247], 0, s[76:77]
	s_add_u32 s28, s28, 0x40080
	ds_read_b128 v[208:211], v207 offset:49152
	ds_read_b128 v[218:221], v207 offset:50176
	ds_read_b128 v[222:225], v207 offset:51200
	ds_read_b128 v[226:229], v207 offset:52224
	ds_read_b128 v[230:233], v207 offset:53248
	ds_read_b128 v[234:237], v207 offset:54272
	ds_read_b128 v[238:241], v207 offset:55296
	ds_read_b128 v[242:245], v207 offset:56320
	global_load_lds_dwordx4 v[194:195], off
	v_lshl_add_u64 v[194:195], v[248:249], 0, s[76:77]
	s_mov_b32 m0, s60
	s_addc_u32 s29, s29, 0
	global_load_lds_dwordx4 v[194:195], off
	v_lshl_add_u64 v[194:195], s[28:29], 0, v[130:131]
	s_mov_b32 m0, s66
	s_nop 0
	global_load_lds_dwordx4 v[194:195], off
	v_lshl_add_u64 v[194:195], s[28:29], 0, v[134:135]
	s_mov_b32 m0, s67
	s_nop 0
	global_load_lds_dwordx4 v[194:195], off
	v_lshl_add_u64 v[194:195], v[250:251], 0, s[76:77]
	s_mov_b32 m0, s61
	s_nop 0
	global_load_lds_dwordx4 v[194:195], off
	v_lshl_add_u64 v[194:195], v[252:253], 0, s[76:77]
	s_mov_b32 m0, s64
	s_nop 0
	global_load_lds_dwordx4 v[194:195], off
	s_waitcnt vmcnt(8)
	s_waitcnt lgkmcnt(0)
	s_barrier
	s_waitcnt lgkmcnt(0)
	v_mfma_f32_16x16x32_bf16 v[60:63], v[142:145], v[208:211], v[60:63]
	v_mfma_f32_16x16x32_bf16 v[56:59], v[150:153], v[208:211], v[56:59]
	v_mfma_f32_16x16x32_bf16 v[44:47], v[142:145], v[222:225], v[44:47]
	v_mfma_f32_16x16x32_bf16 v[40:43], v[150:153], v[222:225], v[40:43]
	v_mfma_f32_16x16x32_bf16 v[28:31], v[142:145], v[230:233], v[28:31]
	v_mfma_f32_16x16x32_bf16 v[24:27], v[150:153], v[230:233], v[24:27]
	v_mfma_f32_16x16x32_bf16 v[12:15], v[142:145], v[238:241], v[12:15]
	v_mfma_f32_16x16x32_bf16 v[8:11], v[150:153], v[238:241], v[8:11]
	v_mfma_f32_16x16x32_bf16 v[60:63], v[146:149], v[218:221], v[60:63]
	v_mfma_f32_16x16x32_bf16 v[56:59], v[154:157], v[218:221], v[56:59]
	v_mfma_f32_16x16x32_bf16 v[44:47], v[146:149], v[226:229], v[44:47]
	v_mfma_f32_16x16x32_bf16 v[40:43], v[154:157], v[226:229], v[40:43]
	v_mfma_f32_16x16x32_bf16 v[28:31], v[146:149], v[234:237], v[28:31]
	v_mfma_f32_16x16x32_bf16 v[24:27], v[154:157], v[234:237], v[24:27]
	v_mfma_f32_16x16x32_bf16 v[12:15], v[146:149], v[242:245], v[12:15]
	v_mfma_f32_16x16x32_bf16 v[8:11], v[154:157], v[242:245], v[8:11]
	v_mfma_f32_16x16x32_bf16 v[52:55], v[158:161], v[208:211], v[52:55]
	v_mfma_f32_16x16x32_bf16 v[48:51], v[166:169], v[208:211], v[48:51]
	v_mfma_f32_16x16x32_bf16 v[36:39], v[158:161], v[222:225], v[36:39]
	v_mfma_f32_16x16x32_bf16 v[32:35], v[166:169], v[222:225], v[32:35]
	v_mfma_f32_16x16x32_bf16 v[20:23], v[158:161], v[230:233], v[20:23]
	v_mfma_f32_16x16x32_bf16 v[16:19], v[166:169], v[230:233], v[16:19]
	v_mfma_f32_16x16x32_bf16 v[4:7], v[158:161], v[238:241], v[4:7]
	v_mfma_f32_16x16x32_bf16 v[0:3], v[166:169], v[238:241], v[0:3]
	v_mfma_f32_16x16x32_bf16 v[52:55], v[162:165], v[218:221], v[52:55]
	v_mfma_f32_16x16x32_bf16 v[48:51], v[170:173], v[218:221], v[48:51]
	v_mfma_f32_16x16x32_bf16 v[36:39], v[162:165], v[226:229], v[36:39]
	v_mfma_f32_16x16x32_bf16 v[32:35], v[170:173], v[226:229], v[32:35]
	v_mfma_f32_16x16x32_bf16 v[20:23], v[162:165], v[234:237], v[20:23]
	v_mfma_f32_16x16x32_bf16 v[16:19], v[170:173], v[234:237], v[16:19]
	v_mfma_f32_16x16x32_bf16 v[4:7], v[162:165], v[242:245], v[4:7]
	v_mfma_f32_16x16x32_bf16 v[0:3], v[170:173], v[242:245], v[0:3]
	s_barrier
	s_add_i32 s82, s82, 2
	s_add_u32 s78, s78, 0x100
	s_addc_u32 s79, s79, 0
	s_add_u32 s26, s26, 0x100
	s_addc_u32 s27, s27, 0
	s_cmp_gt_u32 s82, 13
	s_cbranch_scc0 .LBB0_995
	v_lshl_add_u32 v228, s24, 8, v174
	v_mov_b32_e32 v144, v228
	v_ashrrev_i32_e32 v145, 31, v144
	v_lshlrev_b64 v[144:145], 6, v[144:145]
	v_lshl_add_u64 v[144:145], v[136:137], 0, v[144:145]
	global_load_dwordx4 v[144:147], v[144:145], off
	v_add_u32_e32 v148, 16, v228
	v_ashrrev_i32_e32 v149, 31, v148
	v_lshlrev_b64 v[148:149], 6, v[148:149]
	v_lshl_add_u64 v[148:149], v[136:137], 0, v[148:149]
	global_load_dwordx4 v[148:151], v[148:149], off
	v_add_u32_e32 v152, 32, v228
	v_ashrrev_i32_e32 v153, 31, v152
	v_lshlrev_b64 v[152:153], 6, v[152:153]
	v_lshl_add_u64 v[152:153], v[136:137], 0, v[152:153]
	global_load_dwordx4 v[152:155], v[152:153], off
	v_add_u32_e32 v156, 48, v228
	v_ashrrev_i32_e32 v157, 31, v156
	v_lshlrev_b64 v[156:157], 6, v[156:157]
	v_lshl_add_u64 v[156:157], v[136:137], 0, v[156:157]
	global_load_dwordx4 v[156:159], v[156:157], off
	v_add_u32_e32 v160, 0x80, v228
	v_ashrrev_i32_e32 v161, 31, v160
	v_lshlrev_b64 v[160:161], 6, v[160:161]
	v_lshl_add_u64 v[160:161], v[136:137], 0, v[160:161]
	global_load_dwordx4 v[160:163], v[160:161], off
	v_add_u32_e32 v164, 0x90, v228
	v_ashrrev_i32_e32 v165, 31, v164
	v_lshlrev_b64 v[164:165], 6, v[164:165]
	v_lshl_add_u64 v[164:165], v[136:137], 0, v[164:165]
	global_load_dwordx4 v[164:167], v[164:165], off
	v_add_u32_e32 v168, 0xa0, v228
	v_ashrrev_i32_e32 v169, 31, v168
	v_lshlrev_b64 v[168:169], 6, v[168:169]
	v_lshl_add_u64 v[168:169], v[136:137], 0, v[168:169]
	global_load_dwordx4 v[168:171], v[168:169], off
	v_add_u32_e32 v222, 0xb0, v228
	v_ashrrev_i32_e32 v223, 31, v222
	v_lshlrev_b64 v[222:223], 6, v[222:223]
	v_lshl_add_u64 v[222:223], v[136:137], 0, v[222:223]
	global_load_dwordx4 v[222:225], v[222:223], off
	v_xor_b32_e32 v226, 16, v215
	v_xor_b32_e32 v227, 32, v215
	v_lshlrev_b32_e32 v226, 2, v226
	v_lshlrev_b32_e32 v227, 2, v227
	s_and_b64 vcc, exec, s[12:13]
	s_cbranch_vccz .LBB0_998
	s_barrier

; #define PG8_STAGE(bufoff, gbase, voff) do { _Pragma("unroll") for (int _i = 0; _i < 2; ++_i) \
;         __builtin_amdgcn_global_load_lds((const unsigned*)((const char*)(gbase) + (voff)[_i]), (PG8_LAS unsigned*)(lds + (bufoff) + ldsw + _i * 8192), 16, 0, 0); } while (0)
; #define PG8_LDA(dst, b, h) do { _Pragma("unroll") for (int m = 0; m < 4; ++m) _Pragma("unroll") for (int k = 0; k < 2; ++k) dst[m][k] = *(const PG8_LAS bf16x8*)(lds + PG8_SA(b, h) + aoff + m * 2048 + k * 1024); } while (0)
; #define PG8_LDB(dst, b, h) do { _Pragma("unroll") for (int n = 0; n < 2; ++n) _Pragma("unroll") for (int k = 0; k < 2; ++k) dst[n][k] = *(const PG8_LAS bf16x8*)(lds + PG8_SB(b, h) + boff + n * 2048 + k * 1024); } while (0)
; #define PG8_MMA(ai, bj, At, Bt) do { __builtin_amdgcn_s_setprio(1); _Pragma("unroll") for (int m = 0; m < 4; ++m) _Pragma("unroll") for (int n = 0; n < 2; ++n) _Pragma("unroll") for (int k = 0; k < 2; ++k) \
;         acc[ai][bj][m][n] = __builtin_amdgcn_mfma_f32_16x16x32_bf16(Bt[n][k], At[m][k], acc[ai][bj][m][n], 0, 0, 0); __builtin_amdgcn_s_setprio(0); } while (0)
; #define PG8_WAIT_V(n) asm volatile("s_waitcnt vmcnt(" #n ")" ::: "memory")
; #define PG8_WAIT_L(n) asm volatile("s_waitcnt lgkmcnt(" #n ")" ::: "memory")
; #define PG8_BAR __builtin_amdgcn_s_barrier()
; #define PG8_SCHED __builtin_amdgcn_sched_barrier(0)
; template <class Epi, class Sched, bool ALIGN_EPI = false, bool SP2 = false>
; __device__ __forceinline__ void gemm_phase(PG8_LAS unsigned char* lds, const Gemm g, const Sched& S, const Epi& E) {
;     ...
;             PG8_LDB(B0, 0, 0); PG8_LDB(B1, 0, 1); PG8_SCHED; PG8_LDA(At, 0, 0); PG8_STAGE(PG8_SA(1, 1), a1 + hstepA, voffA);
;             PG8_WAIT_V(8); PG8_WAIT_L(0); PG8_BAR; PG8_MMA(0, 0, At, B0); PG8_MMA(0, 1, At, B1); PG8_BAR; PG8_SCHED;
;             PG8_LDA(At, 0, 1); PG8_STAGE(PG8_SB(0, 0), b2, voffB); PG8_STAGE(PG8_SB(0, 1), b2 + hstepB, voffB); PG8_STAGE(PG8_SA(0, 0), a2, voffA);
.LBB0_1121:
	v_add_u32_e32 v142, s9, v145
	ds_read_b128 v[138:141], v142
	ds_read_b128 v[148:151], v142 offset:1024
	ds_read_b128 v[152:155], v142 offset:2048
	ds_read_b128 v[156:159], v142 offset:3072
	v_add_u32_e32 v142, s42, v145
	ds_read_b128 v[160:163], v142
	ds_read_b128 v[164:167], v142 offset:1024
	ds_read_b128 v[168:171], v142 offset:2048
	ds_read_b128 v[172:175], v142 offset:3072
	s_add_u32 s2, s28, 0xfffc0080
	s_addc_u32 s30, s29, -1
	s_cmp_eq_u32 s82, 12
	s_cselect_b32 s35, s21, s30
	s_cselect_b32 s34, s27, s2
	s_cselect_b32 s31, s19, s79
	s_cselect_b32 s30, s68, s78
	v_lshl_add_u64 v[142:143], s[28:29], 0, v[136:137]
	s_add_i32 m0, s45, 0xc000
	ds_read_b128 v[176:179], v147
	ds_read_b128 v[180:183], v147 offset:1024
	ds_read_b128 v[184:187], v147 offset:2048
	ds_read_b128 v[188:191], v147 offset:3072
	ds_read_b128 v[204:207], v147 offset:4096
	ds_read_b128 v[208:211], v147 offset:5120
	ds_read_b128 v[218:221], v147 offset:6144
	ds_read_b128 v[222:225], v147 offset:7168
	global_load_lds_dwordx4 v[142:143], off
	v_lshl_add_u64 v[142:143], s[28:29], 0, v[134:135]
	s_add_i32 m0, s45, 0xe000
	s_nop 0
	global_load_lds_dwordx4 v[142:143], off
	s_waitcnt vmcnt(8)
	s_waitcnt lgkmcnt(0)
	s_barrier
	s_waitcnt lgkmcnt(0)
	v_mfma_f32_16x16x32_bf16 v[124:127], v[138:141], v[176:179], v[124:127]
	v_mfma_f32_16x16x32_bf16 v[120:123], v[152:155], v[176:179], v[120:123]
	v_mfma_f32_16x16x32_bf16 v[108:111], v[138:141], v[184:187], v[108:111]
	v_mfma_f32_16x16x32_bf16 v[104:107], v[152:155], v[184:187], v[104:107]
	v_mfma_f32_16x16x32_bf16 v[92:95], v[138:141], v[204:207], v[92:95]
	v_mfma_f32_16x16x32_bf16 v[88:91], v[152:155], v[204:207], v[88:91]
	v_mfma_f32_16x16x32_bf16 v[76:79], v[138:141], v[218:221], v[76:79]
	v_mfma_f32_16x16x32_bf16 v[72:75], v[152:155], v[218:221], v[72:75]
	v_mfma_f32_16x16x32_bf16 v[124:127], v[148:151], v[180:183], v[124:127]
	v_mfma_f32_16x16x32_bf16 v[120:123], v[156:159], v[180:183], v[120:123]
	v_mfma_f32_16x16x32_bf16 v[108:111], v[148:151], v[188:191], v[108:111]
	v_mfma_f32_16x16x32_bf16 v[104:107], v[156:159], v[188:191], v[104:107]
	v_mfma_f32_16x16x32_bf16 v[92:95], v[148:151], v[208:211], v[92:95]
	v_mfma_f32_16x16x32_bf16 v[88:91], v[156:159], v[208:211], v[88:91]
	v_mfma_f32_16x16x32_bf16 v[76:79], v[148:151], v[222:225], v[76:79]
	v_mfma_f32_16x16x32_bf16 v[72:75], v[156:159], v[222:225], v[72:75]
	v_mfma_f32_16x16x32_bf16 v[116:119], v[160:163], v[176:179], v[116:119]
	v_mfma_f32_16x16x32_bf16 v[112:115], v[168:171], v[176:179], v[112:115]
	v_mfma_f32_16x16x32_bf16 v[100:103], v[160:163], v[184:187], v[100:103]
	v_mfma_f32_16x16x32_bf16 v[96:99], v[168:171], v[184:187], v[96:99]
	v_mfma_f32_16x16x32_bf16 v[84:87], v[160:163], v[204:207], v[84:87]
	v_mfma_f32_16x16x32_bf16 v[80:83], v[168:171], v[204:207], v[80:83]
	v_mfma_f32_16x16x32_bf16 v[68:71], v[160:163], v[218:221], v[68:71]
	v_mfma_f32_16x16x32_bf16 v[64:67], v[168:171], v[218:221], v[64:67]
	v_mfma_f32_16x16x32_bf16 v[116:119], v[164:167], v[180:183], v[116:119]
	v_mfma_f32_16x16x32_bf16 v[112:115], v[172:175], v[180:183], v[112:115]
	v_mfma_f32_16x16x32_bf16 v[100:103], v[164:167], v[188:191], v[100:103]
	v_mfma_f32_16x16x32_bf16 v[96:99], v[172:175], v[188:191], v[96:99]
	v_mfma_f32_16x16x32_bf16 v[84:87], v[164:167], v[208:211], v[84:87]
	v_mfma_f32_16x16x32_bf16 v[80:83], v[172:175], v[208:211], v[80:83]
	v_mfma_f32_16x16x32_bf16 v[68:71], v[164:167], v[222:225], v[68:71]
	v_mfma_f32_16x16x32_bf16 v[64:67], v[172:175], v[222:225], v[64:67]
	s_barrier
	s_mov_b32 m0, s40
	v_lshl_add_u64 v[142:143], s[30:31], 0, v[192:193]
	s_add_u32 s84, s30, 0x40000
	ds_read_b128 v[176:179], v147 offset:16384
	ds_read_b128 v[180:183], v147 offset:17408
	ds_read_b128 v[184:187], v147 offset:18432
	ds_read_b128 v[188:191], v147 offset:19456
	ds_read_b128 v[204:207], v147 offset:20480
	ds_read_b128 v[208:211], v147 offset:21504
	ds_read_b128 v[218:221], v147 offset:22528
	ds_read_b128 v[222:225], v147 offset:23552
	global_load_lds_dwordx4 v[142:143], off
	v_lshl_add_u64 v[194:195], s[30:31], 0, v[132:133]
	s_mov_b32 m0, s41
	s_addc_u32 s85, s31, 0
	global_load_lds_dwordx4 v[194:195], off
	v_lshl_add_u64 v[226:227], s[84:85], 0, v[192:193]
	s_mov_b32 m0, s43
	v_lshl_add_u64 v[228:229], s[34:35], 0, v[130:131]
	global_load_lds_dwordx4 v[226:227], off
	v_lshl_add_u64 v[226:227], s[84:85], 0, v[132:133]
	s_mov_b32 m0, s44
	s_nop 0
	global_load_lds_dwordx4 v[226:227], off
	v_lshl_add_u64 v[226:227], s[34:35], 0, v[128:129]
	s_mov_b32 m0, s45
	s_nop 0
	global_load_lds_dwordx4 v[226:227], off
	s_mov_b32 m0, s48
	s_nop 0
	global_load_lds_dwordx4 v[228:229], off
	s_waitcnt vmcnt(8)
	s_waitcnt lgkmcnt(0)
	s_barrier
; #define PG8_STAGE(bufoff, gbase, voff) do { _Pragma("unroll") for (int _i = 0; _i < 2; ++_i) \
;         __builtin_amdgcn_global_load_lds((const unsigned*)((const char*)(gbase) + (voff)[_i]), (PG8_LAS unsigned*)(lds + (bufoff) + ldsw + _i * 8192), 16, 0, 0); } while (0)
; #define PG8_LDA(dst, b, h) do { _Pragma("unroll") for (int m = 0; m < 4; ++m) _Pragma("unroll") for (int k = 0; k < 2; ++k) dst[m][k] = *(const PG8_LAS bf16x8*)(lds + PG8_SA(b, h) + aoff + m * 2048 + k * 1024); } while (0)
; #define PG8_LDB(dst, b, h) do { _Pragma("unroll") for (int n = 0; n < 2; ++n) _Pragma("unroll") for (int k = 0; k < 2; ++k) dst[n][k] = *(const PG8_LAS bf16x8*)(lds + PG8_SB(b, h) + boff + n * 2048 + k * 1024); } while (0)
; #define PG8_MMA(ai, bj, At, Bt) do { __builtin_amdgcn_s_setprio(1); _Pragma("unroll") for (int m = 0; m < 4; ++m) _Pragma("unroll") for (int n = 0; n < 2; ++n) _Pragma("unroll") for (int k = 0; k < 2; ++k) \
;         acc[ai][bj][m][n] = __builtin_amdgcn_mfma_f32_16x16x32_bf16(Bt[n][k], At[m][k], acc[ai][bj][m][n], 0, 0, 0); __builtin_amdgcn_s_setprio(0); } while (0)
; #define PG8_WAIT_V(n) asm volatile("s_waitcnt vmcnt(" #n ")" ::: "memory")
; #define PG8_WAIT_L(n) asm volatile("s_waitcnt lgkmcnt(" #n ")" ::: "memory")
; #define PG8_BAR __builtin_amdgcn_s_barrier()
; #define PG8_SCHED __builtin_amdgcn_sched_barrier(0)
; template <class Epi, class Sched, bool ALIGN_EPI = false, bool SP2 = false>
; __device__ __forceinline__ void gemm_phase(PG8_LAS unsigned char* lds, const Gemm g, const Sched& S, const Epi& E) {
;     ...
;             PG8_WAIT_V(8); PG8_WAIT_L(0); PG8_BAR; PG8_MMA(1, 0, At, B0); PG8_MMA(1, 1, At, B1); PG8_BAR; PG8_SCHED;
;             PG8_LDB(B0, 1, 0); PG8_LDB(B1, 1, 1); PG8_SCHED; PG8_LDA(At, 1, 0); PG8_STAGE(PG8_SA(0, 1), a2 + hstepA, voffA);
;             PG8_WAIT_V(8); PG8_WAIT_L(0); PG8_BAR; PG8_MMA(0, 0, At, B0); PG8_MMA(0, 1, At, B1); PG8_BAR; PG8_SCHED;
	s_waitcnt lgkmcnt(0)
	v_mfma_f32_16x16x32_bf16 v[60:63], v[138:141], v[176:179], v[60:63]
	v_mfma_f32_16x16x32_bf16 v[56:59], v[152:155], v[176:179], v[56:59]
	v_mfma_f32_16x16x32_bf16 v[44:47], v[138:141], v[184:187], v[44:47]
	v_mfma_f32_16x16x32_bf16 v[40:43], v[152:155], v[184:187], v[40:43]
	v_mfma_f32_16x16x32_bf16 v[28:31], v[138:141], v[204:207], v[28:31]
	v_mfma_f32_16x16x32_bf16 v[24:27], v[152:155], v[204:207], v[24:27]
	v_mfma_f32_16x16x32_bf16 v[12:15], v[138:141], v[218:221], v[12:15]
	v_mfma_f32_16x16x32_bf16 v[8:11], v[152:155], v[218:221], v[8:11]
	v_mfma_f32_16x16x32_bf16 v[60:63], v[148:151], v[180:183], v[60:63]
	v_mfma_f32_16x16x32_bf16 v[56:59], v[156:159], v[180:183], v[56:59]
	v_mfma_f32_16x16x32_bf16 v[44:47], v[148:151], v[188:191], v[44:47]
	v_mfma_f32_16x16x32_bf16 v[40:43], v[156:159], v[188:191], v[40:43]
	v_mfma_f32_16x16x32_bf16 v[28:31], v[148:151], v[208:211], v[28:31]
	v_mfma_f32_16x16x32_bf16 v[24:27], v[156:159], v[208:211], v[24:27]
	v_mfma_f32_16x16x32_bf16 v[12:15], v[148:151], v[222:225], v[12:15]
	v_mfma_f32_16x16x32_bf16 v[8:11], v[156:159], v[222:225], v[8:11]
	v_mfma_f32_16x16x32_bf16 v[52:55], v[160:163], v[176:179], v[52:55]
	v_mfma_f32_16x16x32_bf16 v[48:51], v[168:171], v[176:179], v[48:51]
	v_mfma_f32_16x16x32_bf16 v[36:39], v[160:163], v[184:187], v[36:39]
	v_mfma_f32_16x16x32_bf16 v[32:35], v[168:171], v[184:187], v[32:35]
	v_mfma_f32_16x16x32_bf16 v[20:23], v[160:163], v[204:207], v[20:23]
	v_mfma_f32_16x16x32_bf16 v[16:19], v[168:171], v[204:207], v[16:19]
	v_mfma_f32_16x16x32_bf16 v[4:7], v[160:163], v[218:221], v[4:7]
	v_mfma_f32_16x16x32_bf16 v[0:3], v[168:171], v[218:221], v[0:3]
	v_mfma_f32_16x16x32_bf16 v[52:55], v[164:167], v[180:183], v[52:55]
	v_mfma_f32_16x16x32_bf16 v[48:51], v[172:175], v[180:183], v[48:51]
	v_mfma_f32_16x16x32_bf16 v[36:39], v[164:167], v[188:191], v[36:39]
	v_mfma_f32_16x16x32_bf16 v[32:35], v[172:175], v[188:191], v[32:35]
	v_mfma_f32_16x16x32_bf16 v[20:23], v[164:167], v[208:211], v[20:23]
	v_mfma_f32_16x16x32_bf16 v[16:19], v[172:175], v[208:211], v[16:19]
	v_mfma_f32_16x16x32_bf16 v[4:7], v[164:167], v[222:225], v[4:7]
	v_mfma_f32_16x16x32_bf16 v[0:3], v[172:175], v[222:225], v[0:3]
	s_barrier
	v_add_u32_e32 v156, s60, v145
	v_add_u32_e32 v172, s67, v145
	ds_read_b128 v[138:141], v156
	ds_read_b128 v[148:151], v156 offset:1024
	ds_read_b128 v[152:155], v156 offset:2048
	ds_read_b128 v[156:159], v156 offset:3072
	ds_read_b128 v[160:163], v172
	ds_read_b128 v[164:167], v172 offset:1024
	ds_read_b128 v[168:171], v172 offset:2048
	ds_read_b128 v[172:175], v172 offset:3072
	s_add_u32 s34, s34, 0x40000
	s_addc_u32 s35, s35, 0
	s_mov_b32 m0, s49
	v_lshl_add_u64 v[230:231], s[34:35], 0, v[128:129]
	ds_read_b128 v[176:179], v147 offset:32768
	ds_read_b128 v[180:183], v147 offset:33792
	ds_read_b128 v[184:187], v147 offset:34816
	ds_read_b128 v[188:191], v147 offset:35840
	ds_read_b128 v[204:207], v147 offset:36864
	ds_read_b128 v[208:211], v147 offset:37888
	ds_read_b128 v[218:221], v147 offset:38912
	ds_read_b128 v[222:225], v147 offset:39936
	global_load_lds_dwordx4 v[230:231], off
	v_lshl_add_u64 v[230:231], s[34:35], 0, v[130:131]
	s_mov_b32 m0, s50
	s_nop 0
	global_load_lds_dwordx4 v[230:231], off
	s_waitcnt vmcnt(8)
	s_waitcnt lgkmcnt(0)
	s_barrier
	s_waitcnt lgkmcnt(0)
	v_mfma_f32_16x16x32_bf16 v[124:127], v[138:141], v[176:179], v[124:127]
	v_mfma_f32_16x16x32_bf16 v[120:123], v[152:155], v[176:179], v[120:123]
	v_mfma_f32_16x16x32_bf16 v[108:111], v[138:141], v[184:187], v[108:111]
	v_mfma_f32_16x16x32_bf16 v[104:107], v[152:155], v[184:187], v[104:107]
	v_mfma_f32_16x16x32_bf16 v[92:95], v[138:141], v[204:207], v[92:95]
	v_mfma_f32_16x16x32_bf16 v[88:91], v[152:155], v[204:207], v[88:91]
	v_mfma_f32_16x16x32_bf16 v[76:79], v[138:141], v[218:221], v[76:79]
	v_mfma_f32_16x16x32_bf16 v[72:75], v[152:155], v[218:221], v[72:75]
	v_mfma_f32_16x16x32_bf16 v[124:127], v[148:151], v[180:183], v[124:127]
	v_mfma_f32_16x16x32_bf16 v[120:123], v[156:159], v[180:183], v[120:123]
	v_mfma_f32_16x16x32_bf16 v[108:111], v[148:151], v[188:191], v[108:111]
	v_mfma_f32_16x16x32_bf16 v[104:107], v[156:159], v[188:191], v[104:107]
	v_mfma_f32_16x16x32_bf16 v[92:95], v[148:151], v[208:211], v[92:95]
	v_mfma_f32_16x16x32_bf16 v[88:91], v[156:159], v[208:211], v[88:91]
	v_mfma_f32_16x16x32_bf16 v[76:79], v[148:151], v[222:225], v[76:79]
	v_mfma_f32_16x16x32_bf16 v[72:75], v[156:159], v[222:225], v[72:75]
	v_mfma_f32_16x16x32_bf16 v[116:119], v[160:163], v[176:179], v[116:119]
	v_mfma_f32_16x16x32_bf16 v[112:115], v[168:171], v[176:179], v[112:115]
	v_mfma_f32_16x16x32_bf16 v[100:103], v[160:163], v[184:187], v[100:103]
	v_mfma_f32_16x16x32_bf16 v[96:99], v[168:171], v[184:187], v[96:99]
	v_mfma_f32_16x16x32_bf16 v[84:87], v[160:163], v[204:207], v[84:87]
	v_mfma_f32_16x16x32_bf16 v[80:83], v[168:171], v[204:207], v[80:83]
	v_mfma_f32_16x16x32_bf16 v[68:71], v[160:163], v[218:221], v[68:71]
	v_mfma_f32_16x16x32_bf16 v[64:67], v[168:171], v[218:221], v[64:67]
	v_mfma_f32_16x16x32_bf16 v[116:119], v[164:167], v[180:183], v[116:119]
	v_mfma_f32_16x16x32_bf16 v[112:115], v[172:175], v[180:183], v[112:115]
	v_mfma_f32_16x16x32_bf16 v[100:103], v[164:167], v[188:191], v[100:103]
	v_mfma_f32_16x16x32_bf16 v[96:99], v[172:175], v[188:191], v[96:99]
	v_mfma_f32_16x16x32_bf16 v[84:87], v[164:167], v[208:211], v[84:87]
	v_mfma_f32_16x16x32_bf16 v[80:83], v[172:175], v[208:211], v[80:83]
	v_mfma_f32_16x16x32_bf16 v[68:71], v[164:167], v[222:225], v[68:71]
	v_mfma_f32_16x16x32_bf16 v[64:67], v[172:175], v[222:225], v[64:67]
	s_barrier
; #define PG8_STAGE(bufoff, gbase, voff) do { _Pragma("unroll") for (int _i = 0; _i < 2; ++_i) \
;         __builtin_amdgcn_global_load_lds((const unsigned*)((const char*)(gbase) + (voff)[_i]), (PG8_LAS unsigned*)(lds + (bufoff) + ldsw + _i * 8192), 16, 0, 0); } while (0)
; #define PG8_LDA(dst, b, h) do { _Pragma("unroll") for (int m = 0; m < 4; ++m) _Pragma("unroll") for (int k = 0; k < 2; ++k) dst[m][k] = *(const PG8_LAS bf16x8*)(lds + PG8_SA(b, h) + aoff + m * 2048 + k * 1024); } while (0)
; #define PG8_MMA(ai, bj, At, Bt) do { __builtin_amdgcn_s_setprio(1); _Pragma("unroll") for (int m = 0; m < 4; ++m) _Pragma("unroll") for (int n = 0; n < 2; ++n) _Pragma("unroll") for (int k = 0; k < 2; ++k) \
;         acc[ai][bj][m][n] = __builtin_amdgcn_mfma_f32_16x16x32_bf16(Bt[n][k], At[m][k], acc[ai][bj][m][n], 0, 0, 0); __builtin_amdgcn_s_setprio(0); } while (0)
; #define PG8_WAIT_V(n) asm volatile("s_waitcnt vmcnt(" #n ")" ::: "memory")
; #define PG8_WAIT_L(n) asm volatile("s_waitcnt lgkmcnt(" #n ")" ::: "memory")
; #define PG8_BAR __builtin_amdgcn_s_barrier()
; #define PG8_SCHED __builtin_amdgcn_sched_barrier(0)
; template <class Epi, class Sched, bool ALIGN_EPI = false, bool SP2 = false>
; __device__ __forceinline__ void gemm_phase(PG8_LAS unsigned char* lds, const Gemm g, const Sched& S, const Epi& E) {
;     ...
;             PG8_LDA(At, 1, 1); PG8_STAGE(PG8_SB(1, 0), b3, voffB); PG8_STAGE(PG8_SB(1, 1), b3 + hstepB, voffB); PG8_STAGE(PG8_SA(1, 0), a3, voffA);
;             PG8_WAIT_V(8); PG8_WAIT_L(0); PG8_BAR; PG8_MMA(1, 0, At, B0); PG8_MMA(1, 1, At, B1); PG8_BAR; PG8_SCHED;
;     __device__ __forceinline__ void operator()(const f32x4 (&acc)[2][2][4][2], const pg8::Unit& u, int wr, int wc, int fr, int fq) const {
;     ...
;                     const size_t off = (size_t)row * DM + col0 + bj * 128;
;                     const v4u b = *(const v4u*)(xb + off);
	s_mov_b32 m0, s61
	v_lshl_add_u64 v[142:143], v[142:143], 0, s[76:77]
	s_add_u32 s30, s30, 0x40080
	ds_read_b128 v[176:179], v147 offset:49152
	ds_read_b128 v[180:183], v147 offset:50176
	ds_read_b128 v[184:187], v147 offset:51200
	ds_read_b128 v[188:191], v147 offset:52224
	ds_read_b128 v[204:207], v147 offset:53248
	ds_read_b128 v[208:211], v147 offset:54272
	ds_read_b128 v[218:221], v147 offset:55296
	ds_read_b128 v[222:225], v147 offset:56320
	global_load_lds_dwordx4 v[142:143], off
	v_lshl_add_u64 v[142:143], v[194:195], 0, s[76:77]
	s_mov_b32 m0, s64
	s_addc_u32 s31, s31, 0
	global_load_lds_dwordx4 v[142:143], off
	v_lshl_add_u64 v[142:143], s[30:31], 0, v[192:193]
	s_mov_b32 m0, s70
	s_nop 0
	global_load_lds_dwordx4 v[142:143], off
	v_lshl_add_u64 v[142:143], s[30:31], 0, v[132:133]
	s_mov_b32 m0, s71
	s_nop 0
	global_load_lds_dwordx4 v[142:143], off
	v_lshl_add_u64 v[142:143], v[226:227], 0, s[76:77]
	s_mov_b32 m0, s65
	s_nop 0
	global_load_lds_dwordx4 v[142:143], off
	v_lshl_add_u64 v[142:143], v[228:229], 0, s[76:77]
	s_mov_b32 m0, s66
	s_nop 0
	global_load_lds_dwordx4 v[142:143], off
	s_waitcnt vmcnt(8)
	s_waitcnt lgkmcnt(0)
	s_barrier
	s_waitcnt lgkmcnt(0)
	v_mfma_f32_16x16x32_bf16 v[60:63], v[138:141], v[176:179], v[60:63]
	v_mfma_f32_16x16x32_bf16 v[56:59], v[152:155], v[176:179], v[56:59]
	v_mfma_f32_16x16x32_bf16 v[44:47], v[138:141], v[184:187], v[44:47]
	v_mfma_f32_16x16x32_bf16 v[40:43], v[152:155], v[184:187], v[40:43]
	v_mfma_f32_16x16x32_bf16 v[28:31], v[138:141], v[204:207], v[28:31]
	v_mfma_f32_16x16x32_bf16 v[24:27], v[152:155], v[204:207], v[24:27]
	v_mfma_f32_16x16x32_bf16 v[12:15], v[138:141], v[218:221], v[12:15]
	v_mfma_f32_16x16x32_bf16 v[8:11], v[152:155], v[218:221], v[8:11]
	v_mfma_f32_16x16x32_bf16 v[60:63], v[148:151], v[180:183], v[60:63]
	v_mfma_f32_16x16x32_bf16 v[56:59], v[156:159], v[180:183], v[56:59]
	v_mfma_f32_16x16x32_bf16 v[44:47], v[148:151], v[188:191], v[44:47]
	v_mfma_f32_16x16x32_bf16 v[40:43], v[156:159], v[188:191], v[40:43]
	v_mfma_f32_16x16x32_bf16 v[28:31], v[148:151], v[208:211], v[28:31]
	v_mfma_f32_16x16x32_bf16 v[24:27], v[156:159], v[208:211], v[24:27]
	v_mfma_f32_16x16x32_bf16 v[12:15], v[148:151], v[222:225], v[12:15]
	v_mfma_f32_16x16x32_bf16 v[8:11], v[156:159], v[222:225], v[8:11]
	v_mfma_f32_16x16x32_bf16 v[52:55], v[160:163], v[176:179], v[52:55]
	v_mfma_f32_16x16x32_bf16 v[48:51], v[168:171], v[176:179], v[48:51]
	v_mfma_f32_16x16x32_bf16 v[36:39], v[160:163], v[184:187], v[36:39]
	v_mfma_f32_16x16x32_bf16 v[32:35], v[168:171], v[184:187], v[32:35]
	v_mfma_f32_16x16x32_bf16 v[20:23], v[160:163], v[204:207], v[20:23]
	v_mfma_f32_16x16x32_bf16 v[16:19], v[168:171], v[204:207], v[16:19]
	v_mfma_f32_16x16x32_bf16 v[4:7], v[160:163], v[218:221], v[4:7]
	v_mfma_f32_16x16x32_bf16 v[0:3], v[168:171], v[218:221], v[0:3]
	v_mfma_f32_16x16x32_bf16 v[52:55], v[164:167], v[180:183], v[52:55]
	v_mfma_f32_16x16x32_bf16 v[48:51], v[172:175], v[180:183], v[48:51]
	v_mfma_f32_16x16x32_bf16 v[36:39], v[164:167], v[188:191], v[36:39]
	v_mfma_f32_16x16x32_bf16 v[32:35], v[172:175], v[188:191], v[32:35]
	v_mfma_f32_16x16x32_bf16 v[20:23], v[164:167], v[208:211], v[20:23]
	v_mfma_f32_16x16x32_bf16 v[16:19], v[172:175], v[208:211], v[16:19]
	v_mfma_f32_16x16x32_bf16 v[4:7], v[164:167], v[222:225], v[4:7]
	v_mfma_f32_16x16x32_bf16 v[0:3], v[172:175], v[222:225], v[0:3]
	s_barrier
	s_add_i32 s82, s82, 2
	s_add_u32 s78, s78, 0x100
	s_addc_u32 s79, s79, 0
	s_add_u32 s28, s28, 0x100
	s_addc_u32 s29, s29, 0
	s_cmp_gt_u32 s82, 13
	s_cbranch_scc0 .LBB0_1121
	v_lshl_add_u32 v159, s26, 8, v144
	v_lshl_or_b32 v158, s8, 8, v146
	v_lshlrev_b32_e32 v159, 11, v159
	v_lshl_add_u32 v159, v158, 1, v159
	v_add_u32_e32 v218, 0x8000, v159
	v_add_u32_e32 v219, 0x10000, v159
	v_add_u32_e32 v240, 0x18000, v159
	v_add_u32_e32 v241, 0x40000, v159
	v_add_u32_e32 v245, 0x48000, v159
	v_add_u32_e32 v246, 0x50000, v159
	v_add_u32_e32 v247, 0x58000, v159
	global_load_dwordx4 v[160:163], v159, s[12:13]
	global_load_dwordx4 v[164:167], v159, s[12:13] offset:256
	global_load_dwordx4 v[168:171], v218, s[12:13]
	global_load_dwordx4 v[172:175], v218, s[12:13] offset:256
	global_load_dwordx4 v[176:179], v219, s[12:13]
	global_load_dwordx4 v[180:183], v219, s[12:13] offset:256
	global_load_dwordx4 v[184:187], v240, s[12:13]
	global_load_dwordx4 v[188:191], v240, s[12:13] offset:256
	global_load_dwordx4 v[204:207], v241, s[12:13]
	global_load_dwordx4 v[208:211], v241, s[12:13] offset:256
	global_load_dwordx4 v[220:223], v245, s[12:13]
	global_load_dwordx4 v[224:227], v245, s[12:13] offset:256
	global_load_dwordx4 v[228:231], v246, s[12:13]
	global_load_dwordx4 v[232:235], v246, s[12:13] offset:256
	global_load_dwordx4 v[236:239], v247, s[12:13]
	global_load_dwordx4 v[248:251], v247, s[12:13] offset:256
	s_and_b64 vcc, exec, s[16:17]
	s_cbranch_vccz .LBB0_1124
	s_barrier

; #define PG8_STAGE(bufoff, gbase, voff) do { _Pragma("unroll") for (int _i = 0; _i < 2; ++_i) \
;         __builtin_amdgcn_global_load_lds((const unsigned*)((const char*)(gbase) + (voff)[_i]), (PG8_LAS unsigned*)(lds + (bufoff) + ldsw + _i * 8192), 16, 0, 0); } while (0)
; #define PG8_LDA(dst, b, h) do { _Pragma("unroll") for (int m = 0; m < 4; ++m) _Pragma("unroll") for (int k = 0; k < 2; ++k) dst[m][k] = *(const PG8_LAS bf16x8*)(lds + PG8_SA(b, h) + aoff + m * 2048 + k * 1024); } while (0)
; #define PG8_LDB(dst, b, h) do { _Pragma("unroll") for (int n = 0; n < 2; ++n) _Pragma("unroll") for (int k = 0; k < 2; ++k) dst[n][k] = *(const PG8_LAS bf16x8*)(lds + PG8_SB(b, h) + boff + n * 2048 + k * 1024); } while (0)
; #define PG8_MMA(ai, bj, At, Bt) do { __builtin_amdgcn_s_setprio(1); _Pragma("unroll") for (int m = 0; m < 4; ++m) _Pragma("unroll") for (int n = 0; n < 2; ++n) _Pragma("unroll") for (int k = 0; k < 2; ++k) \
;         acc[ai][bj][m][n] = __builtin_amdgcn_mfma_f32_16x16x32_bf16(Bt[n][k], At[m][k], acc[ai][bj][m][n], 0, 0, 0); __builtin_amdgcn_s_setprio(0); } while (0)
; #define PG8_WAIT_V(n) asm volatile("s_waitcnt vmcnt(" #n ")" ::: "memory")
; #define PG8_WAIT_L(n) asm volatile("s_waitcnt lgkmcnt(" #n ")" ::: "memory")
; #define PG8_BAR __builtin_amdgcn_s_barrier()
; #define PG8_SCHED __builtin_amdgcn_sched_barrier(0)
; template <class Epi, class Sched, bool ALIGN_EPI = false, bool SP2 = false>
; __device__ __forceinline__ void gemm_phase(PG8_LAS unsigned char* lds, const Gemm g, const Sched& S, const Epi& E) {
;     ...
;             PG8_LDB(B0, 0, 0); PG8_LDB(B1, 0, 1); PG8_SCHED; PG8_LDA(At, 0, 0); PG8_STAGE(PG8_SA(1, 1), a1 + hstepA, voffA);
;             PG8_WAIT_V(8); PG8_WAIT_L(0); PG8_BAR; PG8_MMA(0, 0, At, B0); PG8_MMA(0, 1, At, B1); PG8_BAR; PG8_SCHED;
;             PG8_LDA(At, 0, 1); PG8_STAGE(PG8_SB(0, 0), b2, voffB); PG8_STAGE(PG8_SB(0, 1), b2 + hstepB, voffB); PG8_STAGE(PG8_SA(0, 0), a2, voffA);
.LBB0_1221:
	v_add_u32_e32 v156, s21, v149
	v_add_u32_e32 v172, s37, v149
	ds_read_b128 v[140:143], v156
	ds_read_b128 v[144:147], v156 offset:1024
	ds_read_b128 v[152:155], v156 offset:2048
	ds_read_b128 v[156:159], v156 offset:3072
	ds_read_b128 v[160:163], v172
	ds_read_b128 v[164:167], v172 offset:1024
	ds_read_b128 v[168:171], v172 offset:2048
	ds_read_b128 v[172:175], v172 offset:3072
	s_add_u32 s2, s22, 0xfffc0080
	s_addc_u32 s24, s23, -1
	s_cmp_eq_u32 s72, 12
	s_cselect_b32 s27, s15, s24
	s_cselect_b32 s26, s67, s2
	s_cselect_b32 s25, s13, s71
	s_cselect_b32 s24, s68, s70
	v_lshl_add_u64 v[194:195], s[22:23], 0, v[138:139]
	s_add_i32 m0, s40, 0xc000
	ds_read_b128 v[176:179], v151
	ds_read_b128 v[180:183], v151 offset:1024
	ds_read_b128 v[184:187], v151 offset:2048
	ds_read_b128 v[188:191], v151 offset:3072
	ds_read_b128 v[204:207], v151 offset:4096
	ds_read_b128 v[208:211], v151 offset:5120
	ds_read_b128 v[218:221], v151 offset:6144
	ds_read_b128 v[222:225], v151 offset:7168
	global_load_lds_dwordx4 v[194:195], off
	v_lshl_add_u64 v[194:195], s[22:23], 0, v[136:137]
	s_add_i32 m0, s40, 0xe000
	s_nop 0
	global_load_lds_dwordx4 v[194:195], off
	s_waitcnt vmcnt(8)
	s_waitcnt lgkmcnt(0)
	s_barrier
	s_waitcnt lgkmcnt(0)
	v_mfma_f32_16x16x32_bf16 v[116:119], v[140:143], v[176:179], v[116:119]
	v_mfma_f32_16x16x32_bf16 v[112:115], v[152:155], v[176:179], v[112:115]
	v_mfma_f32_16x16x32_bf16 v[108:111], v[140:143], v[184:187], v[108:111]
	v_mfma_f32_16x16x32_bf16 v[104:107], v[152:155], v[184:187], v[104:107]
	v_mfma_f32_16x16x32_bf16 v[92:95], v[140:143], v[204:207], v[92:95]
	v_mfma_f32_16x16x32_bf16 v[88:91], v[152:155], v[204:207], v[88:91]
	v_mfma_f32_16x16x32_bf16 v[76:79], v[140:143], v[218:221], v[76:79]
	v_mfma_f32_16x16x32_bf16 v[72:75], v[152:155], v[218:221], v[72:75]
	v_mfma_f32_16x16x32_bf16 v[116:119], v[144:147], v[180:183], v[116:119]
	v_mfma_f32_16x16x32_bf16 v[112:115], v[156:159], v[180:183], v[112:115]
	v_mfma_f32_16x16x32_bf16 v[108:111], v[144:147], v[188:191], v[108:111]
	v_mfma_f32_16x16x32_bf16 v[104:107], v[156:159], v[188:191], v[104:107]
	v_mfma_f32_16x16x32_bf16 v[92:95], v[144:147], v[208:211], v[92:95]
	v_mfma_f32_16x16x32_bf16 v[88:91], v[156:159], v[208:211], v[88:91]
	v_mfma_f32_16x16x32_bf16 v[76:79], v[144:147], v[222:225], v[76:79]
	v_mfma_f32_16x16x32_bf16 v[72:75], v[156:159], v[222:225], v[72:75]
	v_mfma_f32_16x16x32_bf16 v[124:127], v[160:163], v[176:179], v[124:127]
	v_mfma_f32_16x16x32_bf16 v[120:123], v[168:171], v[176:179], v[120:123]
	v_mfma_f32_16x16x32_bf16 v[100:103], v[160:163], v[184:187], v[100:103]
	v_mfma_f32_16x16x32_bf16 v[96:99], v[168:171], v[184:187], v[96:99]
	v_mfma_f32_16x16x32_bf16 v[84:87], v[160:163], v[204:207], v[84:87]
	v_mfma_f32_16x16x32_bf16 v[80:83], v[168:171], v[204:207], v[80:83]
	v_mfma_f32_16x16x32_bf16 v[68:71], v[160:163], v[218:221], v[68:71]
	v_mfma_f32_16x16x32_bf16 v[64:67], v[168:171], v[218:221], v[64:67]
	v_mfma_f32_16x16x32_bf16 v[124:127], v[164:167], v[180:183], v[124:127]
	v_mfma_f32_16x16x32_bf16 v[120:123], v[172:175], v[180:183], v[120:123]
	v_mfma_f32_16x16x32_bf16 v[100:103], v[164:167], v[188:191], v[100:103]
	v_mfma_f32_16x16x32_bf16 v[96:99], v[172:175], v[188:191], v[96:99]
	v_mfma_f32_16x16x32_bf16 v[84:87], v[164:167], v[208:211], v[84:87]
	v_mfma_f32_16x16x32_bf16 v[80:83], v[172:175], v[208:211], v[80:83]
	v_mfma_f32_16x16x32_bf16 v[68:71], v[164:167], v[222:225], v[68:71]
	v_mfma_f32_16x16x32_bf16 v[64:67], v[172:175], v[222:225], v[64:67]
	s_barrier
	s_mov_b32 m0, s35
	v_lshl_add_u64 v[194:195], s[24:25], 0, v[192:193]
	s_add_u32 s74, s24, 0x40000
	ds_read_b128 v[176:179], v151 offset:16384
	ds_read_b128 v[180:183], v151 offset:17408
	ds_read_b128 v[184:187], v151 offset:18432
	ds_read_b128 v[188:191], v151 offset:19456
	ds_read_b128 v[204:207], v151 offset:20480
	ds_read_b128 v[208:211], v151 offset:21504
	ds_read_b128 v[218:221], v151 offset:22528
	ds_read_b128 v[222:225], v151 offset:23552
	global_load_lds_dwordx4 v[194:195], off
	v_lshl_add_u64 v[226:227], s[24:25], 0, v[128:129]
	s_mov_b32 m0, s36
	s_addc_u32 s75, s25, 0
	global_load_lds_dwordx4 v[226:227], off
	v_lshl_add_u64 v[228:229], s[74:75], 0, v[192:193]
	s_mov_b32 m0, s38
	v_lshl_add_u64 v[230:231], s[26:27], 0, v[130:131]
	global_load_lds_dwordx4 v[228:229], off
	v_lshl_add_u64 v[228:229], s[74:75], 0, v[128:129]
	s_mov_b32 m0, s39
	s_nop 0
	global_load_lds_dwordx4 v[228:229], off
	v_lshl_add_u64 v[228:229], s[26:27], 0, v[132:133]
	s_mov_b32 m0, s40
	s_nop 0
	global_load_lds_dwordx4 v[228:229], off
	s_mov_b32 m0, s41
	s_nop 0
	global_load_lds_dwordx4 v[230:231], off
	s_waitcnt vmcnt(8)
	s_waitcnt lgkmcnt(0)
	s_barrier
; #define PG8_STAGE(bufoff, gbase, voff) do { _Pragma("unroll") for (int _i = 0; _i < 2; ++_i) \
;         __builtin_amdgcn_global_load_lds((const unsigned*)((const char*)(gbase) + (voff)[_i]), (PG8_LAS unsigned*)(lds + (bufoff) + ldsw + _i * 8192), 16, 0, 0); } while (0)
; #define PG8_LDA(dst, b, h) do { _Pragma("unroll") for (int m = 0; m < 4; ++m) _Pragma("unroll") for (int k = 0; k < 2; ++k) dst[m][k] = *(const PG8_LAS bf16x8*)(lds + PG8_SA(b, h) + aoff + m * 2048 + k * 1024); } while (0)
; #define PG8_LDB(dst, b, h) do { _Pragma("unroll") for (int n = 0; n < 2; ++n) _Pragma("unroll") for (int k = 0; k < 2; ++k) dst[n][k] = *(const PG8_LAS bf16x8*)(lds + PG8_SB(b, h) + boff + n * 2048 + k * 1024); } while (0)
; #define PG8_MMA(ai, bj, At, Bt) do { __builtin_amdgcn_s_setprio(1); _Pragma("unroll") for (int m = 0; m < 4; ++m) _Pragma("unroll") for (int n = 0; n < 2; ++n) _Pragma("unroll") for (int k = 0; k < 2; ++k) \
;         acc[ai][bj][m][n] = __builtin_amdgcn_mfma_f32_16x16x32_bf16(Bt[n][k], At[m][k], acc[ai][bj][m][n], 0, 0, 0); __builtin_amdgcn_s_setprio(0); } while (0)
; #define PG8_WAIT_V(n) asm volatile("s_waitcnt vmcnt(" #n ")" ::: "memory")
; #define PG8_WAIT_L(n) asm volatile("s_waitcnt lgkmcnt(" #n ")" ::: "memory")
; #define PG8_BAR __builtin_amdgcn_s_barrier()
; #define PG8_SCHED __builtin_amdgcn_sched_barrier(0)
; template <class Epi, class Sched, bool ALIGN_EPI = false, bool SP2 = false>
; __device__ __forceinline__ void gemm_phase(PG8_LAS unsigned char* lds, const Gemm g, const Sched& S, const Epi& E) {
;     ...
;             PG8_WAIT_V(8); PG8_WAIT_L(0); PG8_BAR; PG8_MMA(1, 0, At, B0); PG8_MMA(1, 1, At, B1); PG8_BAR; PG8_SCHED;
;             PG8_LDB(B0, 1, 0); PG8_LDB(B1, 1, 1); PG8_SCHED; PG8_LDA(At, 1, 0); PG8_STAGE(PG8_SA(0, 1), a2 + hstepA, voffA);
;             PG8_WAIT_V(8); PG8_WAIT_L(0); PG8_BAR; PG8_MMA(0, 0, At, B0); PG8_MMA(0, 1, At, B1); PG8_BAR; PG8_SCHED;
	s_waitcnt lgkmcnt(0)
	v_mfma_f32_16x16x32_bf16 v[60:63], v[140:143], v[176:179], v[60:63]
	v_mfma_f32_16x16x32_bf16 v[56:59], v[152:155], v[176:179], v[56:59]
	v_mfma_f32_16x16x32_bf16 v[44:47], v[140:143], v[184:187], v[44:47]
	v_mfma_f32_16x16x32_bf16 v[40:43], v[152:155], v[184:187], v[40:43]
	v_mfma_f32_16x16x32_bf16 v[28:31], v[140:143], v[204:207], v[28:31]
	v_mfma_f32_16x16x32_bf16 v[24:27], v[152:155], v[204:207], v[24:27]
	v_mfma_f32_16x16x32_bf16 v[12:15], v[140:143], v[218:221], v[12:15]
	v_mfma_f32_16x16x32_bf16 v[8:11], v[152:155], v[218:221], v[8:11]
	v_mfma_f32_16x16x32_bf16 v[60:63], v[144:147], v[180:183], v[60:63]
	v_mfma_f32_16x16x32_bf16 v[56:59], v[156:159], v[180:183], v[56:59]
	v_mfma_f32_16x16x32_bf16 v[44:47], v[144:147], v[188:191], v[44:47]
	v_mfma_f32_16x16x32_bf16 v[40:43], v[156:159], v[188:191], v[40:43]
	v_mfma_f32_16x16x32_bf16 v[28:31], v[144:147], v[208:211], v[28:31]
	v_mfma_f32_16x16x32_bf16 v[24:27], v[156:159], v[208:211], v[24:27]
	v_mfma_f32_16x16x32_bf16 v[12:15], v[144:147], v[222:225], v[12:15]
	v_mfma_f32_16x16x32_bf16 v[8:11], v[156:159], v[222:225], v[8:11]
	v_mfma_f32_16x16x32_bf16 v[52:55], v[160:163], v[176:179], v[52:55]
	v_mfma_f32_16x16x32_bf16 v[48:51], v[168:171], v[176:179], v[48:51]
	v_mfma_f32_16x16x32_bf16 v[36:39], v[160:163], v[184:187], v[36:39]
	v_mfma_f32_16x16x32_bf16 v[32:35], v[168:171], v[184:187], v[32:35]
	v_mfma_f32_16x16x32_bf16 v[20:23], v[160:163], v[204:207], v[20:23]
	v_mfma_f32_16x16x32_bf16 v[16:19], v[168:171], v[204:207], v[16:19]
	v_mfma_f32_16x16x32_bf16 v[4:7], v[160:163], v[218:221], v[4:7]
	v_mfma_f32_16x16x32_bf16 v[0:3], v[168:171], v[218:221], v[0:3]
	v_mfma_f32_16x16x32_bf16 v[52:55], v[164:167], v[180:183], v[52:55]
	v_mfma_f32_16x16x32_bf16 v[48:51], v[172:175], v[180:183], v[48:51]
	v_mfma_f32_16x16x32_bf16 v[36:39], v[164:167], v[188:191], v[36:39]
	v_mfma_f32_16x16x32_bf16 v[32:35], v[172:175], v[188:191], v[32:35]
	v_mfma_f32_16x16x32_bf16 v[20:23], v[164:167], v[208:211], v[20:23]
	v_mfma_f32_16x16x32_bf16 v[16:19], v[172:175], v[208:211], v[16:19]
	v_mfma_f32_16x16x32_bf16 v[4:7], v[164:167], v[222:225], v[4:7]
	v_mfma_f32_16x16x32_bf16 v[0:3], v[172:175], v[222:225], v[0:3]
	s_barrier
	v_add_u32_e32 v156, s44, v149
	v_add_u32_e32 v172, s51, v149
	ds_read_b128 v[140:143], v156
	ds_read_b128 v[144:147], v156 offset:1024
	ds_read_b128 v[152:155], v156 offset:2048
	ds_read_b128 v[156:159], v156 offset:3072
	ds_read_b128 v[160:163], v172
	ds_read_b128 v[164:167], v172 offset:1024
	ds_read_b128 v[168:171], v172 offset:2048
	ds_read_b128 v[172:175], v172 offset:3072
	s_add_u32 s26, s26, 0x40000
	s_addc_u32 s27, s27, 0
	s_mov_b32 m0, s42
	v_lshl_add_u64 v[232:233], s[26:27], 0, v[132:133]
	ds_read_b128 v[176:179], v151 offset:32768
	ds_read_b128 v[180:183], v151 offset:33792
	ds_read_b128 v[184:187], v151 offset:34816
	ds_read_b128 v[188:191], v151 offset:35840
	ds_read_b128 v[204:207], v151 offset:36864
	ds_read_b128 v[208:211], v151 offset:37888
	ds_read_b128 v[218:221], v151 offset:38912
	ds_read_b128 v[222:225], v151 offset:39936
	global_load_lds_dwordx4 v[232:233], off
	v_lshl_add_u64 v[232:233], s[26:27], 0, v[130:131]
	s_mov_b32 m0, s43
	s_nop 0
	global_load_lds_dwordx4 v[232:233], off
	s_waitcnt vmcnt(8)
	s_waitcnt lgkmcnt(0)
	s_barrier
	s_waitcnt lgkmcnt(0)
	v_mfma_f32_16x16x32_bf16 v[116:119], v[140:143], v[176:179], v[116:119]
	v_mfma_f32_16x16x32_bf16 v[112:115], v[152:155], v[176:179], v[112:115]
	v_mfma_f32_16x16x32_bf16 v[108:111], v[140:143], v[184:187], v[108:111]
	v_mfma_f32_16x16x32_bf16 v[104:107], v[152:155], v[184:187], v[104:107]
	v_mfma_f32_16x16x32_bf16 v[92:95], v[140:143], v[204:207], v[92:95]
	v_mfma_f32_16x16x32_bf16 v[88:91], v[152:155], v[204:207], v[88:91]
	v_mfma_f32_16x16x32_bf16 v[76:79], v[140:143], v[218:221], v[76:79]
	v_mfma_f32_16x16x32_bf16 v[72:75], v[152:155], v[218:221], v[72:75]
	v_mfma_f32_16x16x32_bf16 v[116:119], v[144:147], v[180:183], v[116:119]
	v_mfma_f32_16x16x32_bf16 v[112:115], v[156:159], v[180:183], v[112:115]
	v_mfma_f32_16x16x32_bf16 v[108:111], v[144:147], v[188:191], v[108:111]
	v_mfma_f32_16x16x32_bf16 v[104:107], v[156:159], v[188:191], v[104:107]
	v_mfma_f32_16x16x32_bf16 v[92:95], v[144:147], v[208:211], v[92:95]
	v_mfma_f32_16x16x32_bf16 v[88:91], v[156:159], v[208:211], v[88:91]
	v_mfma_f32_16x16x32_bf16 v[76:79], v[144:147], v[222:225], v[76:79]
	v_mfma_f32_16x16x32_bf16 v[72:75], v[156:159], v[222:225], v[72:75]
	v_mfma_f32_16x16x32_bf16 v[124:127], v[160:163], v[176:179], v[124:127]
	v_mfma_f32_16x16x32_bf16 v[120:123], v[168:171], v[176:179], v[120:123]
	v_mfma_f32_16x16x32_bf16 v[100:103], v[160:163], v[184:187], v[100:103]
	v_mfma_f32_16x16x32_bf16 v[96:99], v[168:171], v[184:187], v[96:99]
	v_mfma_f32_16x16x32_bf16 v[84:87], v[160:163], v[204:207], v[84:87]
	v_mfma_f32_16x16x32_bf16 v[80:83], v[168:171], v[204:207], v[80:83]
	v_mfma_f32_16x16x32_bf16 v[68:71], v[160:163], v[218:221], v[68:71]
	v_mfma_f32_16x16x32_bf16 v[64:67], v[168:171], v[218:221], v[64:67]
	v_mfma_f32_16x16x32_bf16 v[124:127], v[164:167], v[180:183], v[124:127]
	v_mfma_f32_16x16x32_bf16 v[120:123], v[172:175], v[180:183], v[120:123]
	v_mfma_f32_16x16x32_bf16 v[100:103], v[164:167], v[188:191], v[100:103]
	v_mfma_f32_16x16x32_bf16 v[96:99], v[172:175], v[188:191], v[96:99]
	v_mfma_f32_16x16x32_bf16 v[84:87], v[164:167], v[208:211], v[84:87]
	v_mfma_f32_16x16x32_bf16 v[80:83], v[172:175], v[208:211], v[80:83]
	v_mfma_f32_16x16x32_bf16 v[68:71], v[164:167], v[222:225], v[68:71]
	v_mfma_f32_16x16x32_bf16 v[64:67], v[172:175], v[222:225], v[64:67]
	s_barrier
; #define PG8_STAGE(bufoff, gbase, voff) do { _Pragma("unroll") for (int _i = 0; _i < 2; ++_i) \
;         __builtin_amdgcn_global_load_lds((const unsigned*)((const char*)(gbase) + (voff)[_i]), (PG8_LAS unsigned*)(lds + (bufoff) + ldsw + _i * 8192), 16, 0, 0); } while (0)
; #define PG8_LDA(dst, b, h) do { _Pragma("unroll") for (int m = 0; m < 4; ++m) _Pragma("unroll") for (int k = 0; k < 2; ++k) dst[m][k] = *(const PG8_LAS bf16x8*)(lds + PG8_SA(b, h) + aoff + m * 2048 + k * 1024); } while (0)
; #define PG8_MMA(ai, bj, At, Bt) do { __builtin_amdgcn_s_setprio(1); _Pragma("unroll") for (int m = 0; m < 4; ++m) _Pragma("unroll") for (int n = 0; n < 2; ++n) _Pragma("unroll") for (int k = 0; k < 2; ++k) \
;         acc[ai][bj][m][n] = __builtin_amdgcn_mfma_f32_16x16x32_bf16(Bt[n][k], At[m][k], acc[ai][bj][m][n], 0, 0, 0); __builtin_amdgcn_s_setprio(0); } while (0)
; #define PG8_WAIT_V(n) asm volatile("s_waitcnt vmcnt(" #n ")" ::: "memory")
; #define PG8_WAIT_L(n) asm volatile("s_waitcnt lgkmcnt(" #n ")" ::: "memory")
; #define PG8_BAR __builtin_amdgcn_s_barrier()
; #define PG8_SCHED __builtin_amdgcn_sched_barrier(0)
; template <class Epi, class Sched, bool ALIGN_EPI = false, bool SP2 = false>
; __device__ __forceinline__ void gemm_phase(PG8_LAS unsigned char* lds, const Gemm g, const Sched& S, const Epi& E) {
;     ...
;             PG8_LDA(At, 1, 1); PG8_STAGE(PG8_SB(1, 0), b3, voffB); PG8_STAGE(PG8_SB(1, 1), b3 + hstepB, voffB); PG8_STAGE(PG8_SA(1, 0), a3, voffA);
;             PG8_WAIT_V(8); PG8_WAIT_L(0); PG8_BAR; PG8_MMA(1, 0, At, B0); PG8_MMA(1, 1, At, B1); PG8_BAR; PG8_SCHED;
;     ...
;         if constexpr (ALIGN_EPI) { if (wr == 0) PG8_BAR; }
	s_mov_b32 m0, s45
	v_lshl_add_u64 v[194:195], v[194:195], 0, s[76:77]
	s_add_u32 s24, s24, 0x40080
	ds_read_b128 v[176:179], v151 offset:49152
	ds_read_b128 v[180:183], v151 offset:50176
	ds_read_b128 v[184:187], v151 offset:51200
	ds_read_b128 v[188:191], v151 offset:52224
	ds_read_b128 v[204:207], v151 offset:53248
	ds_read_b128 v[208:211], v151 offset:54272
	ds_read_b128 v[218:221], v151 offset:55296
	ds_read_b128 v[222:225], v151 offset:56320
	global_load_lds_dwordx4 v[194:195], off
	v_lshl_add_u64 v[194:195], v[226:227], 0, s[76:77]
	s_mov_b32 m0, s48
	s_addc_u32 s25, s25, 0
	global_load_lds_dwordx4 v[194:195], off
	v_lshl_add_u64 v[194:195], s[24:25], 0, v[192:193]
	s_mov_b32 m0, s60
	s_nop 0
	global_load_lds_dwordx4 v[194:195], off
	v_lshl_add_u64 v[194:195], s[24:25], 0, v[128:129]
	s_mov_b32 m0, s61
	s_nop 0
	global_load_lds_dwordx4 v[194:195], off
	v_lshl_add_u64 v[194:195], v[228:229], 0, s[76:77]
	s_mov_b32 m0, s49
	s_nop 0
	global_load_lds_dwordx4 v[194:195], off
	v_lshl_add_u64 v[194:195], v[230:231], 0, s[76:77]
	s_mov_b32 m0, s50
	s_nop 0
	global_load_lds_dwordx4 v[194:195], off
	s_waitcnt vmcnt(8)
	s_waitcnt lgkmcnt(0)
	s_barrier
	s_waitcnt lgkmcnt(0)
	v_mfma_f32_16x16x32_bf16 v[60:63], v[140:143], v[176:179], v[60:63]
	v_mfma_f32_16x16x32_bf16 v[56:59], v[152:155], v[176:179], v[56:59]
	v_mfma_f32_16x16x32_bf16 v[44:47], v[140:143], v[184:187], v[44:47]
	v_mfma_f32_16x16x32_bf16 v[40:43], v[152:155], v[184:187], v[40:43]
	v_mfma_f32_16x16x32_bf16 v[28:31], v[140:143], v[204:207], v[28:31]
	v_mfma_f32_16x16x32_bf16 v[24:27], v[152:155], v[204:207], v[24:27]
	v_mfma_f32_16x16x32_bf16 v[12:15], v[140:143], v[218:221], v[12:15]
	v_mfma_f32_16x16x32_bf16 v[8:11], v[152:155], v[218:221], v[8:11]
	v_mfma_f32_16x16x32_bf16 v[60:63], v[144:147], v[180:183], v[60:63]
	v_mfma_f32_16x16x32_bf16 v[56:59], v[156:159], v[180:183], v[56:59]
	v_mfma_f32_16x16x32_bf16 v[44:47], v[144:147], v[188:191], v[44:47]
	v_mfma_f32_16x16x32_bf16 v[40:43], v[156:159], v[188:191], v[40:43]
	v_mfma_f32_16x16x32_bf16 v[28:31], v[144:147], v[208:211], v[28:31]
	v_mfma_f32_16x16x32_bf16 v[24:27], v[156:159], v[208:211], v[24:27]
	v_mfma_f32_16x16x32_bf16 v[12:15], v[144:147], v[222:225], v[12:15]
	v_mfma_f32_16x16x32_bf16 v[8:11], v[156:159], v[222:225], v[8:11]
	v_mfma_f32_16x16x32_bf16 v[52:55], v[160:163], v[176:179], v[52:55]
	v_mfma_f32_16x16x32_bf16 v[48:51], v[168:171], v[176:179], v[48:51]
	v_mfma_f32_16x16x32_bf16 v[36:39], v[160:163], v[184:187], v[36:39]
	v_mfma_f32_16x16x32_bf16 v[32:35], v[168:171], v[184:187], v[32:35]
	v_mfma_f32_16x16x32_bf16 v[20:23], v[160:163], v[204:207], v[20:23]
	v_mfma_f32_16x16x32_bf16 v[16:19], v[168:171], v[204:207], v[16:19]
	v_mfma_f32_16x16x32_bf16 v[4:7], v[160:163], v[218:221], v[4:7]
	v_mfma_f32_16x16x32_bf16 v[0:3], v[168:171], v[218:221], v[0:3]
	v_mfma_f32_16x16x32_bf16 v[52:55], v[164:167], v[180:183], v[52:55]
	v_mfma_f32_16x16x32_bf16 v[48:51], v[172:175], v[180:183], v[48:51]
	v_mfma_f32_16x16x32_bf16 v[36:39], v[164:167], v[188:191], v[36:39]
	v_mfma_f32_16x16x32_bf16 v[32:35], v[172:175], v[188:191], v[32:35]
	v_mfma_f32_16x16x32_bf16 v[20:23], v[164:167], v[208:211], v[20:23]
	v_mfma_f32_16x16x32_bf16 v[16:19], v[172:175], v[208:211], v[16:19]
	v_mfma_f32_16x16x32_bf16 v[4:7], v[164:167], v[222:225], v[4:7]
	v_mfma_f32_16x16x32_bf16 v[0:3], v[172:175], v[222:225], v[0:3]
	s_barrier
	s_add_i32 s72, s72, 2
	s_add_u32 s70, s70, 0x100
	s_addc_u32 s71, s71, 0
	s_add_u32 s22, s22, 0x100
	s_addc_u32 s23, s23, 0
	s_cmp_gt_u32 s72, 13
	s_cbranch_scc0 .LBB0_1221
	s_and_b64 vcc, exec, s[10:11]
	s_cbranch_vccz .LBB0_1224
	s_barrier

; #define PG8_STAGE(bufoff, gbase, voff) do { _Pragma("unroll") for (int _i = 0; _i < 2; ++_i) \
;         __builtin_amdgcn_global_load_lds((const unsigned*)((const char*)(gbase) + (voff)[_i]), (PG8_LAS unsigned*)(lds + (bufoff) + ldsw + _i * 8192), 16, 0, 0); } while (0)
; #define PG8_LDA(dst, b, h) do { _Pragma("unroll") for (int m = 0; m < 4; ++m) _Pragma("unroll") for (int k = 0; k < 2; ++k) dst[m][k] = *(const PG8_LAS bf16x8*)(lds + PG8_SA(b, h) + aoff + m * 2048 + k * 1024); } while (0)
; #define PG8_LDB(dst, b, h) do { _Pragma("unroll") for (int n = 0; n < 2; ++n) _Pragma("unroll") for (int k = 0; k < 2; ++k) dst[n][k] = *(const PG8_LAS bf16x8*)(lds + PG8_SB(b, h) + boff + n * 2048 + k * 1024); } while (0)
; #define PG8_MMA(ai, bj, At, Bt) do { __builtin_amdgcn_s_setprio(1); _Pragma("unroll") for (int m = 0; m < 4; ++m) _Pragma("unroll") for (int n = 0; n < 2; ++n) _Pragma("unroll") for (int k = 0; k < 2; ++k) \
;         acc[ai][bj][m][n] = __builtin_amdgcn_mfma_f32_16x16x32_bf16(Bt[n][k], At[m][k], acc[ai][bj][m][n], 0, 0, 0); __builtin_amdgcn_s_setprio(0); } while (0)
; #define PG8_WAIT_V(n) asm volatile("s_waitcnt vmcnt(" #n ")" ::: "memory")
; #define PG8_WAIT_L(n) asm volatile("s_waitcnt lgkmcnt(" #n ")" ::: "memory")
; #define PG8_BAR __builtin_amdgcn_s_barrier()
; #define PG8_SCHED __builtin_amdgcn_sched_barrier(0)
; template <class Epi, class Sched, bool ALIGN_EPI = false, bool SP2 = false>
; __device__ __forceinline__ void gemm_phase(PG8_LAS unsigned char* lds, const Gemm g, const Sched& S, const Epi& E) {
;     ...
;             PG8_LDB(B0, 0, 0); PG8_LDB(B1, 0, 1); PG8_SCHED; PG8_LDA(At, 0, 0); PG8_STAGE(PG8_SA(1, 1), a1 + hstepA, voffA);
;             PG8_WAIT_V(8); PG8_WAIT_L(0); PG8_BAR; PG8_MMA(0, 0, At, B0); PG8_MMA(0, 1, At, B1); PG8_BAR; PG8_SCHED;
;             PG8_LDA(At, 0, 1); PG8_STAGE(PG8_SB(0, 0), b2, voffB); PG8_STAGE(PG8_SB(0, 1), b2 + hstepB, voffB); PG8_STAGE(PG8_SA(0, 0), a2, voffA);
.LBB0_1319:
	v_add_u32_e32 v142, s35, v145
	ds_read_b128 v[138:141], v142
	ds_read_b128 v[148:151], v142 offset:1024
	ds_read_b128 v[152:155], v142 offset:2048
	ds_read_b128 v[156:159], v142 offset:3072
	v_add_u32_e32 v142, s38, v145
	ds_read_b128 v[160:163], v142
	ds_read_b128 v[164:167], v142 offset:1024
	ds_read_b128 v[168:171], v142 offset:2048
	ds_read_b128 v[172:175], v142 offset:3072
	s_add_u32 s22, s20, 0x100
	s_addc_u32 s23, s21, 0
	s_cmp_eq_u32 s78, 40
	s_cselect_b32 s27, s9, s23
	s_cselect_b32 s26, s8, s22
	s_cselect_b32 s25, s19, s75
	s_cselect_b32 s24, s18, s74
	v_lshl_add_u64 v[142:143], s[20:21], 0, v[136:137]
	s_add_i32 m0, s41, 0xc000
	ds_read_b128 v[176:179], v147
	ds_read_b128 v[180:183], v147 offset:1024
	ds_read_b128 v[184:187], v147 offset:2048
	ds_read_b128 v[188:191], v147 offset:3072
	ds_read_b128 v[204:207], v147 offset:4096
	ds_read_b128 v[208:211], v147 offset:5120
	ds_read_b128 v[218:221], v147 offset:6144
	ds_read_b128 v[222:225], v147 offset:7168
	global_load_lds_dwordx4 v[142:143], off
	v_lshl_add_u64 v[142:143], s[20:21], 0, v[134:135]
	s_add_i32 m0, s41, 0xe000
	s_nop 0
	global_load_lds_dwordx4 v[142:143], off
	s_waitcnt vmcnt(8)
	s_waitcnt lgkmcnt(0)
	s_barrier
	s_waitcnt lgkmcnt(0)
	v_mfma_f32_16x16x32_bf16 v[124:127], v[138:141], v[176:179], v[124:127]
	v_mfma_f32_16x16x32_bf16 v[120:123], v[152:155], v[176:179], v[120:123]
	v_mfma_f32_16x16x32_bf16 v[108:111], v[138:141], v[184:187], v[108:111]
	v_mfma_f32_16x16x32_bf16 v[104:107], v[152:155], v[184:187], v[104:107]
	v_mfma_f32_16x16x32_bf16 v[92:95], v[138:141], v[204:207], v[92:95]
	v_mfma_f32_16x16x32_bf16 v[88:91], v[152:155], v[204:207], v[88:91]
	v_mfma_f32_16x16x32_bf16 v[76:79], v[138:141], v[218:221], v[76:79]
	v_mfma_f32_16x16x32_bf16 v[72:75], v[152:155], v[218:221], v[72:75]
	v_mfma_f32_16x16x32_bf16 v[124:127], v[148:151], v[180:183], v[124:127]
	v_mfma_f32_16x16x32_bf16 v[120:123], v[156:159], v[180:183], v[120:123]
	v_mfma_f32_16x16x32_bf16 v[108:111], v[148:151], v[188:191], v[108:111]
	v_mfma_f32_16x16x32_bf16 v[104:107], v[156:159], v[188:191], v[104:107]
	v_mfma_f32_16x16x32_bf16 v[92:95], v[148:151], v[208:211], v[92:95]
	v_mfma_f32_16x16x32_bf16 v[88:91], v[156:159], v[208:211], v[88:91]
	v_mfma_f32_16x16x32_bf16 v[76:79], v[148:151], v[222:225], v[76:79]
	v_mfma_f32_16x16x32_bf16 v[72:75], v[156:159], v[222:225], v[72:75]
	v_mfma_f32_16x16x32_bf16 v[116:119], v[160:163], v[176:179], v[116:119]
	v_mfma_f32_16x16x32_bf16 v[112:115], v[168:171], v[176:179], v[112:115]
	v_mfma_f32_16x16x32_bf16 v[100:103], v[160:163], v[184:187], v[100:103]
	v_mfma_f32_16x16x32_bf16 v[96:99], v[168:171], v[184:187], v[96:99]
	v_mfma_f32_16x16x32_bf16 v[84:87], v[160:163], v[204:207], v[84:87]
	v_mfma_f32_16x16x32_bf16 v[80:83], v[168:171], v[204:207], v[80:83]
	v_mfma_f32_16x16x32_bf16 v[68:71], v[160:163], v[218:221], v[68:71]
	v_mfma_f32_16x16x32_bf16 v[64:67], v[168:171], v[218:221], v[64:67]
	v_mfma_f32_16x16x32_bf16 v[116:119], v[164:167], v[180:183], v[116:119]
	v_mfma_f32_16x16x32_bf16 v[112:115], v[172:175], v[180:183], v[112:115]
	v_mfma_f32_16x16x32_bf16 v[100:103], v[164:167], v[188:191], v[100:103]
	v_mfma_f32_16x16x32_bf16 v[96:99], v[172:175], v[188:191], v[96:99]
	v_mfma_f32_16x16x32_bf16 v[84:87], v[164:167], v[208:211], v[84:87]
	v_mfma_f32_16x16x32_bf16 v[80:83], v[172:175], v[208:211], v[80:83]
	v_mfma_f32_16x16x32_bf16 v[68:71], v[164:167], v[222:225], v[68:71]
	v_mfma_f32_16x16x32_bf16 v[64:67], v[172:175], v[222:225], v[64:67]
	s_barrier
	s_mov_b32 m0, s36
	v_lshl_add_u64 v[142:143], s[24:25], 0, v[192:193]
	s_add_u32 s20, s24, 0xb0000
	ds_read_b128 v[176:179], v147 offset:16384
	ds_read_b128 v[180:183], v147 offset:17408
	ds_read_b128 v[184:187], v147 offset:18432
	ds_read_b128 v[188:191], v147 offset:19456
	ds_read_b128 v[204:207], v147 offset:20480
	ds_read_b128 v[208:211], v147 offset:21504
	ds_read_b128 v[218:221], v147 offset:22528
	ds_read_b128 v[222:225], v147 offset:23552
	global_load_lds_dwordx4 v[142:143], off
	v_lshl_add_u64 v[194:195], s[24:25], 0, v[132:133]
	s_mov_b32 m0, s37
	s_addc_u32 s21, s25, 0
	global_load_lds_dwordx4 v[194:195], off
	v_lshl_add_u64 v[226:227], s[20:21], 0, v[192:193]
	s_mov_b32 m0, s39
	v_lshl_add_u64 v[228:229], s[26:27], 0, v[130:131]
	global_load_lds_dwordx4 v[226:227], off
	v_lshl_add_u64 v[226:227], s[20:21], 0, v[132:133]
	s_mov_b32 m0, s40
	s_nop 0
	global_load_lds_dwordx4 v[226:227], off
	v_lshl_add_u64 v[226:227], s[26:27], 0, v[128:129]
	s_mov_b32 m0, s41
	s_nop 0
	global_load_lds_dwordx4 v[226:227], off
	s_mov_b32 m0, s42
	s_nop 0
	global_load_lds_dwordx4 v[228:229], off
	s_waitcnt vmcnt(8)
	s_waitcnt lgkmcnt(0)
	s_barrier
; #define PG8_STAGE(bufoff, gbase, voff) do { _Pragma("unroll") for (int _i = 0; _i < 2; ++_i) \
;         __builtin_amdgcn_global_load_lds((const unsigned*)((const char*)(gbase) + (voff)[_i]), (PG8_LAS unsigned*)(lds + (bufoff) + ldsw + _i * 8192), 16, 0, 0); } while (0)
; #define PG8_LDA(dst, b, h) do { _Pragma("unroll") for (int m = 0; m < 4; ++m) _Pragma("unroll") for (int k = 0; k < 2; ++k) dst[m][k] = *(const PG8_LAS bf16x8*)(lds + PG8_SA(b, h) + aoff + m * 2048 + k * 1024); } while (0)
; #define PG8_LDB(dst, b, h) do { _Pragma("unroll") for (int n = 0; n < 2; ++n) _Pragma("unroll") for (int k = 0; k < 2; ++k) dst[n][k] = *(const PG8_LAS bf16x8*)(lds + PG8_SB(b, h) + boff + n * 2048 + k * 1024); } while (0)
; #define PG8_MMA(ai, bj, At, Bt) do { __builtin_amdgcn_s_setprio(1); _Pragma("unroll") for (int m = 0; m < 4; ++m) _Pragma("unroll") for (int n = 0; n < 2; ++n) _Pragma("unroll") for (int k = 0; k < 2; ++k) \
;         acc[ai][bj][m][n] = __builtin_amdgcn_mfma_f32_16x16x32_bf16(Bt[n][k], At[m][k], acc[ai][bj][m][n], 0, 0, 0); __builtin_amdgcn_s_setprio(0); } while (0)
; #define PG8_WAIT_V(n) asm volatile("s_waitcnt vmcnt(" #n ")" ::: "memory")
; #define PG8_WAIT_L(n) asm volatile("s_waitcnt lgkmcnt(" #n ")" ::: "memory")
; #define PG8_BAR __builtin_amdgcn_s_barrier()
; #define PG8_SCHED __builtin_amdgcn_sched_barrier(0)
; template <class Epi, class Sched, bool ALIGN_EPI = false, bool SP2 = false>
; __device__ __forceinline__ void gemm_phase(PG8_LAS unsigned char* lds, const Gemm g, const Sched& S, const Epi& E) {
;     ...
;             PG8_WAIT_V(8); PG8_WAIT_L(0); PG8_BAR; PG8_MMA(1, 0, At, B0); PG8_MMA(1, 1, At, B1); PG8_BAR; PG8_SCHED;
;             PG8_LDB(B0, 1, 0); PG8_LDB(B1, 1, 1); PG8_SCHED; PG8_LDA(At, 1, 0); PG8_STAGE(PG8_SA(0, 1), a2 + hstepA, voffA);
;             PG8_WAIT_V(8); PG8_WAIT_L(0); PG8_BAR; PG8_MMA(0, 0, At, B0); PG8_MMA(0, 1, At, B1); PG8_BAR; PG8_SCHED;
	s_waitcnt lgkmcnt(0)
	v_mfma_f32_16x16x32_bf16 v[60:63], v[138:141], v[176:179], v[60:63]
	v_mfma_f32_16x16x32_bf16 v[56:59], v[152:155], v[176:179], v[56:59]
	v_mfma_f32_16x16x32_bf16 v[44:47], v[138:141], v[184:187], v[44:47]
	v_mfma_f32_16x16x32_bf16 v[40:43], v[152:155], v[184:187], v[40:43]
	v_mfma_f32_16x16x32_bf16 v[28:31], v[138:141], v[204:207], v[28:31]
	v_mfma_f32_16x16x32_bf16 v[24:27], v[152:155], v[204:207], v[24:27]
	v_mfma_f32_16x16x32_bf16 v[12:15], v[138:141], v[218:221], v[12:15]
	v_mfma_f32_16x16x32_bf16 v[8:11], v[152:155], v[218:221], v[8:11]
	v_mfma_f32_16x16x32_bf16 v[60:63], v[148:151], v[180:183], v[60:63]
	v_mfma_f32_16x16x32_bf16 v[56:59], v[156:159], v[180:183], v[56:59]
	v_mfma_f32_16x16x32_bf16 v[44:47], v[148:151], v[188:191], v[44:47]
	v_mfma_f32_16x16x32_bf16 v[40:43], v[156:159], v[188:191], v[40:43]
	v_mfma_f32_16x16x32_bf16 v[28:31], v[148:151], v[208:211], v[28:31]
	v_mfma_f32_16x16x32_bf16 v[24:27], v[156:159], v[208:211], v[24:27]
	v_mfma_f32_16x16x32_bf16 v[12:15], v[148:151], v[222:225], v[12:15]
	v_mfma_f32_16x16x32_bf16 v[8:11], v[156:159], v[222:225], v[8:11]
	v_mfma_f32_16x16x32_bf16 v[52:55], v[160:163], v[176:179], v[52:55]
	v_mfma_f32_16x16x32_bf16 v[48:51], v[168:171], v[176:179], v[48:51]
	v_mfma_f32_16x16x32_bf16 v[36:39], v[160:163], v[184:187], v[36:39]
	v_mfma_f32_16x16x32_bf16 v[32:35], v[168:171], v[184:187], v[32:35]
	v_mfma_f32_16x16x32_bf16 v[20:23], v[160:163], v[204:207], v[20:23]
	v_mfma_f32_16x16x32_bf16 v[16:19], v[168:171], v[204:207], v[16:19]
	v_mfma_f32_16x16x32_bf16 v[4:7], v[160:163], v[218:221], v[4:7]
	v_mfma_f32_16x16x32_bf16 v[0:3], v[168:171], v[218:221], v[0:3]
	v_mfma_f32_16x16x32_bf16 v[52:55], v[164:167], v[180:183], v[52:55]
	v_mfma_f32_16x16x32_bf16 v[48:51], v[172:175], v[180:183], v[48:51]
	v_mfma_f32_16x16x32_bf16 v[36:39], v[164:167], v[188:191], v[36:39]
	v_mfma_f32_16x16x32_bf16 v[32:35], v[172:175], v[188:191], v[32:35]
	v_mfma_f32_16x16x32_bf16 v[20:23], v[164:167], v[208:211], v[20:23]
	v_mfma_f32_16x16x32_bf16 v[16:19], v[172:175], v[208:211], v[16:19]
	v_mfma_f32_16x16x32_bf16 v[4:7], v[164:167], v[222:225], v[4:7]
	v_mfma_f32_16x16x32_bf16 v[0:3], v[172:175], v[222:225], v[0:3]
	s_barrier
	v_add_u32_e32 v156, s48, v145
	v_add_u32_e32 v172, s61, v145
	ds_read_b128 v[138:141], v156
	ds_read_b128 v[148:151], v156 offset:1024
	ds_read_b128 v[152:155], v156 offset:2048
	ds_read_b128 v[156:159], v156 offset:3072
	ds_read_b128 v[160:163], v172
	ds_read_b128 v[164:167], v172 offset:1024
	ds_read_b128 v[168:171], v172 offset:2048
	ds_read_b128 v[172:175], v172 offset:3072
	s_add_u32 s20, s26, 0xb0000
	s_addc_u32 s21, s27, 0
	s_mov_b32 m0, s43
	v_lshl_add_u64 v[230:231], s[20:21], 0, v[128:129]
	ds_read_b128 v[176:179], v147 offset:32768
	ds_read_b128 v[180:183], v147 offset:33792
	ds_read_b128 v[184:187], v147 offset:34816
	ds_read_b128 v[188:191], v147 offset:35840
	ds_read_b128 v[204:207], v147 offset:36864
	ds_read_b128 v[208:211], v147 offset:37888
	ds_read_b128 v[218:221], v147 offset:38912
	ds_read_b128 v[222:225], v147 offset:39936
	global_load_lds_dwordx4 v[230:231], off
	v_lshl_add_u64 v[230:231], s[20:21], 0, v[130:131]
	s_mov_b32 m0, s44
	s_nop 0
	global_load_lds_dwordx4 v[230:231], off
	s_waitcnt vmcnt(8)
	s_waitcnt lgkmcnt(0)
	s_barrier
	s_waitcnt lgkmcnt(0)
	v_mfma_f32_16x16x32_bf16 v[124:127], v[138:141], v[176:179], v[124:127]
	v_mfma_f32_16x16x32_bf16 v[120:123], v[152:155], v[176:179], v[120:123]
	v_mfma_f32_16x16x32_bf16 v[108:111], v[138:141], v[184:187], v[108:111]
	v_mfma_f32_16x16x32_bf16 v[104:107], v[152:155], v[184:187], v[104:107]
	v_mfma_f32_16x16x32_bf16 v[92:95], v[138:141], v[204:207], v[92:95]
	v_mfma_f32_16x16x32_bf16 v[88:91], v[152:155], v[204:207], v[88:91]
	v_mfma_f32_16x16x32_bf16 v[76:79], v[138:141], v[218:221], v[76:79]
	v_mfma_f32_16x16x32_bf16 v[72:75], v[152:155], v[218:221], v[72:75]
	v_mfma_f32_16x16x32_bf16 v[124:127], v[148:151], v[180:183], v[124:127]
	v_mfma_f32_16x16x32_bf16 v[120:123], v[156:159], v[180:183], v[120:123]
	v_mfma_f32_16x16x32_bf16 v[108:111], v[148:151], v[188:191], v[108:111]
	v_mfma_f32_16x16x32_bf16 v[104:107], v[156:159], v[188:191], v[104:107]
	v_mfma_f32_16x16x32_bf16 v[92:95], v[148:151], v[208:211], v[92:95]
	v_mfma_f32_16x16x32_bf16 v[88:91], v[156:159], v[208:211], v[88:91]
	v_mfma_f32_16x16x32_bf16 v[76:79], v[148:151], v[222:225], v[76:79]
	v_mfma_f32_16x16x32_bf16 v[72:75], v[156:159], v[222:225], v[72:75]
	v_mfma_f32_16x16x32_bf16 v[116:119], v[160:163], v[176:179], v[116:119]
	v_mfma_f32_16x16x32_bf16 v[112:115], v[168:171], v[176:179], v[112:115]
	v_mfma_f32_16x16x32_bf16 v[100:103], v[160:163], v[184:187], v[100:103]
	v_mfma_f32_16x16x32_bf16 v[96:99], v[168:171], v[184:187], v[96:99]
	v_mfma_f32_16x16x32_bf16 v[84:87], v[160:163], v[204:207], v[84:87]
	v_mfma_f32_16x16x32_bf16 v[80:83], v[168:171], v[204:207], v[80:83]
	v_mfma_f32_16x16x32_bf16 v[68:71], v[160:163], v[218:221], v[68:71]
	v_mfma_f32_16x16x32_bf16 v[64:67], v[168:171], v[218:221], v[64:67]
	v_mfma_f32_16x16x32_bf16 v[116:119], v[164:167], v[180:183], v[116:119]
	v_mfma_f32_16x16x32_bf16 v[112:115], v[172:175], v[180:183], v[112:115]
	v_mfma_f32_16x16x32_bf16 v[100:103], v[164:167], v[188:191], v[100:103]
	v_mfma_f32_16x16x32_bf16 v[96:99], v[172:175], v[188:191], v[96:99]
	v_mfma_f32_16x16x32_bf16 v[84:87], v[164:167], v[208:211], v[84:87]
	v_mfma_f32_16x16x32_bf16 v[80:83], v[172:175], v[208:211], v[80:83]
	v_mfma_f32_16x16x32_bf16 v[68:71], v[164:167], v[222:225], v[68:71]
	v_mfma_f32_16x16x32_bf16 v[64:67], v[172:175], v[222:225], v[64:67]
	s_barrier
; #define PG8_STAGE(bufoff, gbase, voff) do { _Pragma("unroll") for (int _i = 0; _i < 2; ++_i) \
;         __builtin_amdgcn_global_load_lds((const unsigned*)((const char*)(gbase) + (voff)[_i]), (PG8_LAS unsigned*)(lds + (bufoff) + ldsw + _i * 8192), 16, 0, 0); } while (0)
; #define PG8_LDA(dst, b, h) do { _Pragma("unroll") for (int m = 0; m < 4; ++m) _Pragma("unroll") for (int k = 0; k < 2; ++k) dst[m][k] = *(const PG8_LAS bf16x8*)(lds + PG8_SA(b, h) + aoff + m * 2048 + k * 1024); } while (0)
; #define PG8_MMA(ai, bj, At, Bt) do { __builtin_amdgcn_s_setprio(1); _Pragma("unroll") for (int m = 0; m < 4; ++m) _Pragma("unroll") for (int n = 0; n < 2; ++n) _Pragma("unroll") for (int k = 0; k < 2; ++k) \
;         acc[ai][bj][m][n] = __builtin_amdgcn_mfma_f32_16x16x32_bf16(Bt[n][k], At[m][k], acc[ai][bj][m][n], 0, 0, 0); __builtin_amdgcn_s_setprio(0); } while (0)
; #define PG8_WAIT_V(n) asm volatile("s_waitcnt vmcnt(" #n ")" ::: "memory")
; #define PG8_WAIT_L(n) asm volatile("s_waitcnt lgkmcnt(" #n ")" ::: "memory")
; #define PG8_BAR __builtin_amdgcn_s_barrier()
; #define PG8_SCHED __builtin_amdgcn_sched_barrier(0)
; template <class Epi, class Sched, bool ALIGN_EPI = false, bool SP2 = false>
; __device__ __forceinline__ void gemm_phase(PG8_LAS unsigned char* lds, const Gemm g, const Sched& S, const Epi& E) {
;     ...
;             PG8_LDA(At, 1, 1); PG8_STAGE(PG8_SB(1, 0), b3, voffB); PG8_STAGE(PG8_SB(1, 1), b3 + hstepB, voffB); PG8_STAGE(PG8_SA(1, 0), a3, voffA);
;             PG8_WAIT_V(8); PG8_WAIT_L(0); PG8_BAR; PG8_MMA(1, 0, At, B0); PG8_MMA(1, 1, At, B1); PG8_BAR; PG8_SCHED;
;     __device__ __forceinline__ void operator()(const f32x4 (&acc)[2][2][4][2], const pg8::Unit& u, int wr, int wc, int fr, int fq) const {
;     ...
;                     const size_t off = (size_t)row * DM + col0 + bj * 128;
;                     const v4u b = *(const v4u*)(xb + off);
	s_mov_b32 m0, s49
	v_lshl_add_u64 v[142:143], v[142:143], 0, s[76:77]
	s_add_u32 s20, s24, 0xb0080
	ds_read_b128 v[176:179], v147 offset:49152
	ds_read_b128 v[180:183], v147 offset:50176
	ds_read_b128 v[184:187], v147 offset:51200
	ds_read_b128 v[188:191], v147 offset:52224
	ds_read_b128 v[204:207], v147 offset:53248
	ds_read_b128 v[208:211], v147 offset:54272
	ds_read_b128 v[218:221], v147 offset:55296
	ds_read_b128 v[222:225], v147 offset:56320
	global_load_lds_dwordx4 v[142:143], off
	v_lshl_add_u64 v[142:143], v[194:195], 0, s[76:77]
	s_mov_b32 m0, s50
	s_addc_u32 s21, s25, 0
	global_load_lds_dwordx4 v[142:143], off
	v_lshl_add_u64 v[142:143], s[20:21], 0, v[192:193]
	s_mov_b32 m0, s64
	s_nop 0
	global_load_lds_dwordx4 v[142:143], off
	v_lshl_add_u64 v[142:143], s[20:21], 0, v[132:133]
	s_mov_b32 m0, s65
	s_nop 0
	global_load_lds_dwordx4 v[142:143], off
	v_lshl_add_u64 v[142:143], v[226:227], 0, s[76:77]
	s_mov_b32 m0, s51
	s_nop 0
	global_load_lds_dwordx4 v[142:143], off
	v_lshl_add_u64 v[142:143], v[228:229], 0, s[76:77]
	s_mov_b32 m0, s60
	s_nop 0
	global_load_lds_dwordx4 v[142:143], off
	s_waitcnt vmcnt(8)
	s_waitcnt lgkmcnt(0)
	s_barrier
	s_waitcnt lgkmcnt(0)
	v_mfma_f32_16x16x32_bf16 v[60:63], v[138:141], v[176:179], v[60:63]
	v_mfma_f32_16x16x32_bf16 v[56:59], v[152:155], v[176:179], v[56:59]
	v_mfma_f32_16x16x32_bf16 v[44:47], v[138:141], v[184:187], v[44:47]
	v_mfma_f32_16x16x32_bf16 v[40:43], v[152:155], v[184:187], v[40:43]
	v_mfma_f32_16x16x32_bf16 v[28:31], v[138:141], v[204:207], v[28:31]
	v_mfma_f32_16x16x32_bf16 v[24:27], v[152:155], v[204:207], v[24:27]
	v_mfma_f32_16x16x32_bf16 v[12:15], v[138:141], v[218:221], v[12:15]
	v_mfma_f32_16x16x32_bf16 v[8:11], v[152:155], v[218:221], v[8:11]
	v_mfma_f32_16x16x32_bf16 v[60:63], v[148:151], v[180:183], v[60:63]
	v_mfma_f32_16x16x32_bf16 v[56:59], v[156:159], v[180:183], v[56:59]
	v_mfma_f32_16x16x32_bf16 v[44:47], v[148:151], v[188:191], v[44:47]
	v_mfma_f32_16x16x32_bf16 v[40:43], v[156:159], v[188:191], v[40:43]
	v_mfma_f32_16x16x32_bf16 v[28:31], v[148:151], v[208:211], v[28:31]
	v_mfma_f32_16x16x32_bf16 v[24:27], v[156:159], v[208:211], v[24:27]
	v_mfma_f32_16x16x32_bf16 v[12:15], v[148:151], v[222:225], v[12:15]
	v_mfma_f32_16x16x32_bf16 v[8:11], v[156:159], v[222:225], v[8:11]
	v_mfma_f32_16x16x32_bf16 v[52:55], v[160:163], v[176:179], v[52:55]
	v_mfma_f32_16x16x32_bf16 v[48:51], v[168:171], v[176:179], v[48:51]
	v_mfma_f32_16x16x32_bf16 v[36:39], v[160:163], v[184:187], v[36:39]
	v_mfma_f32_16x16x32_bf16 v[32:35], v[168:171], v[184:187], v[32:35]
	v_mfma_f32_16x16x32_bf16 v[20:23], v[160:163], v[204:207], v[20:23]
	v_mfma_f32_16x16x32_bf16 v[16:19], v[168:171], v[204:207], v[16:19]
	v_mfma_f32_16x16x32_bf16 v[4:7], v[160:163], v[218:221], v[4:7]
	v_mfma_f32_16x16x32_bf16 v[0:3], v[168:171], v[218:221], v[0:3]
	v_mfma_f32_16x16x32_bf16 v[52:55], v[164:167], v[180:183], v[52:55]
	v_mfma_f32_16x16x32_bf16 v[48:51], v[172:175], v[180:183], v[48:51]
	v_mfma_f32_16x16x32_bf16 v[36:39], v[164:167], v[188:191], v[36:39]
	v_mfma_f32_16x16x32_bf16 v[32:35], v[172:175], v[188:191], v[32:35]
	v_mfma_f32_16x16x32_bf16 v[20:23], v[164:167], v[208:211], v[20:23]
	v_mfma_f32_16x16x32_bf16 v[16:19], v[172:175], v[208:211], v[16:19]
	v_mfma_f32_16x16x32_bf16 v[4:7], v[164:167], v[222:225], v[4:7]
	v_mfma_f32_16x16x32_bf16 v[0:3], v[172:175], v[222:225], v[0:3]
	s_barrier
	s_add_i32 s78, s78, 2
	s_add_u32 s74, s74, 0x100
	s_addc_u32 s75, s75, 0
	s_cmp_gt_u32 s78, 41
	s_mov_b64 s[20:21], s[22:23]
	s_cbranch_scc0 .LBB0_1319
	v_lshl_add_u32 v159, s68, 8, v144
	v_lshl_or_b32 v158, s34, 8, v146
	v_lshlrev_b32_e32 v159, 11, v159
	v_lshl_add_u32 v159, v158, 1, v159
	v_add_u32_e32 v218, 0x8000, v159
	v_add_u32_e32 v219, 0x10000, v159
	v_add_u32_e32 v240, 0x18000, v159
	v_add_u32_e32 v241, 0x40000, v159
	v_add_u32_e32 v245, 0x48000, v159
	v_add_u32_e32 v246, 0x50000, v159
	v_add_u32_e32 v247, 0x58000, v159
	global_load_dwordx4 v[160:163], v159, s[12:13]
	global_load_dwordx4 v[164:167], v159, s[12:13] offset:256
	global_load_dwordx4 v[168:171], v218, s[12:13]
	global_load_dwordx4 v[172:175], v218, s[12:13] offset:256
	global_load_dwordx4 v[176:179], v219, s[12:13]
	global_load_dwordx4 v[180:183], v219, s[12:13] offset:256
	global_load_dwordx4 v[184:187], v240, s[12:13]
	global_load_dwordx4 v[188:191], v240, s[12:13] offset:256
	global_load_dwordx4 v[204:207], v241, s[12:13]
	global_load_dwordx4 v[208:211], v241, s[12:13] offset:256
	global_load_dwordx4 v[220:223], v245, s[12:13]
	global_load_dwordx4 v[224:227], v245, s[12:13] offset:256
	global_load_dwordx4 v[228:231], v246, s[12:13]
	global_load_dwordx4 v[232:235], v246, s[12:13] offset:256
	global_load_dwordx4 v[236:239], v247, s[12:13]
	global_load_dwordx4 v[248:251], v247, s[12:13] offset:256
	s_and_b64 vcc, exec, s[16:17]
	s_cbranch_vccz .LBB0_1322
	s_barrier
